# speedup vs baseline: 1.0140x; 1.0084x over previous
; #define STAGE(P, BASE, kt) do { const char* _g = (const char*)(BASE) + (size_t)((kt) * (BK * 2)); \
;     __builtin_amdgcn_global_load_lds((const unsigned*)(_g + (size_t)goff0), (unsigned*)((char*)(P) + tid_ * 16), 16, 0, 0); \
;     __builtin_amdgcn_global_load_lds((const unsigned*)(_g + (size_t)goff1), (unsigned*)((char*)(P) + tid_ * 16 + 8192), 16, 0, 0); } while (0)
; #define STAGEA(P, BASE, kt) do { const char* _g = (const char*)(BASE) + (size_t)((kt) * a_kbytes); \
;     __builtin_amdgcn_global_load_lds((const unsigned*)(_g + (size_t)goffA0), (unsigned*)((char*)(P) + tid_ * 16), 16, 0, 0); \
;     __builtin_amdgcn_global_load_lds((const unsigned*)(_g + (size_t)goffA1), (unsigned*)((char*)(P) + tid_ * 16 + 8192), 16, 0, 0); } while (0)
; #define LDA(dst, b, h) for (int m = 0; m < 4; ++m) for (int k = 0; k < 2; ++k) \
;     dst[m][k] = *reinterpret_cast<const bf16x8*>((char*)SA(b, h) + lds_byte(wr * 64 + m * 16 + fr, k * 32 + fq * 8))
; #define LDB(dst, b, h) for (int n = 0; n < 2; ++n) for (int k = 0; k < 2; ++k) \
;     dst[n][k] = *reinterpret_cast<const bf16x8*>((char*)SB(b, h) + lds_byte(wc * 32 + n * 16 + fr, k * 32 + fq * 8))
; #define MMA(ai, bj, At, Bt) do { __builtin_amdgcn_s_setprio(1); \
;     for (int m = 0; m < 4; ++m) for (int n = 0; n < 2; ++n) for (int k = 0; k < 2; ++k) \
;       acc[ai][bj][m][n] = __builtin_amdgcn_mfma_f32_16x16x32_bf16(At[m][k], Bt[n][k], acc[ai][bj][m][n], 0, 0, 0); \
;     __builtin_amdgcn_s_setprio(0); } while (0)
; #define WAIT_L(n) asm volatile("s_waitcnt lgkmcnt(" #n ")" ::: "memory")
; #define BAR __builtin_amdgcn_s_barrier()
; #define SCHED __builtin_amdgcn_sched_barrier(0)
; template <int EPI> ...
;     ...
;     LDB(B0, 0, 0); SCHED; LDA(At, 0, 0); STAGEA(SA(1, 1), A1, t + 1);
;     WAIT_L(8); BAR; WAIT_L(0); MMA(0, 0, At, B0); BAR; SCHED;
;     LDB(B1, 0, 1); STAGE(SB(0, 0), B0p, t + 2);
;     BAR; WAIT_L(0); MMA(0, 1, At, B1); BAR;
;     LDA(At, 0, 1); STAGEA(SA(0, 0), A0, t + 2);
;     BAR; WAIT_L(0); MMA(1, 0, At, B0); BAR; SCHED;
.LBB0_760:
	ds_read_b128 v[176:179], v172
	ds_read_b128 v[180:183], v172 offset:1024
	ds_read_b128 v[184:187], v172 offset:2048
	ds_read_b128 v[188:191], v172 offset:3072
	v_add_u32_e32 v173, 0xc000, v159
	v_lshl_add_u64 v[240:241], s[58:59], 0, v[142:143]
	v_readfirstlane_b32 s55, v173
	v_lshl_add_u64 v[174:175], v[240:241], 0, s[6:7]
	s_mov_b32 m0, s55
	ds_read_b128 v[192:195], v154
	ds_read_b128 v[196:199], v154 offset:1024
	ds_read_b128 v[200:203], v153
	ds_read_b128 v[204:207], v153 offset:1024
	ds_read_b128 v[208:211], v152
	ds_read_b128 v[212:215], v152 offset:1024
	ds_read_b128 v[216:219], v151
	ds_read_b128 v[220:223], v151 offset:1024
	global_load_lds_dwordx4 v[174:175], off
	v_add_u32_e32 v174, 0xe000, v159
	v_lshl_add_u64 v[242:243], s[58:59], 0, v[144:145]
	v_readfirstlane_b32 s55, v174
	v_lshl_add_u64 v[224:225], v[242:243], 0, s[6:7]
	s_mov_b32 m0, s55
	s_nop 0
	global_load_lds_dwordx4 v[224:225], off
	s_waitcnt lgkmcnt(8)
	s_barrier
	s_waitcnt lgkmcnt(0)
	s_setprio 1
	v_mfma_f32_16x16x32_bf16 v[124:127], v[192:195], v[176:179], v[124:127]
	v_mfma_f32_16x16x32_bf16 v[120:123], v[192:195], v[184:187], v[120:123]
	v_mfma_f32_16x16x32_bf16 v[116:119], v[200:203], v[176:179], v[116:119]
	v_mfma_f32_16x16x32_bf16 v[112:115], v[200:203], v[184:187], v[112:115]
	v_mfma_f32_16x16x32_bf16 v[108:111], v[208:211], v[176:179], v[108:111]
	v_mfma_f32_16x16x32_bf16 v[104:107], v[208:211], v[184:187], v[104:107]
	v_mfma_f32_16x16x32_bf16 v[100:103], v[216:219], v[176:179], v[100:103]
	v_mfma_f32_16x16x32_bf16 v[96:99], v[216:219], v[184:187], v[96:99]
	v_mfma_f32_16x16x32_bf16 v[124:127], v[196:199], v[180:183], v[124:127]
	v_mfma_f32_16x16x32_bf16 v[120:123], v[196:199], v[188:191], v[120:123]
	v_mfma_f32_16x16x32_bf16 v[116:119], v[204:207], v[180:183], v[116:119]
	v_mfma_f32_16x16x32_bf16 v[112:115], v[204:207], v[188:191], v[112:115]
	v_mfma_f32_16x16x32_bf16 v[108:111], v[212:215], v[180:183], v[108:111]
	v_mfma_f32_16x16x32_bf16 v[104:107], v[212:215], v[188:191], v[104:107]
	v_mfma_f32_16x16x32_bf16 v[100:103], v[220:223], v[180:183], v[100:103]
	v_mfma_f32_16x16x32_bf16 v[96:99], v[220:223], v[188:191], v[96:99]
	s_setprio 0
	s_barrier
	v_lshl_add_u64 v[244:245], s[58:59], 0, v[128:129]
	v_readfirstlane_b32 s55, v156
	v_lshl_add_u64 v[246:247], v[244:245], 0, s[8:9]
	s_mov_b32 m0, s55
	ds_read_b128 v[224:227], v169
	ds_read_b128 v[228:231], v169 offset:1024
	ds_read_b128 v[232:235], v169 offset:2048
	ds_read_b128 v[236:239], v169 offset:3072
	global_load_lds_dwordx4 v[246:247], off
	v_lshl_add_u64 v[246:247], s[58:59], 0, v[130:131]
	v_readfirstlane_b32 s55, v158
	v_lshl_add_u64 v[248:249], v[246:247], 0, s[8:9]
	s_mov_b32 m0, s55
	s_nop 0
	global_load_lds_dwordx4 v[248:249], off
	s_barrier
	s_waitcnt lgkmcnt(0)
	s_setprio 1
	v_mfma_f32_16x16x32_bf16 v[92:95], v[192:195], v[224:227], v[92:95]
	v_mfma_f32_16x16x32_bf16 v[88:91], v[192:195], v[232:235], v[88:91]
	v_mfma_f32_16x16x32_bf16 v[84:87], v[200:203], v[224:227], v[84:87]
	v_mfma_f32_16x16x32_bf16 v[80:83], v[200:203], v[232:235], v[80:83]
	v_mfma_f32_16x16x32_bf16 v[76:79], v[208:211], v[224:227], v[76:79]
	v_mfma_f32_16x16x32_bf16 v[72:75], v[208:211], v[232:235], v[72:75]
	v_mfma_f32_16x16x32_bf16 v[68:71], v[216:219], v[224:227], v[68:71]
	v_mfma_f32_16x16x32_bf16 v[64:67], v[216:219], v[232:235], v[64:67]
	v_mfma_f32_16x16x32_bf16 v[92:95], v[196:199], v[228:231], v[92:95]
	v_mfma_f32_16x16x32_bf16 v[88:91], v[196:199], v[236:239], v[88:91]
	v_mfma_f32_16x16x32_bf16 v[84:87], v[204:207], v[228:231], v[84:87]
	v_mfma_f32_16x16x32_bf16 v[80:83], v[204:207], v[236:239], v[80:83]
	v_mfma_f32_16x16x32_bf16 v[76:79], v[212:215], v[228:231], v[76:79]
	v_mfma_f32_16x16x32_bf16 v[72:75], v[212:215], v[236:239], v[72:75]
	v_mfma_f32_16x16x32_bf16 v[68:71], v[220:223], v[228:231], v[68:71]
	v_mfma_f32_16x16x32_bf16 v[64:67], v[220:223], v[236:239], v[64:67]
	s_setprio 0
	v_readfirstlane_b32 s55, v159
	v_lshl_add_u64 v[248:249], v[240:241], 0, s[10:11]
	s_mov_b32 m0, s55
	v_readfirstlane_b32 s55, v160
	s_barrier
	ds_read_b128 v[192:195], v154 offset:16384
	ds_read_b128 v[196:199], v154 offset:17408
	ds_read_b128 v[200:203], v153 offset:16384
	ds_read_b128 v[204:207], v153 offset:17408
	ds_read_b128 v[208:211], v152 offset:16384
	ds_read_b128 v[212:215], v152 offset:17408
	ds_read_b128 v[216:219], v151 offset:16384
	ds_read_b128 v[220:223], v151 offset:17408
	global_load_lds_dwordx4 v[248:249], off
	v_lshl_add_u64 v[248:249], v[242:243], 0, s[10:11]
	s_mov_b32 m0, s55
	s_nop 0
	global_load_lds_dwordx4 v[248:249], off
	s_barrier
	s_waitcnt lgkmcnt(0)
	s_setprio 1
	v_mfma_f32_16x16x32_bf16 v[60:63], v[192:195], v[176:179], v[60:63]
	v_mfma_f32_16x16x32_bf16 v[56:59], v[192:195], v[184:187], v[56:59]
	v_mfma_f32_16x16x32_bf16 v[52:55], v[200:203], v[176:179], v[52:55]
	v_mfma_f32_16x16x32_bf16 v[48:51], v[200:203], v[184:187], v[48:51]
	v_mfma_f32_16x16x32_bf16 v[44:47], v[208:211], v[176:179], v[44:47]
	v_mfma_f32_16x16x32_bf16 v[40:43], v[208:211], v[184:187], v[40:43]
	v_mfma_f32_16x16x32_bf16 v[36:39], v[216:219], v[176:179], v[36:39]
	v_mfma_f32_16x16x32_bf16 v[32:35], v[216:219], v[184:187], v[32:35]
	v_mfma_f32_16x16x32_bf16 v[60:63], v[196:199], v[180:183], v[60:63]
	v_mfma_f32_16x16x32_bf16 v[56:59], v[196:199], v[188:191], v[56:59]
	v_mfma_f32_16x16x32_bf16 v[52:55], v[204:207], v[180:183], v[52:55]
	v_mfma_f32_16x16x32_bf16 v[48:51], v[204:207], v[188:191], v[48:51]
	v_mfma_f32_16x16x32_bf16 v[44:47], v[212:215], v[180:183], v[44:47]
	v_mfma_f32_16x16x32_bf16 v[40:43], v[212:215], v[188:191], v[40:43]
	v_mfma_f32_16x16x32_bf16 v[36:39], v[220:223], v[180:183], v[36:39]
	v_mfma_f32_16x16x32_bf16 v[32:35], v[220:223], v[188:191], v[32:35]
	s_setprio 0
	s_barrier
; #define STAGE(P, BASE, kt) do { const char* _g = (const char*)(BASE) + (size_t)((kt) * (BK * 2)); \
;     __builtin_amdgcn_global_load_lds((const unsigned*)(_g + (size_t)goff0), (unsigned*)((char*)(P) + tid_ * 16), 16, 0, 0); \
;     __builtin_amdgcn_global_load_lds((const unsigned*)(_g + (size_t)goff1), (unsigned*)((char*)(P) + tid_ * 16 + 8192), 16, 0, 0); } while (0)
; #define STAGEA(P, BASE, kt) do { const char* _g = (const char*)(BASE) + (size_t)((kt) * a_kbytes); \
;     __builtin_amdgcn_global_load_lds((const unsigned*)(_g + (size_t)goffA0), (unsigned*)((char*)(P) + tid_ * 16), 16, 0, 0); \
;     __builtin_amdgcn_global_load_lds((const unsigned*)(_g + (size_t)goffA1), (unsigned*)((char*)(P) + tid_ * 16 + 8192), 16, 0, 0); } while (0)
; #define LDA(dst, b, h) for (int m = 0; m < 4; ++m) for (int k = 0; k < 2; ++k) \
;     dst[m][k] = *reinterpret_cast<const bf16x8*>((char*)SA(b, h) + lds_byte(wr * 64 + m * 16 + fr, k * 32 + fq * 8))
; #define LDB(dst, b, h) for (int n = 0; n < 2; ++n) for (int k = 0; k < 2; ++k) \
;     dst[n][k] = *reinterpret_cast<const bf16x8*>((char*)SB(b, h) + lds_byte(wc * 32 + n * 16 + fr, k * 32 + fq * 8))
; #define MMA(ai, bj, At, Bt) do { __builtin_amdgcn_s_setprio(1); \
;     for (int m = 0; m < 4; ++m) for (int n = 0; n < 2; ++n) for (int k = 0; k < 2; ++k) \
;       acc[ai][bj][m][n] = __builtin_amdgcn_mfma_f32_16x16x32_bf16(At[m][k], Bt[n][k], acc[ai][bj][m][n], 0, 0, 0); \
;     __builtin_amdgcn_s_setprio(0); } while (0)
; #define WAIT_V(n) asm volatile("s_waitcnt vmcnt(" #n ")" ::: "memory")
; #define WAIT_L(n) asm volatile("s_waitcnt lgkmcnt(" #n ")" ::: "memory")
; #define BAR __builtin_amdgcn_s_barrier()
; #define SCHED __builtin_amdgcn_sched_barrier(0)
; template <int EPI> ...
;     ...
;     STAGE(SB(0, 1), B1p, t + 2);
;     WAIT_V(6); BAR; MMA(1, 1, At, B1); BAR;
;     LDB(B0, 1, 0); SCHED; LDA(At, 1, 0); STAGEA(SA(0, 1), A1, t + 2);
;     WAIT_L(8); BAR; WAIT_L(0); MMA(0, 0, At, B0); BAR; SCHED;
;     LDB(B1, 1, 1); STAGE(SB(1, 0), B0p, t + 3);
;     BAR; WAIT_L(0); MMA(0, 1, At, B1); BAR;
;     LDA(At, 1, 1); STAGEA(SA(1, 0), A0, t + 3);
	v_readfirstlane_b32 s55, v161
	v_lshl_add_u64 v[176:177], v[244:245], 0, s[12:13]
	s_mov_b32 m0, s55
	v_readfirstlane_b32 s55, v162
	global_load_lds_dwordx4 v[176:177], off
	v_lshl_add_u64 v[176:177], v[246:247], 0, s[12:13]
	s_mov_b32 m0, s55
	s_nop 0
	global_load_lds_dwordx4 v[176:177], off
	s_waitcnt vmcnt(6)
	s_barrier
	s_setprio 1
	v_mfma_f32_16x16x32_bf16 v[28:31], v[192:195], v[224:227], v[28:31]
	v_mfma_f32_16x16x32_bf16 v[24:27], v[192:195], v[232:235], v[24:27]
	v_mfma_f32_16x16x32_bf16 v[20:23], v[200:203], v[224:227], v[20:23]
	v_mfma_f32_16x16x32_bf16 v[16:19], v[200:203], v[232:235], v[16:19]
	v_mfma_f32_16x16x32_bf16 v[12:15], v[208:211], v[224:227], v[12:15]
	v_mfma_f32_16x16x32_bf16 v[8:11], v[208:211], v[232:235], v[8:11]
	v_mfma_f32_16x16x32_bf16 v[4:7], v[216:219], v[224:227], v[4:7]
	v_mfma_f32_16x16x32_bf16 v[0:3], v[216:219], v[232:235], v[0:3]
	v_mfma_f32_16x16x32_bf16 v[28:31], v[196:199], v[228:231], v[28:31]
	v_mfma_f32_16x16x32_bf16 v[24:27], v[196:199], v[236:239], v[24:27]
	v_mfma_f32_16x16x32_bf16 v[20:23], v[204:207], v[228:231], v[20:23]
	v_mfma_f32_16x16x32_bf16 v[16:19], v[204:207], v[236:239], v[16:19]
	v_mfma_f32_16x16x32_bf16 v[12:15], v[212:215], v[228:231], v[12:15]
	v_mfma_f32_16x16x32_bf16 v[8:11], v[212:215], v[236:239], v[8:11]
	v_mfma_f32_16x16x32_bf16 v[4:7], v[220:223], v[228:231], v[4:7]
	v_mfma_f32_16x16x32_bf16 v[0:3], v[220:223], v[236:239], v[0:3]
	s_setprio 0
	s_barrier
	ds_read_b128 v[176:179], v157
	ds_read_b128 v[180:183], v157 offset:1024
	ds_read_b128 v[184:187], v157 offset:2048
	ds_read_b128 v[188:191], v157 offset:3072
	v_readfirstlane_b32 s55, v163
	v_lshl_add_u64 v[224:225], v[240:241], 0, s[14:15]
	s_mov_b32 m0, s55
	v_readfirstlane_b32 s55, v164
	ds_read_b128 v[192:195], v154 offset:32768
	ds_read_b128 v[196:199], v154 offset:33792
	ds_read_b128 v[200:203], v153 offset:32768
	ds_read_b128 v[204:207], v153 offset:33792
	ds_read_b128 v[208:211], v152 offset:32768
	ds_read_b128 v[212:215], v152 offset:33792
	ds_read_b128 v[216:219], v151 offset:32768
	ds_read_b128 v[220:223], v151 offset:33792
	global_load_lds_dwordx4 v[224:225], off
	v_lshl_add_u64 v[224:225], v[242:243], 0, s[14:15]
	s_mov_b32 m0, s55
	s_nop 0
	global_load_lds_dwordx4 v[224:225], off
	s_waitcnt lgkmcnt(8)
	s_barrier
	s_waitcnt lgkmcnt(0)
	s_setprio 1
	v_mfma_f32_16x16x32_bf16 v[124:127], v[192:195], v[176:179], v[124:127]
	v_mfma_f32_16x16x32_bf16 v[120:123], v[192:195], v[184:187], v[120:123]
	v_mfma_f32_16x16x32_bf16 v[116:119], v[200:203], v[176:179], v[116:119]
	v_mfma_f32_16x16x32_bf16 v[112:115], v[200:203], v[184:187], v[112:115]
	v_mfma_f32_16x16x32_bf16 v[108:111], v[208:211], v[176:179], v[108:111]
	v_mfma_f32_16x16x32_bf16 v[104:107], v[208:211], v[184:187], v[104:107]
	v_mfma_f32_16x16x32_bf16 v[100:103], v[216:219], v[176:179], v[100:103]
	v_mfma_f32_16x16x32_bf16 v[96:99], v[216:219], v[184:187], v[96:99]
	v_mfma_f32_16x16x32_bf16 v[124:127], v[196:199], v[180:183], v[124:127]
	v_mfma_f32_16x16x32_bf16 v[120:123], v[196:199], v[188:191], v[120:123]
	v_mfma_f32_16x16x32_bf16 v[116:119], v[204:207], v[180:183], v[116:119]
	v_mfma_f32_16x16x32_bf16 v[112:115], v[204:207], v[188:191], v[112:115]
	v_mfma_f32_16x16x32_bf16 v[108:111], v[212:215], v[180:183], v[108:111]
	v_mfma_f32_16x16x32_bf16 v[104:107], v[212:215], v[188:191], v[104:107]
	v_mfma_f32_16x16x32_bf16 v[100:103], v[220:223], v[180:183], v[100:103]
	v_mfma_f32_16x16x32_bf16 v[96:99], v[220:223], v[188:191], v[96:99]
	s_setprio 0
	s_barrier
	v_readfirstlane_b32 s55, v165
	v_lshl_add_u64 v[248:249], v[244:245], 0, s[24:25]
	s_mov_b32 m0, s55
	v_readfirstlane_b32 s55, v166
	ds_read_b128 v[224:227], v155
	ds_read_b128 v[228:231], v155 offset:1024
	ds_read_b128 v[232:235], v155 offset:2048
	ds_read_b128 v[236:239], v155 offset:3072
	global_load_lds_dwordx4 v[248:249], off
	v_lshl_add_u64 v[248:249], v[246:247], 0, s[24:25]
	s_mov_b32 m0, s55
	s_nop 0
	global_load_lds_dwordx4 v[248:249], off
	s_barrier
	s_waitcnt lgkmcnt(0)
	s_setprio 1
	v_mfma_f32_16x16x32_bf16 v[92:95], v[192:195], v[224:227], v[92:95]
	v_mfma_f32_16x16x32_bf16 v[88:91], v[192:195], v[232:235], v[88:91]
	v_mfma_f32_16x16x32_bf16 v[84:87], v[200:203], v[224:227], v[84:87]
	v_mfma_f32_16x16x32_bf16 v[80:83], v[200:203], v[232:235], v[80:83]
	v_mfma_f32_16x16x32_bf16 v[76:79], v[208:211], v[224:227], v[76:79]
	v_mfma_f32_16x16x32_bf16 v[72:75], v[208:211], v[232:235], v[72:75]
	v_mfma_f32_16x16x32_bf16 v[68:71], v[216:219], v[224:227], v[68:71]
	v_mfma_f32_16x16x32_bf16 v[64:67], v[216:219], v[232:235], v[64:67]
	v_mfma_f32_16x16x32_bf16 v[92:95], v[196:199], v[228:231], v[92:95]
	v_mfma_f32_16x16x32_bf16 v[88:91], v[196:199], v[236:239], v[88:91]
	v_mfma_f32_16x16x32_bf16 v[84:87], v[204:207], v[228:231], v[84:87]
	v_mfma_f32_16x16x32_bf16 v[80:83], v[204:207], v[236:239], v[80:83]
	v_mfma_f32_16x16x32_bf16 v[76:79], v[212:215], v[228:231], v[76:79]
	v_mfma_f32_16x16x32_bf16 v[72:75], v[212:215], v[236:239], v[72:75]
	v_mfma_f32_16x16x32_bf16 v[68:71], v[220:223], v[228:231], v[68:71]
	v_mfma_f32_16x16x32_bf16 v[64:67], v[220:223], v[236:239], v[64:67]
	s_setprio 0
	v_readfirstlane_b32 s55, v167
	v_lshl_add_u64 v[240:241], v[240:241], 0, s[42:43]
	s_mov_b32 m0, s55
	v_readfirstlane_b32 s55, v168
	s_barrier
	ds_read_b128 v[192:195], v154 offset:49152
	ds_read_b128 v[196:199], v154 offset:50176
	ds_read_b128 v[200:203], v153 offset:49152
	ds_read_b128 v[204:207], v153 offset:50176
	ds_read_b128 v[208:211], v152 offset:49152
	ds_read_b128 v[212:215], v152 offset:50176
	ds_read_b128 v[216:219], v151 offset:49152
	ds_read_b128 v[220:223], v151 offset:50176
	global_load_lds_dwordx4 v[240:241], off
	v_lshl_add_u64 v[240:241], v[242:243], 0, s[42:43]
	s_mov_b32 m0, s55
	s_nop 0
	global_load_lds_dwordx4 v[240:241], off
	s_barrier
; #define STAGE(P, BASE, kt) do { const char* _g = (const char*)(BASE) + (size_t)((kt) * (BK * 2)); \
;     __builtin_amdgcn_global_load_lds((const unsigned*)(_g + (size_t)goff0), (unsigned*)((char*)(P) + tid_ * 16), 16, 0, 0); \
;     __builtin_amdgcn_global_load_lds((const unsigned*)(_g + (size_t)goff1), (unsigned*)((char*)(P) + tid_ * 16 + 8192), 16, 0, 0); } while (0)
; #define STAGEA(P, BASE, kt) do { const char* _g = (const char*)(BASE) + (size_t)((kt) * a_kbytes); \
;     __builtin_amdgcn_global_load_lds((const unsigned*)(_g + (size_t)goffA0), (unsigned*)((char*)(P) + tid_ * 16), 16, 0, 0); \
;     __builtin_amdgcn_global_load_lds((const unsigned*)(_g + (size_t)goffA1), (unsigned*)((char*)(P) + tid_ * 16 + 8192), 16, 0, 0); } while (0)
; #define LDA(dst, b, h) for (int m = 0; m < 4; ++m) for (int k = 0; k < 2; ++k) \
;     dst[m][k] = *reinterpret_cast<const bf16x8*>((char*)SA(b, h) + lds_byte(wr * 64 + m * 16 + fr, k * 32 + fq * 8))
; #define LDB(dst, b, h) for (int n = 0; n < 2; ++n) for (int k = 0; k < 2; ++k) \
;     dst[n][k] = *reinterpret_cast<const bf16x8*>((char*)SB(b, h) + lds_byte(wc * 32 + n * 16 + fr, k * 32 + fq * 8))
; #define MMA(ai, bj, At, Bt) do { __builtin_amdgcn_s_setprio(1); \
;     for (int m = 0; m < 4; ++m) for (int n = 0; n < 2; ++n) for (int k = 0; k < 2; ++k) \
;       acc[ai][bj][m][n] = __builtin_amdgcn_mfma_f32_16x16x32_bf16(At[m][k], Bt[n][k], acc[ai][bj][m][n], 0, 0, 0); \
;     __builtin_amdgcn_s_setprio(0); } while (0)
; #define WAIT_V(n) asm volatile("s_waitcnt vmcnt(" #n ")" ::: "memory")
; #define WAIT_L(n) asm volatile("s_waitcnt lgkmcnt(" #n ")" ::: "memory")
; #define BAR __builtin_amdgcn_s_barrier()
; #define SCHED __builtin_amdgcn_sched_barrier(0)
; template <int EPI> ...
;     ...
;     BAR; WAIT_L(0); MMA(1, 0, At, B0); BAR; SCHED;
;     STAGE(SB(1, 1), B1p, t + 3);
;     WAIT_V(6); BAR; MMA(1, 1, At, B1); BAR;
;   }
;   { LDB(B0, 0, 0); LDA(At, 0, 0); STAGEA(SA(1, 1), A1, nt - 1);
;     BAR; WAIT_L(0); MMA(0, 0, At, B0); BAR;
;     LDB(B1, 0, 1); BAR; WAIT_L(0); MMA(0, 1, At, B1); BAR;
	s_waitcnt lgkmcnt(0)
	s_setprio 1
	v_mfma_f32_16x16x32_bf16 v[60:63], v[192:195], v[176:179], v[60:63]
	v_mfma_f32_16x16x32_bf16 v[56:59], v[192:195], v[184:187], v[56:59]
	v_mfma_f32_16x16x32_bf16 v[52:55], v[200:203], v[176:179], v[52:55]
	v_mfma_f32_16x16x32_bf16 v[48:51], v[200:203], v[184:187], v[48:51]
	v_mfma_f32_16x16x32_bf16 v[44:47], v[208:211], v[176:179], v[44:47]
	v_mfma_f32_16x16x32_bf16 v[40:43], v[208:211], v[184:187], v[40:43]
	v_mfma_f32_16x16x32_bf16 v[36:39], v[216:219], v[176:179], v[36:39]
	v_mfma_f32_16x16x32_bf16 v[32:35], v[216:219], v[184:187], v[32:35]
	v_mfma_f32_16x16x32_bf16 v[60:63], v[196:199], v[180:183], v[60:63]
	v_mfma_f32_16x16x32_bf16 v[56:59], v[196:199], v[188:191], v[56:59]
	v_mfma_f32_16x16x32_bf16 v[52:55], v[204:207], v[180:183], v[52:55]
	v_mfma_f32_16x16x32_bf16 v[48:51], v[204:207], v[188:191], v[48:51]
	v_mfma_f32_16x16x32_bf16 v[44:47], v[212:215], v[180:183], v[44:47]
	v_mfma_f32_16x16x32_bf16 v[40:43], v[212:215], v[188:191], v[40:43]
	v_mfma_f32_16x16x32_bf16 v[36:39], v[220:223], v[180:183], v[36:39]
	v_mfma_f32_16x16x32_bf16 v[32:35], v[220:223], v[188:191], v[32:35]
	s_setprio 0
	s_barrier
	v_readfirstlane_b32 s55, v170
	v_lshl_add_u64 v[176:177], v[244:245], 0, s[46:47]
	s_mov_b32 m0, s55
	v_readfirstlane_b32 s55, v171
	global_load_lds_dwordx4 v[176:177], off
	v_lshl_add_u64 v[176:177], v[246:247], 0, s[46:47]
	s_mov_b32 m0, s55
	s_nop 0
	global_load_lds_dwordx4 v[176:177], off
	s_waitcnt vmcnt(6)
	s_barrier
	s_setprio 1
	v_mfma_f32_16x16x32_bf16 v[28:31], v[192:195], v[224:227], v[28:31]
	v_mfma_f32_16x16x32_bf16 v[24:27], v[192:195], v[232:235], v[24:27]
	v_mfma_f32_16x16x32_bf16 v[20:23], v[200:203], v[224:227], v[20:23]
	v_mfma_f32_16x16x32_bf16 v[16:19], v[200:203], v[232:235], v[16:19]
	v_mfma_f32_16x16x32_bf16 v[12:15], v[208:211], v[224:227], v[12:15]
	v_mfma_f32_16x16x32_bf16 v[8:11], v[208:211], v[232:235], v[8:11]
	v_mfma_f32_16x16x32_bf16 v[4:7], v[216:219], v[224:227], v[4:7]
	v_mfma_f32_16x16x32_bf16 v[0:3], v[216:219], v[232:235], v[0:3]
	v_mfma_f32_16x16x32_bf16 v[28:31], v[196:199], v[228:231], v[28:31]
	v_mfma_f32_16x16x32_bf16 v[24:27], v[196:199], v[236:239], v[24:27]
	v_mfma_f32_16x16x32_bf16 v[20:23], v[204:207], v[228:231], v[20:23]
	v_mfma_f32_16x16x32_bf16 v[16:19], v[204:207], v[236:239], v[16:19]
	v_mfma_f32_16x16x32_bf16 v[12:15], v[212:215], v[228:231], v[12:15]
	v_mfma_f32_16x16x32_bf16 v[8:11], v[212:215], v[236:239], v[8:11]
	v_mfma_f32_16x16x32_bf16 v[4:7], v[220:223], v[228:231], v[4:7]
	v_mfma_f32_16x16x32_bf16 v[0:3], v[220:223], v[236:239], v[0:3]
	s_setprio 0
	s_add_i32 s53, s53, 2
	s_add_u32 s58, s58, 0x100
	s_addc_u32 s59, s59, 0
	s_cmp_lt_u32 s53, 28
	s_barrier
	s_cbranch_scc1 .LBB0_760
	s_add_u32 s56, s56, 0x80f80
	s_addc_u32 s57, s57, 0
	v_readfirstlane_b32 s53, v173
	v_lshl_add_u64 v[166:167], s[56:57], 0, v[134:135]
	s_mov_b32 m0, s53
	v_readfirstlane_b32 s53, v174
	ds_read_b128 v[128:131], v172
	ds_read_b128 v[142:145], v172 offset:1024
	ds_read_b128 v[158:161], v172 offset:2048
	ds_read_b128 v[162:165], v172 offset:3072
	ds_read_b128 v[176:179], v154
	ds_read_b128 v[180:183], v154 offset:1024
	ds_read_b128 v[184:187], v153
	ds_read_b128 v[188:191], v153 offset:1024
	ds_read_b128 v[192:195], v152
	ds_read_b128 v[196:199], v152 offset:1024
	ds_read_b128 v[200:203], v151
	ds_read_b128 v[204:207], v151 offset:1024
	global_load_lds_dwordx4 v[166:167], off
	v_lshl_add_u64 v[166:167], s[56:57], 0, v[132:133]
	s_mov_b32 m0, s53
	s_nop 0
	global_load_lds_dwordx4 v[166:167], off
	s_barrier
	s_waitcnt lgkmcnt(0)
	s_setprio 1
	v_mfma_f32_16x16x32_bf16 v[124:127], v[176:179], v[128:131], v[124:127]
	v_mfma_f32_16x16x32_bf16 v[120:123], v[176:179], v[158:161], v[120:123]
	v_mfma_f32_16x16x32_bf16 v[108:111], v[192:195], v[128:131], v[108:111]
	v_mfma_f32_16x16x32_bf16 v[104:107], v[192:195], v[158:161], v[104:107]
	v_mfma_f32_16x16x32_bf16 v[124:127], v[180:183], v[142:145], v[124:127]
	v_mfma_f32_16x16x32_bf16 v[120:123], v[180:183], v[162:165], v[120:123]
	v_mfma_f32_16x16x32_bf16 v[116:119], v[184:187], v[128:131], v[116:119]
	v_mfma_f32_16x16x32_bf16 v[112:115], v[184:187], v[158:161], v[112:115]
	v_mfma_f32_16x16x32_bf16 v[108:111], v[196:199], v[142:145], v[108:111]
	v_mfma_f32_16x16x32_bf16 v[104:107], v[196:199], v[162:165], v[104:107]
	v_mfma_f32_16x16x32_bf16 v[100:103], v[200:203], v[128:131], v[100:103]
	v_mfma_f32_16x16x32_bf16 v[96:99], v[200:203], v[158:161], v[96:99]
	v_mfma_f32_16x16x32_bf16 v[170:173], v[188:191], v[142:145], v[116:119]
	v_mfma_f32_16x16x32_bf16 v[208:211], v[188:191], v[162:165], v[112:115]
	v_mfma_f32_16x16x32_bf16 v[212:215], v[204:207], v[142:145], v[100:103]
	v_mfma_f32_16x16x32_bf16 v[216:219], v[204:207], v[162:165], v[96:99]
	s_setprio 0
	s_barrier
	s_nop 1
	ds_read_b128 v[96:99], v169
	ds_read_b128 v[100:103], v169 offset:1024
	ds_read_b128 v[112:115], v169 offset:2048
	ds_read_b128 v[116:119], v169 offset:3072
	s_barrier
	s_waitcnt lgkmcnt(0)
	s_setprio 1
	v_mfma_f32_16x16x32_bf16 v[92:95], v[176:179], v[96:99], v[92:95]
	v_mfma_f32_16x16x32_bf16 v[88:91], v[176:179], v[112:115], v[88:91]
	v_mfma_f32_16x16x32_bf16 v[76:79], v[192:195], v[96:99], v[76:79]
	v_mfma_f32_16x16x32_bf16 v[72:75], v[192:195], v[112:115], v[72:75]
	v_mfma_f32_16x16x32_bf16 v[92:95], v[180:183], v[100:103], v[92:95]
	v_mfma_f32_16x16x32_bf16 v[88:91], v[180:183], v[116:119], v[88:91]
	v_mfma_f32_16x16x32_bf16 v[84:87], v[184:187], v[96:99], v[84:87]
	v_mfma_f32_16x16x32_bf16 v[80:83], v[184:187], v[112:115], v[80:83]
	v_mfma_f32_16x16x32_bf16 v[76:79], v[196:199], v[100:103], v[76:79]
	v_mfma_f32_16x16x32_bf16 v[72:75], v[196:199], v[116:119], v[72:75]
	v_mfma_f32_16x16x32_bf16 v[68:71], v[200:203], v[96:99], v[68:71]
	v_mfma_f32_16x16x32_bf16 v[64:67], v[200:203], v[112:115], v[64:67]
	v_mfma_f32_16x16x32_bf16 v[166:169], v[188:191], v[100:103], v[84:87]
	v_mfma_f32_16x16x32_bf16 v[174:177], v[188:191], v[116:119], v[80:83]
	v_mfma_f32_16x16x32_bf16 v[178:181], v[204:207], v[100:103], v[68:71]
	v_mfma_f32_16x16x32_bf16 v[182:185], v[204:207], v[116:119], v[64:67]
	s_setprio 0
	s_barrier
; #define LDA(dst, b, h) for (int m = 0; m < 4; ++m) for (int k = 0; k < 2; ++k) \
;     dst[m][k] = *reinterpret_cast<const bf16x8*>((char*)SA(b, h) + lds_byte(wr * 64 + m * 16 + fr, k * 32 + fq * 8))
; #define LDB(dst, b, h) for (int n = 0; n < 2; ++n) for (int k = 0; k < 2; ++k) \
;     dst[n][k] = *reinterpret_cast<const bf16x8*>((char*)SB(b, h) + lds_byte(wc * 32 + n * 16 + fr, k * 32 + fq * 8))
; #define MMA(ai, bj, At, Bt) do { __builtin_amdgcn_s_setprio(1); \
;     for (int m = 0; m < 4; ++m) for (int n = 0; n < 2; ++n) for (int k = 0; k < 2; ++k) \
;       acc[ai][bj][m][n] = __builtin_amdgcn_mfma_f32_16x16x32_bf16(At[m][k], Bt[n][k], acc[ai][bj][m][n], 0, 0, 0); \
;     __builtin_amdgcn_s_setprio(0); } while (0)
; #define WAIT_V(n) asm volatile("s_waitcnt vmcnt(" #n ")" ::: "memory")
; #define WAIT_L(n) asm volatile("s_waitcnt lgkmcnt(" #n ")" ::: "memory")
; #define BAR __builtin_amdgcn_s_barrier()
; template <int EPI> ...
;     ...
;     LDA(At, 0, 1); WAIT_V(4); BAR; WAIT_L(0); MMA(1, 0, At, B0); MMA(1, 1, At, B1); BAR; }
;   { LDB(B0, 1, 0); LDA(At, 1, 0); WAIT_V(2); BAR; WAIT_L(0); MMA(0, 0, At, B0); BAR;
	s_nop 1
	ds_read_b128 v[64:67], v154 offset:16384
	ds_read_b128 v[68:71], v154 offset:17408
	ds_read_b128 v[80:83], v153 offset:16384
	ds_read_b128 v[84:87], v153 offset:17408
	ds_read_b128 v[186:189], v152 offset:16384
	ds_read_b128 v[190:193], v152 offset:17408
	ds_read_b128 v[194:197], v151 offset:16384
	ds_read_b128 v[198:201], v151 offset:17408
	s_waitcnt vmcnt(4)
	s_barrier
	s_waitcnt lgkmcnt(0)
	s_setprio 1
	v_mfma_f32_16x16x32_bf16 v[60:63], v[64:67], v[128:131], v[60:63]
	v_mfma_f32_16x16x32_bf16 v[52:55], v[80:83], v[128:131], v[52:55]
	v_mfma_f32_16x16x32_bf16 v[44:47], v[186:189], v[128:131], v[44:47]
	v_mfma_f32_16x16x32_bf16 v[36:39], v[194:197], v[128:131], v[36:39]
	v_mfma_f32_16x16x32_bf16 v[60:63], v[68:71], v[142:145], v[60:63]
	v_mfma_f32_16x16x32_bf16 v[56:59], v[64:67], v[158:161], v[56:59]
	v_mfma_f32_16x16x32_bf16 v[52:55], v[84:87], v[142:145], v[52:55]
	v_mfma_f32_16x16x32_bf16 v[48:51], v[80:83], v[158:161], v[48:51]
	v_mfma_f32_16x16x32_bf16 v[44:47], v[190:193], v[142:145], v[44:47]
	v_mfma_f32_16x16x32_bf16 v[40:43], v[186:189], v[158:161], v[40:43]
	v_mfma_f32_16x16x32_bf16 v[36:39], v[198:201], v[142:145], v[36:39]
	v_mfma_f32_16x16x32_bf16 v[32:35], v[194:197], v[158:161], v[32:35]
	v_mfma_f32_16x16x32_bf16 v[202:205], v[68:71], v[162:165], v[56:59]
	v_mfma_f32_16x16x32_bf16 v[220:223], v[84:87], v[162:165], v[48:51]
	v_mfma_f32_16x16x32_bf16 v[224:227], v[190:193], v[162:165], v[40:43]
	v_mfma_f32_16x16x32_bf16 v[128:131], v[198:201], v[162:165], v[32:35]
	s_setprio 0
	s_setprio 1
	v_mfma_f32_16x16x32_bf16 v[28:31], v[64:67], v[96:99], v[28:31]
	v_mfma_f32_16x16x32_bf16 v[20:23], v[80:83], v[96:99], v[20:23]
	v_mfma_f32_16x16x32_bf16 v[12:15], v[186:189], v[96:99], v[12:15]
	v_mfma_f32_16x16x32_bf16 v[4:7], v[194:197], v[96:99], v[4:7]
	v_mfma_f32_16x16x32_bf16 v[28:31], v[68:71], v[100:103], v[28:31]
	v_mfma_f32_16x16x32_bf16 v[24:27], v[64:67], v[112:115], v[24:27]
	v_mfma_f32_16x16x32_bf16 v[20:23], v[84:87], v[100:103], v[20:23]
	v_mfma_f32_16x16x32_bf16 v[16:19], v[80:83], v[112:115], v[16:19]
	v_mfma_f32_16x16x32_bf16 v[12:15], v[190:193], v[100:103], v[12:15]
	v_mfma_f32_16x16x32_bf16 v[8:11], v[186:189], v[112:115], v[8:11]
	v_mfma_f32_16x16x32_bf16 v[4:7], v[198:201], v[100:103], v[4:7]
	v_mfma_f32_16x16x32_bf16 v[0:3], v[194:197], v[112:115], v[0:3]
	v_mfma_f32_16x16x32_bf16 v[142:145], v[68:71], v[116:119], v[24:27]
	v_mfma_f32_16x16x32_bf16 v[158:161], v[84:87], v[116:119], v[16:19]
	v_mfma_f32_16x16x32_bf16 v[162:165], v[190:193], v[116:119], v[8:11]
	v_mfma_f32_16x16x32_bf16 v[186:189], v[198:201], v[116:119], v[0:3]
	s_setprio 0
	s_barrier
	s_nop 1
	ds_read_b128 v[0:3], v157
	ds_read_b128 v[8:11], v157 offset:1024
	ds_read_b128 v[190:193], v157 offset:2048
	ds_read_b128 v[194:197], v157 offset:3072
	ds_read_b128 v[16:19], v154 offset:32768
	ds_read_b128 v[24:27], v154 offset:33792
	ds_read_b128 v[32:35], v153 offset:32768
	ds_read_b128 v[40:43], v153 offset:33792
	ds_read_b128 v[48:51], v152 offset:32768
	ds_read_b128 v[56:59], v152 offset:33792
	ds_read_b128 v[198:201], v151 offset:32768
	ds_read_b128 v[228:231], v151 offset:33792
	s_waitcnt vmcnt(2)
	s_barrier
	s_waitcnt lgkmcnt(0)
	s_setprio 1
	v_mfma_f32_16x16x32_bf16 v[64:67], v[16:19], v[0:3], v[124:127]
	v_mfma_f32_16x16x32_bf16 v[116:119], v[24:27], v[8:11], v[64:67]
	v_mfma_f32_16x16x32_bf16 v[64:67], v[16:19], v[190:193], v[120:123]
	v_mfma_f32_16x16x32_bf16 v[112:115], v[24:27], v[194:197], v[64:67]
	v_mfma_f32_16x16x32_bf16 v[64:67], v[32:35], v[0:3], v[170:173]
	v_mfma_f32_16x16x32_bf16 v[100:103], v[40:43], v[8:11], v[64:67]
	v_mfma_f32_16x16x32_bf16 v[64:67], v[32:35], v[190:193], v[208:211]
	v_mfma_f32_16x16x32_bf16 v[96:99], v[40:43], v[194:197], v[64:67]
	v_mfma_f32_16x16x32_bf16 v[64:67], v[48:51], v[0:3], v[108:111]
	v_mfma_f32_16x16x32_bf16 v[84:87], v[56:59], v[8:11], v[64:67]
	v_mfma_f32_16x16x32_bf16 v[64:67], v[48:51], v[190:193], v[104:107]
	v_mfma_f32_16x16x32_bf16 v[80:83], v[56:59], v[194:197], v[64:67]
	v_mfma_f32_16x16x32_bf16 v[64:67], v[198:201], v[0:3], v[212:215]
	v_mfma_f32_16x16x32_bf16 v[68:71], v[228:231], v[8:11], v[64:67]
	v_mfma_f32_16x16x32_bf16 v[64:67], v[198:201], v[190:193], v[216:219]
	v_mfma_f32_16x16x32_bf16 v[64:67], v[228:231], v[194:197], v[64:67]
	s_setprio 0
	s_barrier
; #define LDA(dst, b, h) for (int m = 0; m < 4; ++m) for (int k = 0; k < 2; ++k) \
;     dst[m][k] = *reinterpret_cast<const bf16x8*>((char*)SA(b, h) + lds_byte(wr * 64 + m * 16 + fr, k * 32 + fq * 8))
; #define LDB(dst, b, h) for (int n = 0; n < 2; ++n) for (int k = 0; k < 2; ++k) \
;     dst[n][k] = *reinterpret_cast<const bf16x8*>((char*)SB(b, h) + lds_byte(wc * 32 + n * 16 + fr, k * 32 + fq * 8))
; #define MMA(ai, bj, At, Bt) do { __builtin_amdgcn_s_setprio(1); \
;     for (int m = 0; m < 4; ++m) for (int n = 0; n < 2; ++n) for (int k = 0; k < 2; ++k) \
;       acc[ai][bj][m][n] = __builtin_amdgcn_mfma_f32_16x16x32_bf16(At[m][k], Bt[n][k], acc[ai][bj][m][n], 0, 0, 0); \
;     __builtin_amdgcn_s_setprio(0); } while (0)
; #define WAIT_V(n) asm volatile("s_waitcnt vmcnt(" #n ")" ::: "memory")
; #define WAIT_L(n) asm volatile("s_waitcnt lgkmcnt(" #n ")" ::: "memory")
; #define BAR __builtin_amdgcn_s_barrier()
; template <int EPI> ...
;     ...
;     LDB(B1, 1, 1); WAIT_V(0); BAR; WAIT_L(0); MMA(0, 1, At, B1); BAR;
;     LDA(At, 1, 1); BAR; WAIT_L(0); MMA(1, 0, At, B0); MMA(1, 1, At, B1); BAR; }
;   if (wr == 0) BAR;
	ds_read_b128 v[170:173], v155
	ds_read_b128 v[206:209], v155 offset:1024
	ds_read_b128 v[210:213], v155 offset:2048
	ds_read_b128 v[214:217], v155 offset:3072
	s_waitcnt vmcnt(0)
	s_barrier
	s_waitcnt lgkmcnt(0)
	s_setprio 1
	v_mfma_f32_16x16x32_bf16 v[92:95], v[16:19], v[170:173], v[92:95]
	v_mfma_f32_16x16x32_bf16 v[16:19], v[16:19], v[210:213], v[88:91]
	v_mfma_f32_16x16x32_bf16 v[120:123], v[24:27], v[214:217], v[16:19]
	v_mfma_f32_16x16x32_bf16 v[16:19], v[32:35], v[170:173], v[166:169]
	v_mfma_f32_16x16x32_bf16 v[108:111], v[40:43], v[206:209], v[16:19]
	v_mfma_f32_16x16x32_bf16 v[16:19], v[32:35], v[210:213], v[174:177]
	v_mfma_f32_16x16x32_bf16 v[104:107], v[40:43], v[214:217], v[16:19]
	v_mfma_f32_16x16x32_bf16 v[16:19], v[48:51], v[170:173], v[76:79]
	v_mfma_f32_16x16x32_bf16 v[124:127], v[24:27], v[206:209], v[92:95]
	v_mfma_f32_16x16x32_bf16 v[92:95], v[56:59], v[206:209], v[16:19]
	v_mfma_f32_16x16x32_bf16 v[16:19], v[48:51], v[210:213], v[72:75]
	v_mfma_f32_16x16x32_bf16 v[88:91], v[56:59], v[214:217], v[16:19]
	v_mfma_f32_16x16x32_bf16 v[16:19], v[198:201], v[170:173], v[178:181]
	v_mfma_f32_16x16x32_bf16 v[76:79], v[228:231], v[206:209], v[16:19]
	v_mfma_f32_16x16x32_bf16 v[16:19], v[198:201], v[210:213], v[182:185]
	v_mfma_f32_16x16x32_bf16 v[72:75], v[228:231], v[214:217], v[16:19]
	s_setprio 0
	s_barrier
	ds_read_b128 v[166:169], v154 offset:49152
	ds_read_b128 v[154:157], v154 offset:50176
	ds_read_b128 v[174:177], v153 offset:49152
	ds_read_b128 v[178:181], v153 offset:50176
	ds_read_b128 v[182:185], v152 offset:49152
	ds_read_b128 v[198:201], v152 offset:50176
	ds_read_b128 v[228:231], v151 offset:49152
	ds_read_b128 v[232:235], v151 offset:50176
	s_barrier
	s_waitcnt lgkmcnt(0)
	s_setprio 1
	v_mfma_f32_16x16x32_bf16 v[16:19], v[166:169], v[0:3], v[60:63]
	v_mfma_f32_16x16x32_bf16 v[56:59], v[154:157], v[8:11], v[16:19]
	v_mfma_f32_16x16x32_bf16 v[16:19], v[166:169], v[190:193], v[202:205]
	v_mfma_f32_16x16x32_bf16 v[48:51], v[154:157], v[194:197], v[16:19]
	v_mfma_f32_16x16x32_bf16 v[16:19], v[174:177], v[0:3], v[52:55]
	v_mfma_f32_16x16x32_bf16 v[40:43], v[178:181], v[8:11], v[16:19]
	v_mfma_f32_16x16x32_bf16 v[16:19], v[174:177], v[190:193], v[220:223]
	v_mfma_f32_16x16x32_bf16 v[32:35], v[178:181], v[194:197], v[16:19]
	v_mfma_f32_16x16x32_bf16 v[16:19], v[182:185], v[0:3], v[44:47]
	v_mfma_f32_16x16x32_bf16 v[0:3], v[228:231], v[0:3], v[36:39]
	v_mfma_f32_16x16x32_bf16 v[24:27], v[198:201], v[8:11], v[16:19]
	v_mfma_f32_16x16x32_bf16 v[16:19], v[182:185], v[190:193], v[224:227]
	v_mfma_f32_16x16x32_bf16 v[8:11], v[232:235], v[8:11], v[0:3]
	v_mfma_f32_16x16x32_bf16 v[0:3], v[228:231], v[190:193], v[128:131]
	v_mfma_f32_16x16x32_bf16 v[16:19], v[198:201], v[194:197], v[16:19]
	v_mfma_f32_16x16x32_bf16 v[0:3], v[232:235], v[194:197], v[0:3]
	s_setprio 0
	s_setprio 1
	v_mfma_f32_16x16x32_bf16 v[28:31], v[166:169], v[170:173], v[28:31]
	v_mfma_f32_16x16x32_bf16 v[60:63], v[154:157], v[206:209], v[28:31]
	v_mfma_f32_16x16x32_bf16 v[28:31], v[166:169], v[210:213], v[142:145]
	v_mfma_f32_16x16x32_bf16 v[20:23], v[174:177], v[170:173], v[20:23]
	v_mfma_f32_16x16x32_bf16 v[12:15], v[182:185], v[170:173], v[12:15]
	v_mfma_f32_16x16x32_bf16 v[52:55], v[154:157], v[214:217], v[28:31]
	v_mfma_f32_16x16x32_bf16 v[44:47], v[178:181], v[206:209], v[20:23]
	v_mfma_f32_16x16x32_bf16 v[20:23], v[174:177], v[210:213], v[158:161]
	v_mfma_f32_16x16x32_bf16 v[28:31], v[198:201], v[206:209], v[12:15]
	v_mfma_f32_16x16x32_bf16 v[12:15], v[182:185], v[210:213], v[162:165]
	v_mfma_f32_16x16x32_bf16 v[4:7], v[228:231], v[170:173], v[4:7]
	v_mfma_f32_16x16x32_bf16 v[36:39], v[178:181], v[214:217], v[20:23]
	v_mfma_f32_16x16x32_bf16 v[20:23], v[198:201], v[214:217], v[12:15]
	v_mfma_f32_16x16x32_bf16 v[12:15], v[232:235], v[206:209], v[4:7]
	v_mfma_f32_16x16x32_bf16 v[4:7], v[228:231], v[210:213], v[186:189]
	v_mfma_f32_16x16x32_bf16 v[4:7], v[232:235], v[214:217], v[4:7]
	s_setprio 0
	v_cmp_gt_u32_e32 vcc, s86, v136
	s_barrier
	s_and_saveexec_b64 s[56:57], vcc
	s_cbranch_execz .LBB0_763
	s_barrier

; #define STAGE(P, BASE, kt) do { const char* _g = (const char*)(BASE) + (size_t)((kt) * (BK * 2)); \
;     __builtin_amdgcn_global_load_lds((const unsigned*)(_g + (size_t)goff0), (unsigned*)((char*)(P) + tid_ * 16), 16, 0, 0); \
;     __builtin_amdgcn_global_load_lds((const unsigned*)(_g + (size_t)goff1), (unsigned*)((char*)(P) + tid_ * 16 + 8192), 16, 0, 0); } while (0)
; #define STAGEA(P, BASE, kt) do { const char* _g = (const char*)(BASE) + (size_t)((kt) * a_kbytes); \
;     __builtin_amdgcn_global_load_lds((const unsigned*)(_g + (size_t)goffA0), (unsigned*)((char*)(P) + tid_ * 16), 16, 0, 0); \
;     __builtin_amdgcn_global_load_lds((const unsigned*)(_g + (size_t)goffA1), (unsigned*)((char*)(P) + tid_ * 16 + 8192), 16, 0, 0); } while (0)
; #define LDA(dst, b, h) for (int m = 0; m < 4; ++m) for (int k = 0; k < 2; ++k) \
;     dst[m][k] = *reinterpret_cast<const bf16x8*>((char*)SA(b, h) + lds_byte(wr * 64 + m * 16 + fr, k * 32 + fq * 8))
; #define LDB(dst, b, h) for (int n = 0; n < 2; ++n) for (int k = 0; k < 2; ++k) \
;     dst[n][k] = *reinterpret_cast<const bf16x8*>((char*)SB(b, h) + lds_byte(wc * 32 + n * 16 + fr, k * 32 + fq * 8))
; #define MMA(ai, bj, At, Bt) do { __builtin_amdgcn_s_setprio(1); \
;     for (int m = 0; m < 4; ++m) for (int n = 0; n < 2; ++n) for (int k = 0; k < 2; ++k) \
;       acc[ai][bj][m][n] = __builtin_amdgcn_mfma_f32_16x16x32_bf16(At[m][k], Bt[n][k], acc[ai][bj][m][n], 0, 0, 0); \
;     __builtin_amdgcn_s_setprio(0); } while (0)
; #define WAIT_L(n) asm volatile("s_waitcnt lgkmcnt(" #n ")" ::: "memory")
; #define BAR __builtin_amdgcn_s_barrier()
; #define SCHED __builtin_amdgcn_sched_barrier(0)
; template <int EPI> ...
;     ...
;     LDB(B0, 0, 0); SCHED; LDA(At, 0, 0); STAGEA(SA(1, 1), A1, t + 1);
;     WAIT_L(8); BAR; WAIT_L(0); MMA(0, 0, At, B0); BAR; SCHED;
;     LDB(B1, 0, 1); STAGE(SB(0, 0), B0p, t + 2);
;     BAR; WAIT_L(0); MMA(0, 1, At, B1); BAR;
;     LDA(At, 0, 1); STAGEA(SA(0, 0), A0, t + 2);
;     BAR; WAIT_L(0); MMA(1, 0, At, B0); BAR; SCHED;
.LBB0_782:
	ds_read_b128 v[174:177], v171
	ds_read_b128 v[178:181], v171 offset:1024
	ds_read_b128 v[182:185], v171 offset:2048
	ds_read_b128 v[186:189], v171 offset:3072
	v_add_u32_e32 v172, 0xc000, v158
	v_lshl_add_u64 v[238:239], s[54:55], 0, v[136:137]
	v_readfirstlane_b32 s86, v172
	v_add_u32_e32 v173, 0xe000, v158
	v_lshl_add_u64 v[222:223], v[238:239], 0, s[4:5]
	s_mov_b32 m0, s86
	v_lshl_add_u64 v[240:241], s[54:55], 0, v[138:139]
	v_readfirstlane_b32 s86, v173
	ds_read_b128 v[190:193], v153
	ds_read_b128 v[194:197], v153 offset:1024
	ds_read_b128 v[198:201], v152
	ds_read_b128 v[202:205], v152 offset:1024
	ds_read_b128 v[206:209], v151
	ds_read_b128 v[210:213], v151 offset:1024
	ds_read_b128 v[214:217], v150
	ds_read_b128 v[218:221], v150 offset:1024
	global_load_lds_dwordx4 v[222:223], off
	v_lshl_add_u64 v[222:223], v[240:241], 0, s[4:5]
	s_mov_b32 m0, s86
	s_nop 0
	global_load_lds_dwordx4 v[222:223], off
	s_waitcnt lgkmcnt(8)
	s_barrier
	s_waitcnt lgkmcnt(0)
	s_setprio 1
	v_mfma_f32_16x16x32_bf16 v[124:127], v[190:193], v[174:177], v[124:127]
	v_mfma_f32_16x16x32_bf16 v[120:123], v[190:193], v[182:185], v[120:123]
	v_mfma_f32_16x16x32_bf16 v[116:119], v[198:201], v[174:177], v[116:119]
	v_mfma_f32_16x16x32_bf16 v[112:115], v[198:201], v[182:185], v[112:115]
	v_mfma_f32_16x16x32_bf16 v[108:111], v[206:209], v[174:177], v[108:111]
	v_mfma_f32_16x16x32_bf16 v[104:107], v[206:209], v[182:185], v[104:107]
	v_mfma_f32_16x16x32_bf16 v[100:103], v[214:217], v[174:177], v[100:103]
	v_mfma_f32_16x16x32_bf16 v[96:99], v[214:217], v[182:185], v[96:99]
	v_mfma_f32_16x16x32_bf16 v[124:127], v[194:197], v[178:181], v[124:127]
	v_mfma_f32_16x16x32_bf16 v[120:123], v[194:197], v[186:189], v[120:123]
	v_mfma_f32_16x16x32_bf16 v[116:119], v[202:205], v[178:181], v[116:119]
	v_mfma_f32_16x16x32_bf16 v[112:115], v[202:205], v[186:189], v[112:115]
	v_mfma_f32_16x16x32_bf16 v[108:111], v[210:213], v[178:181], v[108:111]
	v_mfma_f32_16x16x32_bf16 v[104:107], v[210:213], v[186:189], v[104:107]
	v_mfma_f32_16x16x32_bf16 v[100:103], v[218:221], v[178:181], v[100:103]
	v_mfma_f32_16x16x32_bf16 v[96:99], v[218:221], v[186:189], v[96:99]
	s_setprio 0
	s_barrier
	v_lshl_add_u64 v[242:243], s[52:53], 0, v[140:141]
	v_readfirstlane_b32 s86, v155
	v_lshl_add_u64 v[244:245], v[242:243], 0, s[6:7]
	s_mov_b32 m0, s86
	ds_read_b128 v[222:225], v167
	ds_read_b128 v[226:229], v167 offset:1024
	ds_read_b128 v[230:233], v167 offset:2048
	ds_read_b128 v[234:237], v167 offset:3072
	global_load_lds_dwordx4 v[244:245], off
	v_lshl_add_u64 v[244:245], s[52:53], 0, v[142:143]
	v_readfirstlane_b32 s86, v157
	v_lshl_add_u64 v[246:247], v[244:245], 0, s[6:7]
	s_mov_b32 m0, s86
	s_nop 0
	global_load_lds_dwordx4 v[246:247], off
	s_barrier
	s_waitcnt lgkmcnt(0)
	s_setprio 1
	v_mfma_f32_16x16x32_bf16 v[92:95], v[190:193], v[222:225], v[92:95]
	v_mfma_f32_16x16x32_bf16 v[88:91], v[190:193], v[230:233], v[88:91]
	v_mfma_f32_16x16x32_bf16 v[84:87], v[198:201], v[222:225], v[84:87]
	v_mfma_f32_16x16x32_bf16 v[80:83], v[198:201], v[230:233], v[80:83]
	v_mfma_f32_16x16x32_bf16 v[76:79], v[206:209], v[222:225], v[76:79]
	v_mfma_f32_16x16x32_bf16 v[72:75], v[206:209], v[230:233], v[72:75]
	v_mfma_f32_16x16x32_bf16 v[68:71], v[214:217], v[222:225], v[68:71]
	v_mfma_f32_16x16x32_bf16 v[64:67], v[214:217], v[230:233], v[64:67]
	v_mfma_f32_16x16x32_bf16 v[92:95], v[194:197], v[226:229], v[92:95]
	v_mfma_f32_16x16x32_bf16 v[88:91], v[194:197], v[234:237], v[88:91]
	v_mfma_f32_16x16x32_bf16 v[84:87], v[202:205], v[226:229], v[84:87]
	v_mfma_f32_16x16x32_bf16 v[80:83], v[202:205], v[234:237], v[80:83]
	v_mfma_f32_16x16x32_bf16 v[76:79], v[210:213], v[226:229], v[76:79]
	v_mfma_f32_16x16x32_bf16 v[72:75], v[210:213], v[234:237], v[72:75]
	v_mfma_f32_16x16x32_bf16 v[68:71], v[218:221], v[226:229], v[68:71]
	v_mfma_f32_16x16x32_bf16 v[64:67], v[218:221], v[234:237], v[64:67]
	s_setprio 0
	v_readfirstlane_b32 s86, v158
	v_lshl_add_u64 v[246:247], v[238:239], 0, s[8:9]
	s_mov_b32 m0, s86
	v_readfirstlane_b32 s86, v159
	s_barrier
	ds_read_b128 v[190:193], v153 offset:16384
	ds_read_b128 v[194:197], v153 offset:17408
	ds_read_b128 v[198:201], v152 offset:16384
	ds_read_b128 v[202:205], v152 offset:17408
	ds_read_b128 v[206:209], v151 offset:16384
	ds_read_b128 v[210:213], v151 offset:17408
	ds_read_b128 v[214:217], v150 offset:16384
	ds_read_b128 v[218:221], v150 offset:17408
	global_load_lds_dwordx4 v[246:247], off
	v_lshl_add_u64 v[246:247], v[240:241], 0, s[8:9]
	s_mov_b32 m0, s86
	s_nop 0
	global_load_lds_dwordx4 v[246:247], off
	s_barrier
	s_waitcnt lgkmcnt(0)
	s_setprio 1
	v_mfma_f32_16x16x32_bf16 v[60:63], v[190:193], v[174:177], v[60:63]
	v_mfma_f32_16x16x32_bf16 v[56:59], v[190:193], v[182:185], v[56:59]
	v_mfma_f32_16x16x32_bf16 v[52:55], v[198:201], v[174:177], v[52:55]
	v_mfma_f32_16x16x32_bf16 v[48:51], v[198:201], v[182:185], v[48:51]
	v_mfma_f32_16x16x32_bf16 v[44:47], v[206:209], v[174:177], v[44:47]
	v_mfma_f32_16x16x32_bf16 v[40:43], v[206:209], v[182:185], v[40:43]
	v_mfma_f32_16x16x32_bf16 v[36:39], v[214:217], v[174:177], v[36:39]
	v_mfma_f32_16x16x32_bf16 v[32:35], v[214:217], v[182:185], v[32:35]
	v_mfma_f32_16x16x32_bf16 v[60:63], v[194:197], v[178:181], v[60:63]
	v_mfma_f32_16x16x32_bf16 v[56:59], v[194:197], v[186:189], v[56:59]
	v_mfma_f32_16x16x32_bf16 v[52:55], v[202:205], v[178:181], v[52:55]
	v_mfma_f32_16x16x32_bf16 v[48:51], v[202:205], v[186:189], v[48:51]
	v_mfma_f32_16x16x32_bf16 v[44:47], v[210:213], v[178:181], v[44:47]
	v_mfma_f32_16x16x32_bf16 v[40:43], v[210:213], v[186:189], v[40:43]
	v_mfma_f32_16x16x32_bf16 v[36:39], v[218:221], v[178:181], v[36:39]
	v_mfma_f32_16x16x32_bf16 v[32:35], v[218:221], v[186:189], v[32:35]
	s_setprio 0
	s_barrier
; #define STAGE(P, BASE, kt) do { const char* _g = (const char*)(BASE) + (size_t)((kt) * (BK * 2)); \
;     __builtin_amdgcn_global_load_lds((const unsigned*)(_g + (size_t)goff0), (unsigned*)((char*)(P) + tid_ * 16), 16, 0, 0); \
;     __builtin_amdgcn_global_load_lds((const unsigned*)(_g + (size_t)goff1), (unsigned*)((char*)(P) + tid_ * 16 + 8192), 16, 0, 0); } while (0)
; #define STAGEA(P, BASE, kt) do { const char* _g = (const char*)(BASE) + (size_t)((kt) * a_kbytes); \
;     __builtin_amdgcn_global_load_lds((const unsigned*)(_g + (size_t)goffA0), (unsigned*)((char*)(P) + tid_ * 16), 16, 0, 0); \
;     __builtin_amdgcn_global_load_lds((const unsigned*)(_g + (size_t)goffA1), (unsigned*)((char*)(P) + tid_ * 16 + 8192), 16, 0, 0); } while (0)
; #define LDA(dst, b, h) for (int m = 0; m < 4; ++m) for (int k = 0; k < 2; ++k) \
;     dst[m][k] = *reinterpret_cast<const bf16x8*>((char*)SA(b, h) + lds_byte(wr * 64 + m * 16 + fr, k * 32 + fq * 8))
; #define LDB(dst, b, h) for (int n = 0; n < 2; ++n) for (int k = 0; k < 2; ++k) \
;     dst[n][k] = *reinterpret_cast<const bf16x8*>((char*)SB(b, h) + lds_byte(wc * 32 + n * 16 + fr, k * 32 + fq * 8))
; #define MMA(ai, bj, At, Bt) do { __builtin_amdgcn_s_setprio(1); \
;     for (int m = 0; m < 4; ++m) for (int n = 0; n < 2; ++n) for (int k = 0; k < 2; ++k) \
;       acc[ai][bj][m][n] = __builtin_amdgcn_mfma_f32_16x16x32_bf16(At[m][k], Bt[n][k], acc[ai][bj][m][n], 0, 0, 0); \
;     __builtin_amdgcn_s_setprio(0); } while (0)
; #define WAIT_V(n) asm volatile("s_waitcnt vmcnt(" #n ")" ::: "memory")
; #define WAIT_L(n) asm volatile("s_waitcnt lgkmcnt(" #n ")" ::: "memory")
; #define BAR __builtin_amdgcn_s_barrier()
; #define SCHED __builtin_amdgcn_sched_barrier(0)
; template <int EPI> ...
;     ...
;     STAGE(SB(0, 1), B1p, t + 2);
;     WAIT_V(6); BAR; MMA(1, 1, At, B1); BAR;
;     LDB(B0, 1, 0); SCHED; LDA(At, 1, 0); STAGEA(SA(0, 1), A1, t + 2);
;     WAIT_L(8); BAR; WAIT_L(0); MMA(0, 0, At, B0); BAR; SCHED;
;     LDB(B1, 1, 1); STAGE(SB(1, 0), B0p, t + 3);
;     BAR; WAIT_L(0); MMA(0, 1, At, B1); BAR;
;     LDA(At, 1, 1); STAGEA(SA(1, 0), A0, t + 3);
	v_readfirstlane_b32 s86, v160
	v_lshl_add_u64 v[174:175], v[242:243], 0, s[10:11]
	s_mov_b32 m0, s86
	v_readfirstlane_b32 s86, v161
	global_load_lds_dwordx4 v[174:175], off
	v_lshl_add_u64 v[174:175], v[244:245], 0, s[10:11]
	s_mov_b32 m0, s86
	s_nop 0
	global_load_lds_dwordx4 v[174:175], off
	s_waitcnt vmcnt(6)
	s_barrier
	s_setprio 1
	v_mfma_f32_16x16x32_bf16 v[28:31], v[190:193], v[222:225], v[28:31]
	v_mfma_f32_16x16x32_bf16 v[24:27], v[190:193], v[230:233], v[24:27]
	v_mfma_f32_16x16x32_bf16 v[20:23], v[198:201], v[222:225], v[20:23]
	v_mfma_f32_16x16x32_bf16 v[16:19], v[198:201], v[230:233], v[16:19]
	v_mfma_f32_16x16x32_bf16 v[12:15], v[206:209], v[222:225], v[12:15]
	v_mfma_f32_16x16x32_bf16 v[8:11], v[206:209], v[230:233], v[8:11]
	v_mfma_f32_16x16x32_bf16 v[4:7], v[214:217], v[222:225], v[4:7]
	v_mfma_f32_16x16x32_bf16 v[0:3], v[214:217], v[230:233], v[0:3]
	v_mfma_f32_16x16x32_bf16 v[28:31], v[194:197], v[226:229], v[28:31]
	v_mfma_f32_16x16x32_bf16 v[24:27], v[194:197], v[234:237], v[24:27]
	v_mfma_f32_16x16x32_bf16 v[20:23], v[202:205], v[226:229], v[20:23]
	v_mfma_f32_16x16x32_bf16 v[16:19], v[202:205], v[234:237], v[16:19]
	v_mfma_f32_16x16x32_bf16 v[12:15], v[210:213], v[226:229], v[12:15]
	v_mfma_f32_16x16x32_bf16 v[8:11], v[210:213], v[234:237], v[8:11]
	v_mfma_f32_16x16x32_bf16 v[4:7], v[218:221], v[226:229], v[4:7]
	v_mfma_f32_16x16x32_bf16 v[0:3], v[218:221], v[234:237], v[0:3]
	s_setprio 0
	s_barrier
	ds_read_b128 v[174:177], v156
	ds_read_b128 v[178:181], v156 offset:1024
	ds_read_b128 v[182:185], v156 offset:2048
	ds_read_b128 v[186:189], v156 offset:3072
	v_readfirstlane_b32 s86, v162
	v_lshl_add_u64 v[222:223], v[238:239], 0, s[12:13]
	s_mov_b32 m0, s86
	v_readfirstlane_b32 s86, v163
	ds_read_b128 v[190:193], v153 offset:32768
	ds_read_b128 v[194:197], v153 offset:33792
	ds_read_b128 v[198:201], v152 offset:32768
	ds_read_b128 v[202:205], v152 offset:33792
	ds_read_b128 v[206:209], v151 offset:32768
	ds_read_b128 v[210:213], v151 offset:33792
	ds_read_b128 v[214:217], v150 offset:32768
	ds_read_b128 v[218:221], v150 offset:33792
	global_load_lds_dwordx4 v[222:223], off
	v_lshl_add_u64 v[222:223], v[240:241], 0, s[12:13]
	s_mov_b32 m0, s86
	s_nop 0
	global_load_lds_dwordx4 v[222:223], off
	s_waitcnt lgkmcnt(8)
	s_barrier
	s_waitcnt lgkmcnt(0)
	s_setprio 1
	v_mfma_f32_16x16x32_bf16 v[124:127], v[190:193], v[174:177], v[124:127]
	v_mfma_f32_16x16x32_bf16 v[120:123], v[190:193], v[182:185], v[120:123]
	v_mfma_f32_16x16x32_bf16 v[116:119], v[198:201], v[174:177], v[116:119]
	v_mfma_f32_16x16x32_bf16 v[112:115], v[198:201], v[182:185], v[112:115]
	v_mfma_f32_16x16x32_bf16 v[108:111], v[206:209], v[174:177], v[108:111]
	v_mfma_f32_16x16x32_bf16 v[104:107], v[206:209], v[182:185], v[104:107]
	v_mfma_f32_16x16x32_bf16 v[100:103], v[214:217], v[174:177], v[100:103]
	v_mfma_f32_16x16x32_bf16 v[96:99], v[214:217], v[182:185], v[96:99]
	v_mfma_f32_16x16x32_bf16 v[124:127], v[194:197], v[178:181], v[124:127]
	v_mfma_f32_16x16x32_bf16 v[120:123], v[194:197], v[186:189], v[120:123]
	v_mfma_f32_16x16x32_bf16 v[116:119], v[202:205], v[178:181], v[116:119]
	v_mfma_f32_16x16x32_bf16 v[112:115], v[202:205], v[186:189], v[112:115]
	v_mfma_f32_16x16x32_bf16 v[108:111], v[210:213], v[178:181], v[108:111]
	v_mfma_f32_16x16x32_bf16 v[104:107], v[210:213], v[186:189], v[104:107]
	v_mfma_f32_16x16x32_bf16 v[100:103], v[218:221], v[178:181], v[100:103]
	v_mfma_f32_16x16x32_bf16 v[96:99], v[218:221], v[186:189], v[96:99]
	s_setprio 0
	s_barrier
	v_readfirstlane_b32 s86, v164
	v_lshl_add_u64 v[246:247], v[242:243], 0, s[14:15]
	s_mov_b32 m0, s86
	v_readfirstlane_b32 s86, v165
	ds_read_b128 v[222:225], v154
	ds_read_b128 v[226:229], v154 offset:1024
	ds_read_b128 v[230:233], v154 offset:2048
	ds_read_b128 v[234:237], v154 offset:3072
	global_load_lds_dwordx4 v[246:247], off
	v_lshl_add_u64 v[246:247], v[244:245], 0, s[14:15]
	s_mov_b32 m0, s86
	s_nop 0
	global_load_lds_dwordx4 v[246:247], off
	s_barrier
	s_waitcnt lgkmcnt(0)
	s_setprio 1
	v_mfma_f32_16x16x32_bf16 v[92:95], v[190:193], v[222:225], v[92:95]
	v_mfma_f32_16x16x32_bf16 v[88:91], v[190:193], v[230:233], v[88:91]
	v_mfma_f32_16x16x32_bf16 v[84:87], v[198:201], v[222:225], v[84:87]
	v_mfma_f32_16x16x32_bf16 v[80:83], v[198:201], v[230:233], v[80:83]
	v_mfma_f32_16x16x32_bf16 v[76:79], v[206:209], v[222:225], v[76:79]
	v_mfma_f32_16x16x32_bf16 v[72:75], v[206:209], v[230:233], v[72:75]
	v_mfma_f32_16x16x32_bf16 v[68:71], v[214:217], v[222:225], v[68:71]
	v_mfma_f32_16x16x32_bf16 v[64:67], v[214:217], v[230:233], v[64:67]
	v_mfma_f32_16x16x32_bf16 v[92:95], v[194:197], v[226:229], v[92:95]
	v_mfma_f32_16x16x32_bf16 v[88:91], v[194:197], v[234:237], v[88:91]
	v_mfma_f32_16x16x32_bf16 v[84:87], v[202:205], v[226:229], v[84:87]
	v_mfma_f32_16x16x32_bf16 v[80:83], v[202:205], v[234:237], v[80:83]
	v_mfma_f32_16x16x32_bf16 v[76:79], v[210:213], v[226:229], v[76:79]
	v_mfma_f32_16x16x32_bf16 v[72:75], v[210:213], v[234:237], v[72:75]
	v_mfma_f32_16x16x32_bf16 v[68:71], v[218:221], v[226:229], v[68:71]
	v_mfma_f32_16x16x32_bf16 v[64:67], v[218:221], v[234:237], v[64:67]
	s_setprio 0
	v_readfirstlane_b32 s86, v166
	v_lshl_add_u64 v[238:239], v[238:239], 0, s[24:25]
	s_mov_b32 m0, s86
	v_readfirstlane_b32 s86, v168
	s_barrier
	ds_read_b128 v[190:193], v153 offset:49152
	ds_read_b128 v[194:197], v153 offset:50176
	ds_read_b128 v[198:201], v152 offset:49152
	ds_read_b128 v[202:205], v152 offset:50176
	ds_read_b128 v[206:209], v151 offset:49152
	ds_read_b128 v[210:213], v151 offset:50176
	ds_read_b128 v[214:217], v150 offset:49152
	ds_read_b128 v[218:221], v150 offset:50176
	global_load_lds_dwordx4 v[238:239], off
	v_lshl_add_u64 v[238:239], v[240:241], 0, s[24:25]
	s_mov_b32 m0, s86
	s_nop 0
	global_load_lds_dwordx4 v[238:239], off
	s_barrier
; #define STAGE(P, BASE, kt) do { const char* _g = (const char*)(BASE) + (size_t)((kt) * (BK * 2)); \
;     __builtin_amdgcn_global_load_lds((const unsigned*)(_g + (size_t)goff0), (unsigned*)((char*)(P) + tid_ * 16), 16, 0, 0); \
;     __builtin_amdgcn_global_load_lds((const unsigned*)(_g + (size_t)goff1), (unsigned*)((char*)(P) + tid_ * 16 + 8192), 16, 0, 0); } while (0)
; #define STAGEA(P, BASE, kt) do { const char* _g = (const char*)(BASE) + (size_t)((kt) * a_kbytes); \
;     __builtin_amdgcn_global_load_lds((const unsigned*)(_g + (size_t)goffA0), (unsigned*)((char*)(P) + tid_ * 16), 16, 0, 0); \
;     __builtin_amdgcn_global_load_lds((const unsigned*)(_g + (size_t)goffA1), (unsigned*)((char*)(P) + tid_ * 16 + 8192), 16, 0, 0); } while (0)
; #define LDA(dst, b, h) for (int m = 0; m < 4; ++m) for (int k = 0; k < 2; ++k) \
;     dst[m][k] = *reinterpret_cast<const bf16x8*>((char*)SA(b, h) + lds_byte(wr * 64 + m * 16 + fr, k * 32 + fq * 8))
; #define LDB(dst, b, h) for (int n = 0; n < 2; ++n) for (int k = 0; k < 2; ++k) \
;     dst[n][k] = *reinterpret_cast<const bf16x8*>((char*)SB(b, h) + lds_byte(wc * 32 + n * 16 + fr, k * 32 + fq * 8))
; #define MMA(ai, bj, At, Bt) do { __builtin_amdgcn_s_setprio(1); \
;     for (int m = 0; m < 4; ++m) for (int n = 0; n < 2; ++n) for (int k = 0; k < 2; ++k) \
;       acc[ai][bj][m][n] = __builtin_amdgcn_mfma_f32_16x16x32_bf16(At[m][k], Bt[n][k], acc[ai][bj][m][n], 0, 0, 0); \
;     __builtin_amdgcn_s_setprio(0); } while (0)
; #define WAIT_V(n) asm volatile("s_waitcnt vmcnt(" #n ")" ::: "memory")
; #define WAIT_L(n) asm volatile("s_waitcnt lgkmcnt(" #n ")" ::: "memory")
; #define BAR __builtin_amdgcn_s_barrier()
; #define SCHED __builtin_amdgcn_sched_barrier(0)
; template <int EPI> ...
;     ...
;     BAR; WAIT_L(0); MMA(1, 0, At, B0); BAR; SCHED;
;     STAGE(SB(1, 1), B1p, t + 3);
;     WAIT_V(6); BAR; MMA(1, 1, At, B1); BAR;
;   }
;   { LDB(B0, 0, 0); LDA(At, 0, 0); STAGEA(SA(1, 1), A1, nt - 1);
;     BAR; WAIT_L(0); MMA(0, 0, At, B0); BAR;
;     LDB(B1, 0, 1); BAR; WAIT_L(0); MMA(0, 1, At, B1); BAR;
	s_waitcnt lgkmcnt(0)
	s_setprio 1
	v_mfma_f32_16x16x32_bf16 v[60:63], v[190:193], v[174:177], v[60:63]
	v_mfma_f32_16x16x32_bf16 v[56:59], v[190:193], v[182:185], v[56:59]
	v_mfma_f32_16x16x32_bf16 v[52:55], v[198:201], v[174:177], v[52:55]
	v_mfma_f32_16x16x32_bf16 v[48:51], v[198:201], v[182:185], v[48:51]
	v_mfma_f32_16x16x32_bf16 v[44:47], v[206:209], v[174:177], v[44:47]
	v_mfma_f32_16x16x32_bf16 v[40:43], v[206:209], v[182:185], v[40:43]
	v_mfma_f32_16x16x32_bf16 v[36:39], v[214:217], v[174:177], v[36:39]
	v_mfma_f32_16x16x32_bf16 v[32:35], v[214:217], v[182:185], v[32:35]
	v_mfma_f32_16x16x32_bf16 v[60:63], v[194:197], v[178:181], v[60:63]
	v_mfma_f32_16x16x32_bf16 v[56:59], v[194:197], v[186:189], v[56:59]
	v_mfma_f32_16x16x32_bf16 v[52:55], v[202:205], v[178:181], v[52:55]
	v_mfma_f32_16x16x32_bf16 v[48:51], v[202:205], v[186:189], v[48:51]
	v_mfma_f32_16x16x32_bf16 v[44:47], v[210:213], v[178:181], v[44:47]
	v_mfma_f32_16x16x32_bf16 v[40:43], v[210:213], v[186:189], v[40:43]
	v_mfma_f32_16x16x32_bf16 v[36:39], v[218:221], v[178:181], v[36:39]
	v_mfma_f32_16x16x32_bf16 v[32:35], v[218:221], v[186:189], v[32:35]
	s_setprio 0
	s_barrier
	v_readfirstlane_b32 s86, v169
	v_lshl_add_u64 v[174:175], v[242:243], 0, s[42:43]
	s_mov_b32 m0, s86
	v_readfirstlane_b32 s86, v170
	global_load_lds_dwordx4 v[174:175], off
	v_lshl_add_u64 v[174:175], v[244:245], 0, s[42:43]
	s_mov_b32 m0, s86
	s_nop 0
	global_load_lds_dwordx4 v[174:175], off
	s_waitcnt vmcnt(6)
	s_barrier
	s_setprio 1
	v_mfma_f32_16x16x32_bf16 v[28:31], v[190:193], v[222:225], v[28:31]
	v_mfma_f32_16x16x32_bf16 v[24:27], v[190:193], v[230:233], v[24:27]
	v_mfma_f32_16x16x32_bf16 v[20:23], v[198:201], v[222:225], v[20:23]
	v_mfma_f32_16x16x32_bf16 v[16:19], v[198:201], v[230:233], v[16:19]
	v_mfma_f32_16x16x32_bf16 v[12:15], v[206:209], v[222:225], v[12:15]
	v_mfma_f32_16x16x32_bf16 v[8:11], v[206:209], v[230:233], v[8:11]
	v_mfma_f32_16x16x32_bf16 v[4:7], v[214:217], v[222:225], v[4:7]
	v_mfma_f32_16x16x32_bf16 v[0:3], v[214:217], v[230:233], v[0:3]
	v_mfma_f32_16x16x32_bf16 v[28:31], v[194:197], v[226:229], v[28:31]
	v_mfma_f32_16x16x32_bf16 v[24:27], v[194:197], v[234:237], v[24:27]
	v_mfma_f32_16x16x32_bf16 v[20:23], v[202:205], v[226:229], v[20:23]
	v_mfma_f32_16x16x32_bf16 v[16:19], v[202:205], v[234:237], v[16:19]
	v_mfma_f32_16x16x32_bf16 v[12:15], v[210:213], v[226:229], v[12:15]
	v_mfma_f32_16x16x32_bf16 v[8:11], v[210:213], v[234:237], v[8:11]
	v_mfma_f32_16x16x32_bf16 v[4:7], v[218:221], v[226:229], v[4:7]
	v_mfma_f32_16x16x32_bf16 v[0:3], v[218:221], v[234:237], v[0:3]
	s_setprio 0
	s_add_i32 s85, s85, 2
	s_add_u32 s54, s54, 0x10000
	s_addc_u32 s55, s55, 0
	s_add_u32 s52, s52, 0x100
	s_addc_u32 s53, s53, 0
	s_cmpk_lt_u32 s85, 0x54
	s_barrier
	s_cbranch_scc1 .LBB0_782
	s_add_u32 s48, s48, 0x2bc000
	s_addc_u32 s49, s49, 0
	v_readfirstlane_b32 s52, v172
	v_lshl_add_u64 v[210:211], s[48:49], 0, v[130:131]
	s_mov_b32 m0, s52
	ds_read_b128 v[158:161], v171
	ds_read_b128 v[162:165], v171 offset:1024
	ds_read_b128 v[174:177], v171 offset:2048
	ds_read_b128 v[168:171], v171 offset:3072
	ds_read_b128 v[178:181], v153
	ds_read_b128 v[182:185], v153 offset:1024
	ds_read_b128 v[186:189], v152
	ds_read_b128 v[190:193], v152 offset:1024
	ds_read_b128 v[194:197], v151
	ds_read_b128 v[198:201], v151 offset:1024
	ds_read_b128 v[202:205], v150
	ds_read_b128 v[206:209], v150 offset:1024
	global_load_lds_dwordx4 v[210:211], off
	v_lshl_add_u64 v[210:211], s[48:49], 0, v[128:129]
	v_readfirstlane_b32 s48, v173
	s_mov_b32 m0, s48
	s_nop 0
	global_load_lds_dwordx4 v[210:211], off
	s_barrier
	s_waitcnt lgkmcnt(0)
	s_setprio 1
	v_mfma_f32_16x16x32_bf16 v[124:127], v[178:181], v[158:161], v[124:127]
	v_mfma_f32_16x16x32_bf16 v[120:123], v[178:181], v[174:177], v[120:123]
	v_mfma_f32_16x16x32_bf16 v[108:111], v[194:197], v[158:161], v[108:111]
	v_mfma_f32_16x16x32_bf16 v[104:107], v[194:197], v[174:177], v[104:107]
	v_mfma_f32_16x16x32_bf16 v[124:127], v[182:185], v[162:165], v[124:127]
	v_mfma_f32_16x16x32_bf16 v[120:123], v[182:185], v[168:171], v[120:123]
	v_mfma_f32_16x16x32_bf16 v[116:119], v[186:189], v[158:161], v[116:119]
	v_mfma_f32_16x16x32_bf16 v[112:115], v[186:189], v[174:177], v[112:115]
	v_mfma_f32_16x16x32_bf16 v[108:111], v[198:201], v[162:165], v[108:111]
	v_mfma_f32_16x16x32_bf16 v[104:107], v[198:201], v[168:171], v[104:107]
	v_mfma_f32_16x16x32_bf16 v[100:103], v[202:205], v[158:161], v[100:103]
	v_mfma_f32_16x16x32_bf16 v[96:99], v[202:205], v[174:177], v[96:99]
	v_mfma_f32_16x16x32_bf16 v[210:213], v[190:193], v[162:165], v[116:119]
	v_mfma_f32_16x16x32_bf16 v[214:217], v[190:193], v[168:171], v[112:115]
	v_mfma_f32_16x16x32_bf16 v[218:221], v[206:209], v[162:165], v[100:103]
	v_mfma_f32_16x16x32_bf16 v[222:225], v[206:209], v[168:171], v[96:99]
	s_setprio 0
	s_barrier
	s_nop 1
	ds_read_b128 v[96:99], v167
	ds_read_b128 v[100:103], v167 offset:1024
	ds_read_b128 v[112:115], v167 offset:2048
	ds_read_b128 v[116:119], v167 offset:3072
	s_barrier
	s_waitcnt lgkmcnt(0)
	s_setprio 1
	v_mfma_f32_16x16x32_bf16 v[92:95], v[178:181], v[96:99], v[92:95]
	v_mfma_f32_16x16x32_bf16 v[88:91], v[178:181], v[112:115], v[88:91]
	v_mfma_f32_16x16x32_bf16 v[76:79], v[194:197], v[96:99], v[76:79]
	v_mfma_f32_16x16x32_bf16 v[72:75], v[194:197], v[112:115], v[72:75]
	v_mfma_f32_16x16x32_bf16 v[92:95], v[182:185], v[100:103], v[92:95]
	v_mfma_f32_16x16x32_bf16 v[88:91], v[182:185], v[116:119], v[88:91]
	v_mfma_f32_16x16x32_bf16 v[84:87], v[186:189], v[96:99], v[84:87]
	v_mfma_f32_16x16x32_bf16 v[80:83], v[186:189], v[112:115], v[80:83]
	v_mfma_f32_16x16x32_bf16 v[76:79], v[198:201], v[100:103], v[76:79]
	v_mfma_f32_16x16x32_bf16 v[72:75], v[198:201], v[116:119], v[72:75]
	v_mfma_f32_16x16x32_bf16 v[68:71], v[202:205], v[96:99], v[68:71]
	v_mfma_f32_16x16x32_bf16 v[64:67], v[202:205], v[112:115], v[64:67]
	v_mfma_f32_16x16x32_bf16 v[178:181], v[190:193], v[100:103], v[84:87]
	v_mfma_f32_16x16x32_bf16 v[182:185], v[190:193], v[116:119], v[80:83]
	v_mfma_f32_16x16x32_bf16 v[186:189], v[206:209], v[100:103], v[68:71]
	v_mfma_f32_16x16x32_bf16 v[190:193], v[206:209], v[116:119], v[64:67]
	s_setprio 0
	s_barrier
; #define LDA(dst, b, h) for (int m = 0; m < 4; ++m) for (int k = 0; k < 2; ++k) \
;     dst[m][k] = *reinterpret_cast<const bf16x8*>((char*)SA(b, h) + lds_byte(wr * 64 + m * 16 + fr, k * 32 + fq * 8))
; #define LDB(dst, b, h) for (int n = 0; n < 2; ++n) for (int k = 0; k < 2; ++k) \
;     dst[n][k] = *reinterpret_cast<const bf16x8*>((char*)SB(b, h) + lds_byte(wc * 32 + n * 16 + fr, k * 32 + fq * 8))
; #define MMA(ai, bj, At, Bt) do { __builtin_amdgcn_s_setprio(1); \
;     for (int m = 0; m < 4; ++m) for (int n = 0; n < 2; ++n) for (int k = 0; k < 2; ++k) \
;       acc[ai][bj][m][n] = __builtin_amdgcn_mfma_f32_16x16x32_bf16(At[m][k], Bt[n][k], acc[ai][bj][m][n], 0, 0, 0); \
;     __builtin_amdgcn_s_setprio(0); } while (0)
; #define WAIT_V(n) asm volatile("s_waitcnt vmcnt(" #n ")" ::: "memory")
; #define WAIT_L(n) asm volatile("s_waitcnt lgkmcnt(" #n ")" ::: "memory")
; #define BAR __builtin_amdgcn_s_barrier()
; template <int EPI> ...
;     ...
;     LDA(At, 0, 1); WAIT_V(4); BAR; WAIT_L(0); MMA(1, 0, At, B0); MMA(1, 1, At, B1); BAR; }
;   { LDB(B0, 1, 0); LDA(At, 1, 0); WAIT_V(2); BAR; WAIT_L(0); MMA(0, 0, At, B0); BAR;
	s_nop 1
	ds_read_b128 v[64:67], v153 offset:16384
	ds_read_b128 v[68:71], v153 offset:17408
	ds_read_b128 v[80:83], v152 offset:16384
	ds_read_b128 v[84:87], v152 offset:17408
	ds_read_b128 v[194:197], v151 offset:16384
	ds_read_b128 v[198:201], v151 offset:17408
	ds_read_b128 v[202:205], v150 offset:16384
	ds_read_b128 v[206:209], v150 offset:17408
	s_waitcnt vmcnt(4)
	s_barrier
	s_waitcnt lgkmcnt(0)
	s_setprio 1
	v_mfma_f32_16x16x32_bf16 v[60:63], v[64:67], v[158:161], v[60:63]
	v_mfma_f32_16x16x32_bf16 v[56:59], v[64:67], v[174:177], v[56:59]
	v_mfma_f32_16x16x32_bf16 v[44:47], v[194:197], v[158:161], v[44:47]
	v_mfma_f32_16x16x32_bf16 v[40:43], v[194:197], v[174:177], v[40:43]
	v_mfma_f32_16x16x32_bf16 v[60:63], v[68:71], v[162:165], v[60:63]
	v_mfma_f32_16x16x32_bf16 v[56:59], v[68:71], v[168:171], v[56:59]
	v_mfma_f32_16x16x32_bf16 v[52:55], v[80:83], v[158:161], v[52:55]
	v_mfma_f32_16x16x32_bf16 v[48:51], v[80:83], v[174:177], v[48:51]
	v_mfma_f32_16x16x32_bf16 v[44:47], v[198:201], v[162:165], v[44:47]
	v_mfma_f32_16x16x32_bf16 v[40:43], v[198:201], v[168:171], v[40:43]
	v_mfma_f32_16x16x32_bf16 v[36:39], v[202:205], v[158:161], v[36:39]
	v_mfma_f32_16x16x32_bf16 v[32:35], v[202:205], v[174:177], v[32:35]
	v_mfma_f32_16x16x32_bf16 v[226:229], v[84:87], v[162:165], v[52:55]
	v_mfma_f32_16x16x32_bf16 v[230:233], v[84:87], v[168:171], v[48:51]
	v_mfma_f32_16x16x32_bf16 v[158:161], v[206:209], v[162:165], v[36:39]
	v_mfma_f32_16x16x32_bf16 v[162:165], v[206:209], v[168:171], v[32:35]
	s_setprio 0
	s_setprio 1
	v_mfma_f32_16x16x32_bf16 v[28:31], v[64:67], v[96:99], v[28:31]
	v_mfma_f32_16x16x32_bf16 v[24:27], v[64:67], v[112:115], v[24:27]
	v_mfma_f32_16x16x32_bf16 v[12:15], v[194:197], v[96:99], v[12:15]
	v_mfma_f32_16x16x32_bf16 v[8:11], v[194:197], v[112:115], v[8:11]
	v_mfma_f32_16x16x32_bf16 v[28:31], v[68:71], v[100:103], v[28:31]
	v_mfma_f32_16x16x32_bf16 v[24:27], v[68:71], v[116:119], v[24:27]
	v_mfma_f32_16x16x32_bf16 v[20:23], v[80:83], v[96:99], v[20:23]
	v_mfma_f32_16x16x32_bf16 v[16:19], v[80:83], v[112:115], v[16:19]
	v_mfma_f32_16x16x32_bf16 v[12:15], v[198:201], v[100:103], v[12:15]
	v_mfma_f32_16x16x32_bf16 v[8:11], v[198:201], v[116:119], v[8:11]
	v_mfma_f32_16x16x32_bf16 v[4:7], v[202:205], v[96:99], v[4:7]
	v_mfma_f32_16x16x32_bf16 v[0:3], v[202:205], v[112:115], v[0:3]
	v_mfma_f32_16x16x32_bf16 v[166:169], v[84:87], v[100:103], v[20:23]
	v_mfma_f32_16x16x32_bf16 v[170:173], v[84:87], v[116:119], v[16:19]
	v_mfma_f32_16x16x32_bf16 v[174:177], v[206:209], v[100:103], v[4:7]
	v_mfma_f32_16x16x32_bf16 v[194:197], v[206:209], v[116:119], v[0:3]
	s_setprio 0
	s_barrier
	s_nop 1
	ds_read_b128 v[0:3], v156
	ds_read_b128 v[4:7], v156 offset:1024
	ds_read_b128 v[198:201], v156 offset:2048
	ds_read_b128 v[202:205], v156 offset:3072
	ds_read_b128 v[16:19], v153 offset:32768
	ds_read_b128 v[20:23], v153 offset:33792
	ds_read_b128 v[32:35], v152 offset:32768
	ds_read_b128 v[36:39], v152 offset:33792
	ds_read_b128 v[48:51], v151 offset:32768
	ds_read_b128 v[52:55], v151 offset:33792
	ds_read_b128 v[206:209], v150 offset:32768
	ds_read_b128 v[234:237], v150 offset:33792
	s_waitcnt vmcnt(2)
	s_barrier
	s_waitcnt lgkmcnt(0)
	s_setprio 1
	v_mfma_f32_16x16x32_bf16 v[64:67], v[16:19], v[0:3], v[124:127]
	v_mfma_f32_16x16x32_bf16 v[116:119], v[20:23], v[4:7], v[64:67]
	v_mfma_f32_16x16x32_bf16 v[64:67], v[16:19], v[198:201], v[120:123]
	v_mfma_f32_16x16x32_bf16 v[112:115], v[20:23], v[202:205], v[64:67]
	v_mfma_f32_16x16x32_bf16 v[64:67], v[32:35], v[0:3], v[210:213]
	v_mfma_f32_16x16x32_bf16 v[100:103], v[36:39], v[4:7], v[64:67]
	v_mfma_f32_16x16x32_bf16 v[64:67], v[32:35], v[198:201], v[214:217]
	v_mfma_f32_16x16x32_bf16 v[96:99], v[36:39], v[202:205], v[64:67]
	v_mfma_f32_16x16x32_bf16 v[64:67], v[48:51], v[0:3], v[108:111]
	v_mfma_f32_16x16x32_bf16 v[84:87], v[52:55], v[4:7], v[64:67]
	v_mfma_f32_16x16x32_bf16 v[64:67], v[48:51], v[198:201], v[104:107]
	v_mfma_f32_16x16x32_bf16 v[80:83], v[52:55], v[202:205], v[64:67]
	v_mfma_f32_16x16x32_bf16 v[64:67], v[206:209], v[0:3], v[218:221]
	v_mfma_f32_16x16x32_bf16 v[68:71], v[234:237], v[4:7], v[64:67]
	v_mfma_f32_16x16x32_bf16 v[64:67], v[206:209], v[198:201], v[222:225]
	v_mfma_f32_16x16x32_bf16 v[64:67], v[234:237], v[202:205], v[64:67]
	s_setprio 0
	s_barrier
; #define LDA(dst, b, h) for (int m = 0; m < 4; ++m) for (int k = 0; k < 2; ++k) \
;     dst[m][k] = *reinterpret_cast<const bf16x8*>((char*)SA(b, h) + lds_byte(wr * 64 + m * 16 + fr, k * 32 + fq * 8))
; #define LDB(dst, b, h) for (int n = 0; n < 2; ++n) for (int k = 0; k < 2; ++k) \
;     dst[n][k] = *reinterpret_cast<const bf16x8*>((char*)SB(b, h) + lds_byte(wc * 32 + n * 16 + fr, k * 32 + fq * 8))
; #define MMA(ai, bj, At, Bt) do { __builtin_amdgcn_s_setprio(1); \
;     for (int m = 0; m < 4; ++m) for (int n = 0; n < 2; ++n) for (int k = 0; k < 2; ++k) \
;       acc[ai][bj][m][n] = __builtin_amdgcn_mfma_f32_16x16x32_bf16(At[m][k], Bt[n][k], acc[ai][bj][m][n], 0, 0, 0); \
;     __builtin_amdgcn_s_setprio(0); } while (0)
; #define WAIT_V(n) asm volatile("s_waitcnt vmcnt(" #n ")" ::: "memory")
; #define WAIT_L(n) asm volatile("s_waitcnt lgkmcnt(" #n ")" ::: "memory")
; #define BAR __builtin_amdgcn_s_barrier()
; template <int EPI> ...
;     ...
;     LDB(B1, 1, 1); WAIT_V(0); BAR; WAIT_L(0); MMA(0, 1, At, B1); BAR;
;     LDA(At, 1, 1); BAR; WAIT_L(0); MMA(1, 0, At, B0); MMA(1, 1, At, B1); BAR; }
;   if (wr == 0) BAR;
	ds_read_b128 v[210:213], v154
	ds_read_b128 v[214:217], v154 offset:1024
	ds_read_b128 v[218:221], v154 offset:2048
	ds_read_b128 v[154:157], v154 offset:3072
	s_waitcnt vmcnt(0)
	s_barrier
	s_waitcnt lgkmcnt(0)
	s_setprio 1
	v_mfma_f32_16x16x32_bf16 v[92:95], v[16:19], v[210:213], v[92:95]
	v_mfma_f32_16x16x32_bf16 v[16:19], v[16:19], v[218:221], v[88:91]
	v_mfma_f32_16x16x32_bf16 v[120:123], v[20:23], v[154:157], v[16:19]
	v_mfma_f32_16x16x32_bf16 v[16:19], v[32:35], v[210:213], v[178:181]
	v_mfma_f32_16x16x32_bf16 v[108:111], v[36:39], v[214:217], v[16:19]
	v_mfma_f32_16x16x32_bf16 v[16:19], v[32:35], v[218:221], v[182:185]
	v_mfma_f32_16x16x32_bf16 v[104:107], v[36:39], v[154:157], v[16:19]
	v_mfma_f32_16x16x32_bf16 v[16:19], v[48:51], v[210:213], v[76:79]
	v_mfma_f32_16x16x32_bf16 v[124:127], v[20:23], v[214:217], v[92:95]
	v_mfma_f32_16x16x32_bf16 v[92:95], v[52:55], v[214:217], v[16:19]
	v_mfma_f32_16x16x32_bf16 v[16:19], v[48:51], v[218:221], v[72:75]
	v_mfma_f32_16x16x32_bf16 v[88:91], v[52:55], v[154:157], v[16:19]
	v_mfma_f32_16x16x32_bf16 v[16:19], v[206:209], v[210:213], v[186:189]
	v_mfma_f32_16x16x32_bf16 v[76:79], v[234:237], v[214:217], v[16:19]
	v_mfma_f32_16x16x32_bf16 v[16:19], v[206:209], v[218:221], v[190:193]
	v_mfma_f32_16x16x32_bf16 v[72:75], v[234:237], v[154:157], v[16:19]
	s_setprio 0
	s_barrier
	ds_read_b128 v[178:181], v153 offset:49152
	ds_read_b128 v[182:185], v153 offset:50176
	ds_read_b128 v[186:189], v152 offset:49152
	ds_read_b128 v[190:193], v152 offset:50176
	ds_read_b128 v[206:209], v151 offset:49152
	ds_read_b128 v[222:225], v151 offset:50176
	ds_read_b128 v[234:237], v150 offset:49152
	ds_read_b128 v[150:153], v150 offset:50176
	s_barrier
	s_waitcnt lgkmcnt(0)
	s_setprio 1
	v_mfma_f32_16x16x32_bf16 v[16:19], v[178:181], v[0:3], v[60:63]
	v_mfma_f32_16x16x32_bf16 v[52:55], v[182:185], v[4:7], v[16:19]
	v_mfma_f32_16x16x32_bf16 v[16:19], v[178:181], v[198:201], v[56:59]
	v_mfma_f32_16x16x32_bf16 v[48:51], v[182:185], v[202:205], v[16:19]
	v_mfma_f32_16x16x32_bf16 v[16:19], v[186:189], v[0:3], v[226:229]
	v_mfma_f32_16x16x32_bf16 v[36:39], v[190:193], v[4:7], v[16:19]
	v_mfma_f32_16x16x32_bf16 v[16:19], v[186:189], v[198:201], v[230:233]
	v_mfma_f32_16x16x32_bf16 v[32:35], v[190:193], v[202:205], v[16:19]
	v_mfma_f32_16x16x32_bf16 v[16:19], v[206:209], v[0:3], v[44:47]
	v_mfma_f32_16x16x32_bf16 v[0:3], v[234:237], v[0:3], v[158:161]
	v_mfma_f32_16x16x32_bf16 v[20:23], v[222:225], v[4:7], v[16:19]
	v_mfma_f32_16x16x32_bf16 v[16:19], v[206:209], v[198:201], v[40:43]
	v_mfma_f32_16x16x32_bf16 v[4:7], v[150:153], v[4:7], v[0:3]
	v_mfma_f32_16x16x32_bf16 v[0:3], v[234:237], v[198:201], v[162:165]
	v_mfma_f32_16x16x32_bf16 v[16:19], v[222:225], v[202:205], v[16:19]
	v_mfma_f32_16x16x32_bf16 v[0:3], v[150:153], v[202:205], v[0:3]
	s_setprio 0
	s_setprio 1
	v_mfma_f32_16x16x32_bf16 v[24:27], v[178:181], v[218:221], v[24:27]
	v_mfma_f32_16x16x32_bf16 v[56:59], v[182:185], v[154:157], v[24:27]
	v_mfma_f32_16x16x32_bf16 v[24:27], v[186:189], v[210:213], v[166:169]
	v_mfma_f32_16x16x32_bf16 v[44:47], v[190:193], v[214:217], v[24:27]
	v_mfma_f32_16x16x32_bf16 v[24:27], v[186:189], v[218:221], v[170:173]
	v_mfma_f32_16x16x32_bf16 v[8:11], v[206:209], v[218:221], v[8:11]
	v_mfma_f32_16x16x32_bf16 v[28:31], v[178:181], v[210:213], v[28:31]
	v_mfma_f32_16x16x32_bf16 v[40:43], v[190:193], v[154:157], v[24:27]
	v_mfma_f32_16x16x32_bf16 v[12:15], v[206:209], v[210:213], v[12:15]
	v_mfma_f32_16x16x32_bf16 v[24:27], v[222:225], v[154:157], v[8:11]
	v_mfma_f32_16x16x32_bf16 v[8:11], v[234:237], v[210:213], v[174:177]
	v_mfma_f32_16x16x32_bf16 v[60:63], v[182:185], v[214:217], v[28:31]
	v_mfma_f32_16x16x32_bf16 v[28:31], v[222:225], v[214:217], v[12:15]
	v_mfma_f32_16x16x32_bf16 v[12:15], v[150:153], v[214:217], v[8:11]
	v_mfma_f32_16x16x32_bf16 v[8:11], v[234:237], v[218:221], v[194:197]
	v_mfma_f32_16x16x32_bf16 v[8:11], v[150:153], v[154:157], v[8:11]
	s_setprio 0
	v_cmp_gt_u32_e32 vcc, s67, v144
	s_barrier
	s_and_saveexec_b64 s[48:49], vcc
	s_cbranch_execz .LBB0_785
	s_barrier

; #define STAGE(P, BASE, kt) do { const char* _g = (const char*)(BASE) + (size_t)((kt) * (BK * 2)); \
;     __builtin_amdgcn_global_load_lds((const unsigned*)(_g + (size_t)goff0), (unsigned*)((char*)(P) + tid_ * 16), 16, 0, 0); \
;     __builtin_amdgcn_global_load_lds((const unsigned*)(_g + (size_t)goff1), (unsigned*)((char*)(P) + tid_ * 16 + 8192), 16, 0, 0); } while (0)
; #define STAGEA(P, BASE, kt) do { const char* _g = (const char*)(BASE) + (size_t)((kt) * a_kbytes); \
;     __builtin_amdgcn_global_load_lds((const unsigned*)(_g + (size_t)goffA0), (unsigned*)((char*)(P) + tid_ * 16), 16, 0, 0); \
;     __builtin_amdgcn_global_load_lds((const unsigned*)(_g + (size_t)goffA1), (unsigned*)((char*)(P) + tid_ * 16 + 8192), 16, 0, 0); } while (0)
; #define LDA(dst, b, h) for (int m = 0; m < 4; ++m) for (int k = 0; k < 2; ++k) \
;     dst[m][k] = *reinterpret_cast<const bf16x8*>((char*)SA(b, h) + lds_byte(wr * 64 + m * 16 + fr, k * 32 + fq * 8))
; #define LDB(dst, b, h) for (int n = 0; n < 2; ++n) for (int k = 0; k < 2; ++k) \
;     dst[n][k] = *reinterpret_cast<const bf16x8*>((char*)SB(b, h) + lds_byte(wc * 32 + n * 16 + fr, k * 32 + fq * 8))
; #define MMA(ai, bj, At, Bt) do { __builtin_amdgcn_s_setprio(1); \
;     for (int m = 0; m < 4; ++m) for (int n = 0; n < 2; ++n) for (int k = 0; k < 2; ++k) \
;       acc[ai][bj][m][n] = __builtin_amdgcn_mfma_f32_16x16x32_bf16(At[m][k], Bt[n][k], acc[ai][bj][m][n], 0, 0, 0); \
;     __builtin_amdgcn_s_setprio(0); } while (0)
; #define WAIT_L(n) asm volatile("s_waitcnt lgkmcnt(" #n ")" ::: "memory")
; #define BAR __builtin_amdgcn_s_barrier()
; #define SCHED __builtin_amdgcn_sched_barrier(0)
; template <int EPI> ...
;     ...
;     LDB(B0, 0, 0); SCHED; LDA(At, 0, 0); STAGEA(SA(1, 1), A1, t + 1);
;     WAIT_L(8); BAR; WAIT_L(0); MMA(0, 0, At, B0); BAR; SCHED;
;     LDB(B1, 0, 1); STAGE(SB(0, 0), B0p, t + 2);
;     BAR; WAIT_L(0); MMA(0, 1, At, B1); BAR;
;     LDA(At, 0, 1); STAGEA(SA(0, 0), A0, t + 2);
;     BAR; WAIT_L(0); MMA(1, 0, At, B0); BAR; SCHED;
.LBB0_818:
	ds_read_b128 v[174:177], v171
	ds_read_b128 v[178:181], v171 offset:1024
	ds_read_b128 v[182:185], v171 offset:2048
	ds_read_b128 v[186:189], v171 offset:3072
	v_add_u32_e32 v172, 0xc000, v158
	v_lshl_add_u64 v[238:239], s[58:59], 0, v[140:141]
	v_readfirstlane_b32 s55, v172
	v_add_u32_e32 v173, 0xe000, v158
	v_lshl_add_u64 v[222:223], v[238:239], 0, s[6:7]
	s_mov_b32 m0, s55
	v_lshl_add_u64 v[240:241], s[58:59], 0, v[142:143]
	v_readfirstlane_b32 s55, v173
	ds_read_b128 v[190:193], v153
	ds_read_b128 v[194:197], v153 offset:1024
	ds_read_b128 v[198:201], v152
	ds_read_b128 v[202:205], v152 offset:1024
	ds_read_b128 v[206:209], v151
	ds_read_b128 v[210:213], v151 offset:1024
	ds_read_b128 v[214:217], v150
	ds_read_b128 v[218:221], v150 offset:1024
	global_load_lds_dwordx4 v[222:223], off
	v_lshl_add_u64 v[222:223], v[240:241], 0, s[6:7]
	s_mov_b32 m0, s55
	s_nop 0
	global_load_lds_dwordx4 v[222:223], off
	s_waitcnt lgkmcnt(8)
	s_barrier
	s_waitcnt lgkmcnt(0)
	s_setprio 1
	v_mfma_f32_16x16x32_bf16 v[124:127], v[190:193], v[174:177], v[124:127]
	v_mfma_f32_16x16x32_bf16 v[120:123], v[190:193], v[182:185], v[120:123]
	v_mfma_f32_16x16x32_bf16 v[116:119], v[198:201], v[174:177], v[116:119]
	v_mfma_f32_16x16x32_bf16 v[112:115], v[198:201], v[182:185], v[112:115]
	v_mfma_f32_16x16x32_bf16 v[108:111], v[206:209], v[174:177], v[108:111]
	v_mfma_f32_16x16x32_bf16 v[104:107], v[206:209], v[182:185], v[104:107]
	v_mfma_f32_16x16x32_bf16 v[100:103], v[214:217], v[174:177], v[100:103]
	v_mfma_f32_16x16x32_bf16 v[96:99], v[214:217], v[182:185], v[96:99]
	v_mfma_f32_16x16x32_bf16 v[124:127], v[194:197], v[178:181], v[124:127]
	v_mfma_f32_16x16x32_bf16 v[120:123], v[194:197], v[186:189], v[120:123]
	v_mfma_f32_16x16x32_bf16 v[116:119], v[202:205], v[178:181], v[116:119]
	v_mfma_f32_16x16x32_bf16 v[112:115], v[202:205], v[186:189], v[112:115]
	v_mfma_f32_16x16x32_bf16 v[108:111], v[210:213], v[178:181], v[108:111]
	v_mfma_f32_16x16x32_bf16 v[104:107], v[210:213], v[186:189], v[104:107]
	v_mfma_f32_16x16x32_bf16 v[100:103], v[218:221], v[178:181], v[100:103]
	v_mfma_f32_16x16x32_bf16 v[96:99], v[218:221], v[186:189], v[96:99]
	s_setprio 0
	s_barrier
	v_lshl_add_u64 v[242:243], s[58:59], 0, v[136:137]
	v_readfirstlane_b32 s55, v155
	v_lshl_add_u64 v[244:245], v[242:243], 0, s[8:9]
	s_mov_b32 m0, s55
	ds_read_b128 v[222:225], v168
	ds_read_b128 v[226:229], v168 offset:1024
	ds_read_b128 v[230:233], v168 offset:2048
	ds_read_b128 v[234:237], v168 offset:3072
	global_load_lds_dwordx4 v[244:245], off
	v_lshl_add_u64 v[244:245], s[58:59], 0, v[138:139]
	v_readfirstlane_b32 s55, v156
	v_lshl_add_u64 v[246:247], v[244:245], 0, s[8:9]
	s_mov_b32 m0, s55
	s_nop 0
	global_load_lds_dwordx4 v[246:247], off
	s_barrier
	s_waitcnt lgkmcnt(0)
	s_setprio 1
	v_mfma_f32_16x16x32_bf16 v[92:95], v[190:193], v[222:225], v[92:95]
	v_mfma_f32_16x16x32_bf16 v[88:91], v[190:193], v[230:233], v[88:91]
	v_mfma_f32_16x16x32_bf16 v[84:87], v[198:201], v[222:225], v[84:87]
	v_mfma_f32_16x16x32_bf16 v[80:83], v[198:201], v[230:233], v[80:83]
	v_mfma_f32_16x16x32_bf16 v[76:79], v[206:209], v[222:225], v[76:79]
	v_mfma_f32_16x16x32_bf16 v[72:75], v[206:209], v[230:233], v[72:75]
	v_mfma_f32_16x16x32_bf16 v[68:71], v[214:217], v[222:225], v[68:71]
	v_mfma_f32_16x16x32_bf16 v[64:67], v[214:217], v[230:233], v[64:67]
	v_mfma_f32_16x16x32_bf16 v[92:95], v[194:197], v[226:229], v[92:95]
	v_mfma_f32_16x16x32_bf16 v[88:91], v[194:197], v[234:237], v[88:91]
	v_mfma_f32_16x16x32_bf16 v[84:87], v[202:205], v[226:229], v[84:87]
	v_mfma_f32_16x16x32_bf16 v[80:83], v[202:205], v[234:237], v[80:83]
	v_mfma_f32_16x16x32_bf16 v[76:79], v[210:213], v[226:229], v[76:79]
	v_mfma_f32_16x16x32_bf16 v[72:75], v[210:213], v[234:237], v[72:75]
	v_mfma_f32_16x16x32_bf16 v[68:71], v[218:221], v[226:229], v[68:71]
	v_mfma_f32_16x16x32_bf16 v[64:67], v[218:221], v[234:237], v[64:67]
	s_setprio 0
	v_readfirstlane_b32 s55, v158
	v_lshl_add_u64 v[246:247], v[238:239], 0, s[10:11]
	s_mov_b32 m0, s55
	v_readfirstlane_b32 s55, v159
	s_barrier
	ds_read_b128 v[190:193], v153 offset:16384
	ds_read_b128 v[194:197], v153 offset:17408
	ds_read_b128 v[198:201], v152 offset:16384
	ds_read_b128 v[202:205], v152 offset:17408
	ds_read_b128 v[206:209], v151 offset:16384
	ds_read_b128 v[210:213], v151 offset:17408
	ds_read_b128 v[214:217], v150 offset:16384
	ds_read_b128 v[218:221], v150 offset:17408
	global_load_lds_dwordx4 v[246:247], off
	v_lshl_add_u64 v[246:247], v[240:241], 0, s[10:11]
	s_mov_b32 m0, s55
	s_nop 0
	global_load_lds_dwordx4 v[246:247], off
	s_barrier
	s_waitcnt lgkmcnt(0)
	s_setprio 1
	v_mfma_f32_16x16x32_bf16 v[60:63], v[190:193], v[174:177], v[60:63]
	v_mfma_f32_16x16x32_bf16 v[56:59], v[190:193], v[182:185], v[56:59]
	v_mfma_f32_16x16x32_bf16 v[52:55], v[198:201], v[174:177], v[52:55]
	v_mfma_f32_16x16x32_bf16 v[48:51], v[198:201], v[182:185], v[48:51]
	v_mfma_f32_16x16x32_bf16 v[44:47], v[206:209], v[174:177], v[44:47]
	v_mfma_f32_16x16x32_bf16 v[40:43], v[206:209], v[182:185], v[40:43]
	v_mfma_f32_16x16x32_bf16 v[36:39], v[214:217], v[174:177], v[36:39]
	v_mfma_f32_16x16x32_bf16 v[32:35], v[214:217], v[182:185], v[32:35]
	v_mfma_f32_16x16x32_bf16 v[60:63], v[194:197], v[178:181], v[60:63]
	v_mfma_f32_16x16x32_bf16 v[56:59], v[194:197], v[186:189], v[56:59]
	v_mfma_f32_16x16x32_bf16 v[52:55], v[202:205], v[178:181], v[52:55]
	v_mfma_f32_16x16x32_bf16 v[48:51], v[202:205], v[186:189], v[48:51]
	v_mfma_f32_16x16x32_bf16 v[44:47], v[210:213], v[178:181], v[44:47]
	v_mfma_f32_16x16x32_bf16 v[40:43], v[210:213], v[186:189], v[40:43]
	v_mfma_f32_16x16x32_bf16 v[36:39], v[218:221], v[178:181], v[36:39]
	v_mfma_f32_16x16x32_bf16 v[32:35], v[218:221], v[186:189], v[32:35]
	s_setprio 0
	s_barrier
; #define STAGE(P, BASE, kt) do { const char* _g = (const char*)(BASE) + (size_t)((kt) * (BK * 2)); \
;     __builtin_amdgcn_global_load_lds((const unsigned*)(_g + (size_t)goff0), (unsigned*)((char*)(P) + tid_ * 16), 16, 0, 0); \
;     __builtin_amdgcn_global_load_lds((const unsigned*)(_g + (size_t)goff1), (unsigned*)((char*)(P) + tid_ * 16 + 8192), 16, 0, 0); } while (0)
; #define STAGEA(P, BASE, kt) do { const char* _g = (const char*)(BASE) + (size_t)((kt) * a_kbytes); \
;     __builtin_amdgcn_global_load_lds((const unsigned*)(_g + (size_t)goffA0), (unsigned*)((char*)(P) + tid_ * 16), 16, 0, 0); \
;     __builtin_amdgcn_global_load_lds((const unsigned*)(_g + (size_t)goffA1), (unsigned*)((char*)(P) + tid_ * 16 + 8192), 16, 0, 0); } while (0)
; #define LDA(dst, b, h) for (int m = 0; m < 4; ++m) for (int k = 0; k < 2; ++k) \
;     dst[m][k] = *reinterpret_cast<const bf16x8*>((char*)SA(b, h) + lds_byte(wr * 64 + m * 16 + fr, k * 32 + fq * 8))
; #define LDB(dst, b, h) for (int n = 0; n < 2; ++n) for (int k = 0; k < 2; ++k) \
;     dst[n][k] = *reinterpret_cast<const bf16x8*>((char*)SB(b, h) + lds_byte(wc * 32 + n * 16 + fr, k * 32 + fq * 8))
; #define MMA(ai, bj, At, Bt) do { __builtin_amdgcn_s_setprio(1); \
;     for (int m = 0; m < 4; ++m) for (int n = 0; n < 2; ++n) for (int k = 0; k < 2; ++k) \
;       acc[ai][bj][m][n] = __builtin_amdgcn_mfma_f32_16x16x32_bf16(At[m][k], Bt[n][k], acc[ai][bj][m][n], 0, 0, 0); \
;     __builtin_amdgcn_s_setprio(0); } while (0)
; #define WAIT_V(n) asm volatile("s_waitcnt vmcnt(" #n ")" ::: "memory")
; #define WAIT_L(n) asm volatile("s_waitcnt lgkmcnt(" #n ")" ::: "memory")
; #define BAR __builtin_amdgcn_s_barrier()
; #define SCHED __builtin_amdgcn_sched_barrier(0)
; template <int EPI> ...
;     ...
;     STAGE(SB(0, 1), B1p, t + 2);
;     WAIT_V(6); BAR; MMA(1, 1, At, B1); BAR;
;     LDB(B0, 1, 0); SCHED; LDA(At, 1, 0); STAGEA(SA(0, 1), A1, t + 2);
;     WAIT_L(8); BAR; WAIT_L(0); MMA(0, 0, At, B0); BAR; SCHED;
;     LDB(B1, 1, 1); STAGE(SB(1, 0), B0p, t + 3);
;     BAR; WAIT_L(0); MMA(0, 1, At, B1); BAR;
;     LDA(At, 1, 1); STAGEA(SA(1, 0), A0, t + 3);
	v_readfirstlane_b32 s55, v160
	v_lshl_add_u64 v[174:175], v[242:243], 0, s[12:13]
	s_mov_b32 m0, s55
	v_readfirstlane_b32 s55, v161
	global_load_lds_dwordx4 v[174:175], off
	v_lshl_add_u64 v[174:175], v[244:245], 0, s[12:13]
	s_mov_b32 m0, s55
	s_nop 0
	global_load_lds_dwordx4 v[174:175], off
	s_waitcnt vmcnt(6)
	s_barrier
	s_setprio 1
	v_mfma_f32_16x16x32_bf16 v[28:31], v[190:193], v[222:225], v[28:31]
	v_mfma_f32_16x16x32_bf16 v[24:27], v[190:193], v[230:233], v[24:27]
	v_mfma_f32_16x16x32_bf16 v[20:23], v[198:201], v[222:225], v[20:23]
	v_mfma_f32_16x16x32_bf16 v[16:19], v[198:201], v[230:233], v[16:19]
	v_mfma_f32_16x16x32_bf16 v[12:15], v[206:209], v[222:225], v[12:15]
	v_mfma_f32_16x16x32_bf16 v[8:11], v[206:209], v[230:233], v[8:11]
	v_mfma_f32_16x16x32_bf16 v[4:7], v[214:217], v[222:225], v[4:7]
	v_mfma_f32_16x16x32_bf16 v[0:3], v[214:217], v[230:233], v[0:3]
	v_mfma_f32_16x16x32_bf16 v[28:31], v[194:197], v[226:229], v[28:31]
	v_mfma_f32_16x16x32_bf16 v[24:27], v[194:197], v[234:237], v[24:27]
	v_mfma_f32_16x16x32_bf16 v[20:23], v[202:205], v[226:229], v[20:23]
	v_mfma_f32_16x16x32_bf16 v[16:19], v[202:205], v[234:237], v[16:19]
	v_mfma_f32_16x16x32_bf16 v[12:15], v[210:213], v[226:229], v[12:15]
	v_mfma_f32_16x16x32_bf16 v[8:11], v[210:213], v[234:237], v[8:11]
	v_mfma_f32_16x16x32_bf16 v[4:7], v[218:221], v[226:229], v[4:7]
	v_mfma_f32_16x16x32_bf16 v[0:3], v[218:221], v[234:237], v[0:3]
	s_setprio 0
	s_barrier
	ds_read_b128 v[174:177], v157
	ds_read_b128 v[178:181], v157 offset:1024
	ds_read_b128 v[182:185], v157 offset:2048
	ds_read_b128 v[186:189], v157 offset:3072
	v_readfirstlane_b32 s55, v162
	v_lshl_add_u64 v[222:223], v[238:239], 0, s[14:15]
	s_mov_b32 m0, s55
	v_readfirstlane_b32 s55, v163
	ds_read_b128 v[190:193], v153 offset:32768
	ds_read_b128 v[194:197], v153 offset:33792
	ds_read_b128 v[198:201], v152 offset:32768
	ds_read_b128 v[202:205], v152 offset:33792
	ds_read_b128 v[206:209], v151 offset:32768
	ds_read_b128 v[210:213], v151 offset:33792
	ds_read_b128 v[214:217], v150 offset:32768
	ds_read_b128 v[218:221], v150 offset:33792
	global_load_lds_dwordx4 v[222:223], off
	v_lshl_add_u64 v[222:223], v[240:241], 0, s[14:15]
	s_mov_b32 m0, s55
	s_nop 0
	global_load_lds_dwordx4 v[222:223], off
	s_waitcnt lgkmcnt(8)
	s_barrier
	s_waitcnt lgkmcnt(0)
	s_setprio 1
	v_mfma_f32_16x16x32_bf16 v[124:127], v[190:193], v[174:177], v[124:127]
	v_mfma_f32_16x16x32_bf16 v[120:123], v[190:193], v[182:185], v[120:123]
	v_mfma_f32_16x16x32_bf16 v[116:119], v[198:201], v[174:177], v[116:119]
	v_mfma_f32_16x16x32_bf16 v[112:115], v[198:201], v[182:185], v[112:115]
	v_mfma_f32_16x16x32_bf16 v[108:111], v[206:209], v[174:177], v[108:111]
	v_mfma_f32_16x16x32_bf16 v[104:107], v[206:209], v[182:185], v[104:107]
	v_mfma_f32_16x16x32_bf16 v[100:103], v[214:217], v[174:177], v[100:103]
	v_mfma_f32_16x16x32_bf16 v[96:99], v[214:217], v[182:185], v[96:99]
	v_mfma_f32_16x16x32_bf16 v[124:127], v[194:197], v[178:181], v[124:127]
	v_mfma_f32_16x16x32_bf16 v[120:123], v[194:197], v[186:189], v[120:123]
	v_mfma_f32_16x16x32_bf16 v[116:119], v[202:205], v[178:181], v[116:119]
	v_mfma_f32_16x16x32_bf16 v[112:115], v[202:205], v[186:189], v[112:115]
	v_mfma_f32_16x16x32_bf16 v[108:111], v[210:213], v[178:181], v[108:111]
	v_mfma_f32_16x16x32_bf16 v[104:107], v[210:213], v[186:189], v[104:107]
	v_mfma_f32_16x16x32_bf16 v[100:103], v[218:221], v[178:181], v[100:103]
	v_mfma_f32_16x16x32_bf16 v[96:99], v[218:221], v[186:189], v[96:99]
	s_setprio 0
	s_barrier
	v_readfirstlane_b32 s55, v164
	v_lshl_add_u64 v[246:247], v[242:243], 0, s[24:25]
	s_mov_b32 m0, s55
	v_readfirstlane_b32 s55, v165
	ds_read_b128 v[222:225], v154
	ds_read_b128 v[226:229], v154 offset:1024
	ds_read_b128 v[230:233], v154 offset:2048
	ds_read_b128 v[234:237], v154 offset:3072
	global_load_lds_dwordx4 v[246:247], off
	v_lshl_add_u64 v[246:247], v[244:245], 0, s[24:25]
	s_mov_b32 m0, s55
	s_nop 0
	global_load_lds_dwordx4 v[246:247], off
	s_barrier
	s_waitcnt lgkmcnt(0)
	s_setprio 1
	v_mfma_f32_16x16x32_bf16 v[92:95], v[190:193], v[222:225], v[92:95]
	v_mfma_f32_16x16x32_bf16 v[88:91], v[190:193], v[230:233], v[88:91]
	v_mfma_f32_16x16x32_bf16 v[84:87], v[198:201], v[222:225], v[84:87]
	v_mfma_f32_16x16x32_bf16 v[80:83], v[198:201], v[230:233], v[80:83]
	v_mfma_f32_16x16x32_bf16 v[76:79], v[206:209], v[222:225], v[76:79]
	v_mfma_f32_16x16x32_bf16 v[72:75], v[206:209], v[230:233], v[72:75]
	v_mfma_f32_16x16x32_bf16 v[68:71], v[214:217], v[222:225], v[68:71]
	v_mfma_f32_16x16x32_bf16 v[64:67], v[214:217], v[230:233], v[64:67]
	v_mfma_f32_16x16x32_bf16 v[92:95], v[194:197], v[226:229], v[92:95]
	v_mfma_f32_16x16x32_bf16 v[88:91], v[194:197], v[234:237], v[88:91]
	v_mfma_f32_16x16x32_bf16 v[84:87], v[202:205], v[226:229], v[84:87]
	v_mfma_f32_16x16x32_bf16 v[80:83], v[202:205], v[234:237], v[80:83]
	v_mfma_f32_16x16x32_bf16 v[76:79], v[210:213], v[226:229], v[76:79]
	v_mfma_f32_16x16x32_bf16 v[72:75], v[210:213], v[234:237], v[72:75]
	v_mfma_f32_16x16x32_bf16 v[68:71], v[218:221], v[226:229], v[68:71]
	v_mfma_f32_16x16x32_bf16 v[64:67], v[218:221], v[234:237], v[64:67]
	s_setprio 0
	v_readfirstlane_b32 s55, v166
	v_lshl_add_u64 v[238:239], v[238:239], 0, s[42:43]
	s_mov_b32 m0, s55
	v_readfirstlane_b32 s55, v167
	s_barrier
	ds_read_b128 v[190:193], v153 offset:49152
	ds_read_b128 v[194:197], v153 offset:50176
	ds_read_b128 v[198:201], v152 offset:49152
	ds_read_b128 v[202:205], v152 offset:50176
	ds_read_b128 v[206:209], v151 offset:49152
	ds_read_b128 v[210:213], v151 offset:50176
	ds_read_b128 v[214:217], v150 offset:49152
	ds_read_b128 v[218:221], v150 offset:50176
	global_load_lds_dwordx4 v[238:239], off
	v_lshl_add_u64 v[238:239], v[240:241], 0, s[42:43]
	s_mov_b32 m0, s55
	s_nop 0
	global_load_lds_dwordx4 v[238:239], off
	s_barrier
; #define STAGE(P, BASE, kt) do { const char* _g = (const char*)(BASE) + (size_t)((kt) * (BK * 2)); \
;     __builtin_amdgcn_global_load_lds((const unsigned*)(_g + (size_t)goff0), (unsigned*)((char*)(P) + tid_ * 16), 16, 0, 0); \
;     __builtin_amdgcn_global_load_lds((const unsigned*)(_g + (size_t)goff1), (unsigned*)((char*)(P) + tid_ * 16 + 8192), 16, 0, 0); } while (0)
; #define STAGEA(P, BASE, kt) do { const char* _g = (const char*)(BASE) + (size_t)((kt) * a_kbytes); \
;     __builtin_amdgcn_global_load_lds((const unsigned*)(_g + (size_t)goffA0), (unsigned*)((char*)(P) + tid_ * 16), 16, 0, 0); \
;     __builtin_amdgcn_global_load_lds((const unsigned*)(_g + (size_t)goffA1), (unsigned*)((char*)(P) + tid_ * 16 + 8192), 16, 0, 0); } while (0)
; #define LDA(dst, b, h) for (int m = 0; m < 4; ++m) for (int k = 0; k < 2; ++k) \
;     dst[m][k] = *reinterpret_cast<const bf16x8*>((char*)SA(b, h) + lds_byte(wr * 64 + m * 16 + fr, k * 32 + fq * 8))
; #define LDB(dst, b, h) for (int n = 0; n < 2; ++n) for (int k = 0; k < 2; ++k) \
;     dst[n][k] = *reinterpret_cast<const bf16x8*>((char*)SB(b, h) + lds_byte(wc * 32 + n * 16 + fr, k * 32 + fq * 8))
; #define MMA(ai, bj, At, Bt) do { __builtin_amdgcn_s_setprio(1); \
;     for (int m = 0; m < 4; ++m) for (int n = 0; n < 2; ++n) for (int k = 0; k < 2; ++k) \
;       acc[ai][bj][m][n] = __builtin_amdgcn_mfma_f32_16x16x32_bf16(At[m][k], Bt[n][k], acc[ai][bj][m][n], 0, 0, 0); \
;     __builtin_amdgcn_s_setprio(0); } while (0)
; #define WAIT_V(n) asm volatile("s_waitcnt vmcnt(" #n ")" ::: "memory")
; #define WAIT_L(n) asm volatile("s_waitcnt lgkmcnt(" #n ")" ::: "memory")
; #define BAR __builtin_amdgcn_s_barrier()
; #define SCHED __builtin_amdgcn_sched_barrier(0)
; template <int EPI> ...
;     ...
;     BAR; WAIT_L(0); MMA(1, 0, At, B0); BAR; SCHED;
;     STAGE(SB(1, 1), B1p, t + 3);
;     WAIT_V(6); BAR; MMA(1, 1, At, B1); BAR;
;   }
;   { LDB(B0, 0, 0); LDA(At, 0, 0); STAGEA(SA(1, 1), A1, nt - 1);
;     BAR; WAIT_L(0); MMA(0, 0, At, B0); BAR;
;     LDB(B1, 0, 1); BAR; WAIT_L(0); MMA(0, 1, At, B1); BAR;
	s_waitcnt lgkmcnt(0)
	s_setprio 1
	v_mfma_f32_16x16x32_bf16 v[60:63], v[190:193], v[174:177], v[60:63]
	v_mfma_f32_16x16x32_bf16 v[56:59], v[190:193], v[182:185], v[56:59]
	v_mfma_f32_16x16x32_bf16 v[52:55], v[198:201], v[174:177], v[52:55]
	v_mfma_f32_16x16x32_bf16 v[48:51], v[198:201], v[182:185], v[48:51]
	v_mfma_f32_16x16x32_bf16 v[44:47], v[206:209], v[174:177], v[44:47]
	v_mfma_f32_16x16x32_bf16 v[40:43], v[206:209], v[182:185], v[40:43]
	v_mfma_f32_16x16x32_bf16 v[36:39], v[214:217], v[174:177], v[36:39]
	v_mfma_f32_16x16x32_bf16 v[32:35], v[214:217], v[182:185], v[32:35]
	v_mfma_f32_16x16x32_bf16 v[60:63], v[194:197], v[178:181], v[60:63]
	v_mfma_f32_16x16x32_bf16 v[56:59], v[194:197], v[186:189], v[56:59]
	v_mfma_f32_16x16x32_bf16 v[52:55], v[202:205], v[178:181], v[52:55]
	v_mfma_f32_16x16x32_bf16 v[48:51], v[202:205], v[186:189], v[48:51]
	v_mfma_f32_16x16x32_bf16 v[44:47], v[210:213], v[178:181], v[44:47]
	v_mfma_f32_16x16x32_bf16 v[40:43], v[210:213], v[186:189], v[40:43]
	v_mfma_f32_16x16x32_bf16 v[36:39], v[218:221], v[178:181], v[36:39]
	v_mfma_f32_16x16x32_bf16 v[32:35], v[218:221], v[186:189], v[32:35]
	s_setprio 0
	s_barrier
	v_readfirstlane_b32 s55, v169
	v_lshl_add_u64 v[174:175], v[242:243], 0, s[46:47]
	s_mov_b32 m0, s55
	v_readfirstlane_b32 s55, v170
	global_load_lds_dwordx4 v[174:175], off
	v_lshl_add_u64 v[174:175], v[244:245], 0, s[46:47]
	s_mov_b32 m0, s55
	s_nop 0
	global_load_lds_dwordx4 v[174:175], off
	s_waitcnt vmcnt(6)
	s_barrier
	s_setprio 1
	v_mfma_f32_16x16x32_bf16 v[28:31], v[190:193], v[222:225], v[28:31]
	v_mfma_f32_16x16x32_bf16 v[24:27], v[190:193], v[230:233], v[24:27]
	v_mfma_f32_16x16x32_bf16 v[20:23], v[198:201], v[222:225], v[20:23]
	v_mfma_f32_16x16x32_bf16 v[16:19], v[198:201], v[230:233], v[16:19]
	v_mfma_f32_16x16x32_bf16 v[12:15], v[206:209], v[222:225], v[12:15]
	v_mfma_f32_16x16x32_bf16 v[8:11], v[206:209], v[230:233], v[8:11]
	v_mfma_f32_16x16x32_bf16 v[4:7], v[214:217], v[222:225], v[4:7]
	v_mfma_f32_16x16x32_bf16 v[0:3], v[214:217], v[230:233], v[0:3]
	v_mfma_f32_16x16x32_bf16 v[28:31], v[194:197], v[226:229], v[28:31]
	v_mfma_f32_16x16x32_bf16 v[24:27], v[194:197], v[234:237], v[24:27]
	v_mfma_f32_16x16x32_bf16 v[20:23], v[202:205], v[226:229], v[20:23]
	v_mfma_f32_16x16x32_bf16 v[16:19], v[202:205], v[234:237], v[16:19]
	v_mfma_f32_16x16x32_bf16 v[12:15], v[210:213], v[226:229], v[12:15]
	v_mfma_f32_16x16x32_bf16 v[8:11], v[210:213], v[234:237], v[8:11]
	v_mfma_f32_16x16x32_bf16 v[4:7], v[218:221], v[226:229], v[4:7]
	v_mfma_f32_16x16x32_bf16 v[0:3], v[218:221], v[234:237], v[0:3]
	s_setprio 0
	s_add_i32 s53, s53, 2
	s_add_u32 s58, s58, 0x100
	s_addc_u32 s59, s59, 0
	s_cmp_lt_u32 s53, 28
	s_barrier
	s_cbranch_scc1 .LBB0_818
	s_add_u32 s56, s56, 0x80f80
	s_addc_u32 s57, s57, 0
	v_readfirstlane_b32 s53, v172
	v_lshl_add_u64 v[166:167], s[56:57], 0, v[130:131]
	s_mov_b32 m0, s53
	v_readfirstlane_b32 s53, v173
	ds_read_b128 v[136:139], v171
	ds_read_b128 v[140:143], v171 offset:1024
	ds_read_b128 v[158:161], v171 offset:2048
	ds_read_b128 v[162:165], v171 offset:3072
	ds_read_b128 v[174:177], v153
	ds_read_b128 v[178:181], v153 offset:1024
	ds_read_b128 v[182:185], v152
	ds_read_b128 v[186:189], v152 offset:1024
	ds_read_b128 v[190:193], v151
	ds_read_b128 v[194:197], v151 offset:1024
	ds_read_b128 v[198:201], v150
	ds_read_b128 v[202:205], v150 offset:1024
	global_load_lds_dwordx4 v[166:167], off
	v_lshl_add_u64 v[166:167], s[56:57], 0, v[128:129]
	s_mov_b32 m0, s53
	s_nop 0
	global_load_lds_dwordx4 v[166:167], off
	s_barrier
	s_waitcnt lgkmcnt(0)
	s_setprio 1
	v_mfma_f32_16x16x32_bf16 v[124:127], v[174:177], v[136:139], v[124:127]
	v_mfma_f32_16x16x32_bf16 v[120:123], v[174:177], v[158:161], v[120:123]
	v_mfma_f32_16x16x32_bf16 v[108:111], v[190:193], v[136:139], v[108:111]
	v_mfma_f32_16x16x32_bf16 v[104:107], v[190:193], v[158:161], v[104:107]
	v_mfma_f32_16x16x32_bf16 v[124:127], v[178:181], v[140:143], v[124:127]
	v_mfma_f32_16x16x32_bf16 v[120:123], v[178:181], v[162:165], v[120:123]
	v_mfma_f32_16x16x32_bf16 v[116:119], v[182:185], v[136:139], v[116:119]
	v_mfma_f32_16x16x32_bf16 v[112:115], v[182:185], v[158:161], v[112:115]
	v_mfma_f32_16x16x32_bf16 v[108:111], v[194:197], v[140:143], v[108:111]
	v_mfma_f32_16x16x32_bf16 v[104:107], v[194:197], v[162:165], v[104:107]
	v_mfma_f32_16x16x32_bf16 v[100:103], v[198:201], v[136:139], v[100:103]
	v_mfma_f32_16x16x32_bf16 v[96:99], v[198:201], v[158:161], v[96:99]
	v_mfma_f32_16x16x32_bf16 v[170:173], v[186:189], v[140:143], v[116:119]
	v_mfma_f32_16x16x32_bf16 v[206:209], v[186:189], v[162:165], v[112:115]
	v_mfma_f32_16x16x32_bf16 v[210:213], v[202:205], v[140:143], v[100:103]
	v_mfma_f32_16x16x32_bf16 v[214:217], v[202:205], v[162:165], v[96:99]
	s_setprio 0
	s_barrier
	s_nop 1
	ds_read_b128 v[96:99], v168
	ds_read_b128 v[100:103], v168 offset:1024
	ds_read_b128 v[112:115], v168 offset:2048
	ds_read_b128 v[116:119], v168 offset:3072
	s_barrier
	s_waitcnt lgkmcnt(0)
	s_setprio 1
	v_mfma_f32_16x16x32_bf16 v[92:95], v[174:177], v[96:99], v[92:95]
	v_mfma_f32_16x16x32_bf16 v[88:91], v[174:177], v[112:115], v[88:91]
	v_mfma_f32_16x16x32_bf16 v[76:79], v[190:193], v[96:99], v[76:79]
	v_mfma_f32_16x16x32_bf16 v[72:75], v[190:193], v[112:115], v[72:75]
	v_mfma_f32_16x16x32_bf16 v[92:95], v[178:181], v[100:103], v[92:95]
	v_mfma_f32_16x16x32_bf16 v[88:91], v[178:181], v[116:119], v[88:91]
	v_mfma_f32_16x16x32_bf16 v[84:87], v[182:185], v[96:99], v[84:87]
	v_mfma_f32_16x16x32_bf16 v[80:83], v[182:185], v[112:115], v[80:83]
	v_mfma_f32_16x16x32_bf16 v[76:79], v[194:197], v[100:103], v[76:79]
	v_mfma_f32_16x16x32_bf16 v[72:75], v[194:197], v[116:119], v[72:75]
	v_mfma_f32_16x16x32_bf16 v[68:71], v[198:201], v[96:99], v[68:71]
	v_mfma_f32_16x16x32_bf16 v[64:67], v[198:201], v[112:115], v[64:67]
	v_mfma_f32_16x16x32_bf16 v[166:169], v[186:189], v[100:103], v[84:87]
	v_mfma_f32_16x16x32_bf16 v[174:177], v[186:189], v[116:119], v[80:83]
	v_mfma_f32_16x16x32_bf16 v[178:181], v[202:205], v[100:103], v[68:71]
	v_mfma_f32_16x16x32_bf16 v[182:185], v[202:205], v[116:119], v[64:67]
	s_setprio 0
	s_barrier
; #define LDA(dst, b, h) for (int m = 0; m < 4; ++m) for (int k = 0; k < 2; ++k) \
;     dst[m][k] = *reinterpret_cast<const bf16x8*>((char*)SA(b, h) + lds_byte(wr * 64 + m * 16 + fr, k * 32 + fq * 8))
; #define LDB(dst, b, h) for (int n = 0; n < 2; ++n) for (int k = 0; k < 2; ++k) \
;     dst[n][k] = *reinterpret_cast<const bf16x8*>((char*)SB(b, h) + lds_byte(wc * 32 + n * 16 + fr, k * 32 + fq * 8))
; #define MMA(ai, bj, At, Bt) do { __builtin_amdgcn_s_setprio(1); \
;     for (int m = 0; m < 4; ++m) for (int n = 0; n < 2; ++n) for (int k = 0; k < 2; ++k) \
;       acc[ai][bj][m][n] = __builtin_amdgcn_mfma_f32_16x16x32_bf16(At[m][k], Bt[n][k], acc[ai][bj][m][n], 0, 0, 0); \
;     __builtin_amdgcn_s_setprio(0); } while (0)
; #define WAIT_V(n) asm volatile("s_waitcnt vmcnt(" #n ")" ::: "memory")
; #define WAIT_L(n) asm volatile("s_waitcnt lgkmcnt(" #n ")" ::: "memory")
; #define BAR __builtin_amdgcn_s_barrier()
; template <int EPI> ...
;     ...
;     LDA(At, 0, 1); WAIT_V(4); BAR; WAIT_L(0); MMA(1, 0, At, B0); MMA(1, 1, At, B1); BAR; }
;   { LDB(B0, 1, 0); LDA(At, 1, 0); WAIT_V(2); BAR; WAIT_L(0); MMA(0, 0, At, B0); BAR;
	s_nop 1
	ds_read_b128 v[64:67], v153 offset:16384
	ds_read_b128 v[68:71], v153 offset:17408
	ds_read_b128 v[80:83], v152 offset:16384
	ds_read_b128 v[84:87], v152 offset:17408
	ds_read_b128 v[186:189], v151 offset:16384
	ds_read_b128 v[190:193], v151 offset:17408
	ds_read_b128 v[194:197], v150 offset:16384
	ds_read_b128 v[198:201], v150 offset:17408
	s_waitcnt vmcnt(4)
	s_barrier
	s_waitcnt lgkmcnt(0)
	s_setprio 1
	v_mfma_f32_16x16x32_bf16 v[60:63], v[64:67], v[136:139], v[60:63]
	v_mfma_f32_16x16x32_bf16 v[56:59], v[64:67], v[158:161], v[56:59]
	v_mfma_f32_16x16x32_bf16 v[44:47], v[186:189], v[136:139], v[44:47]
	v_mfma_f32_16x16x32_bf16 v[40:43], v[186:189], v[158:161], v[40:43]
	v_mfma_f32_16x16x32_bf16 v[60:63], v[68:71], v[140:143], v[60:63]
	v_mfma_f32_16x16x32_bf16 v[56:59], v[68:71], v[162:165], v[56:59]
	v_mfma_f32_16x16x32_bf16 v[52:55], v[80:83], v[136:139], v[52:55]
	v_mfma_f32_16x16x32_bf16 v[48:51], v[80:83], v[158:161], v[48:51]
	v_mfma_f32_16x16x32_bf16 v[44:47], v[190:193], v[140:143], v[44:47]
	v_mfma_f32_16x16x32_bf16 v[40:43], v[190:193], v[162:165], v[40:43]
	v_mfma_f32_16x16x32_bf16 v[36:39], v[194:197], v[136:139], v[36:39]
	v_mfma_f32_16x16x32_bf16 v[32:35], v[194:197], v[158:161], v[32:35]
	v_mfma_f32_16x16x32_bf16 v[202:205], v[84:87], v[140:143], v[52:55]
	v_mfma_f32_16x16x32_bf16 v[218:221], v[84:87], v[162:165], v[48:51]
	v_mfma_f32_16x16x32_bf16 v[136:139], v[198:201], v[140:143], v[36:39]
	v_mfma_f32_16x16x32_bf16 v[140:143], v[198:201], v[162:165], v[32:35]
	s_setprio 0
	s_setprio 1
	v_mfma_f32_16x16x32_bf16 v[28:31], v[64:67], v[96:99], v[28:31]
	v_mfma_f32_16x16x32_bf16 v[24:27], v[64:67], v[112:115], v[24:27]
	v_mfma_f32_16x16x32_bf16 v[12:15], v[186:189], v[96:99], v[12:15]
	v_mfma_f32_16x16x32_bf16 v[8:11], v[186:189], v[112:115], v[8:11]
	v_mfma_f32_16x16x32_bf16 v[28:31], v[68:71], v[100:103], v[28:31]
	v_mfma_f32_16x16x32_bf16 v[24:27], v[68:71], v[116:119], v[24:27]
	v_mfma_f32_16x16x32_bf16 v[20:23], v[80:83], v[96:99], v[20:23]
	v_mfma_f32_16x16x32_bf16 v[16:19], v[80:83], v[112:115], v[16:19]
	v_mfma_f32_16x16x32_bf16 v[12:15], v[190:193], v[100:103], v[12:15]
	v_mfma_f32_16x16x32_bf16 v[8:11], v[190:193], v[116:119], v[8:11]
	v_mfma_f32_16x16x32_bf16 v[4:7], v[194:197], v[96:99], v[4:7]
	v_mfma_f32_16x16x32_bf16 v[0:3], v[194:197], v[112:115], v[0:3]
	v_mfma_f32_16x16x32_bf16 v[158:161], v[84:87], v[100:103], v[20:23]
	v_mfma_f32_16x16x32_bf16 v[162:165], v[84:87], v[116:119], v[16:19]
	v_mfma_f32_16x16x32_bf16 v[186:189], v[198:201], v[100:103], v[4:7]
	v_mfma_f32_16x16x32_bf16 v[190:193], v[198:201], v[116:119], v[0:3]
	s_setprio 0
	s_barrier
	s_nop 1
	ds_read_b128 v[0:3], v157
	ds_read_b128 v[4:7], v157 offset:1024
	ds_read_b128 v[194:197], v157 offset:2048
	ds_read_b128 v[198:201], v157 offset:3072
	ds_read_b128 v[16:19], v153 offset:32768
	ds_read_b128 v[20:23], v153 offset:33792
	ds_read_b128 v[32:35], v152 offset:32768
	ds_read_b128 v[36:39], v152 offset:33792
	ds_read_b128 v[48:51], v151 offset:32768
	ds_read_b128 v[52:55], v151 offset:33792
	ds_read_b128 v[222:225], v150 offset:32768
	ds_read_b128 v[226:229], v150 offset:33792
	s_waitcnt vmcnt(2)
	s_barrier
	s_waitcnt lgkmcnt(0)
	s_setprio 1
	v_mfma_f32_16x16x32_bf16 v[64:67], v[16:19], v[0:3], v[124:127]
	v_mfma_f32_16x16x32_bf16 v[116:119], v[20:23], v[4:7], v[64:67]
	v_mfma_f32_16x16x32_bf16 v[64:67], v[16:19], v[194:197], v[120:123]
	v_mfma_f32_16x16x32_bf16 v[112:115], v[20:23], v[198:201], v[64:67]
	v_mfma_f32_16x16x32_bf16 v[64:67], v[32:35], v[0:3], v[170:173]
	v_mfma_f32_16x16x32_bf16 v[100:103], v[36:39], v[4:7], v[64:67]
	v_mfma_f32_16x16x32_bf16 v[64:67], v[32:35], v[194:197], v[206:209]
	v_mfma_f32_16x16x32_bf16 v[96:99], v[36:39], v[198:201], v[64:67]
	v_mfma_f32_16x16x32_bf16 v[64:67], v[48:51], v[0:3], v[108:111]
	v_mfma_f32_16x16x32_bf16 v[84:87], v[52:55], v[4:7], v[64:67]
	v_mfma_f32_16x16x32_bf16 v[64:67], v[48:51], v[194:197], v[104:107]
	v_mfma_f32_16x16x32_bf16 v[80:83], v[52:55], v[198:201], v[64:67]
	v_mfma_f32_16x16x32_bf16 v[64:67], v[222:225], v[0:3], v[210:213]
	v_mfma_f32_16x16x32_bf16 v[68:71], v[226:229], v[4:7], v[64:67]
	v_mfma_f32_16x16x32_bf16 v[64:67], v[222:225], v[194:197], v[214:217]
	v_mfma_f32_16x16x32_bf16 v[64:67], v[226:229], v[198:201], v[64:67]
	s_setprio 0
	s_barrier
; #define LDA(dst, b, h) for (int m = 0; m < 4; ++m) for (int k = 0; k < 2; ++k) \
;     dst[m][k] = *reinterpret_cast<const bf16x8*>((char*)SA(b, h) + lds_byte(wr * 64 + m * 16 + fr, k * 32 + fq * 8))
; #define LDB(dst, b, h) for (int n = 0; n < 2; ++n) for (int k = 0; k < 2; ++k) \
;     dst[n][k] = *reinterpret_cast<const bf16x8*>((char*)SB(b, h) + lds_byte(wc * 32 + n * 16 + fr, k * 32 + fq * 8))
; #define MMA(ai, bj, At, Bt) do { __builtin_amdgcn_s_setprio(1); \
;     for (int m = 0; m < 4; ++m) for (int n = 0; n < 2; ++n) for (int k = 0; k < 2; ++k) \
;       acc[ai][bj][m][n] = __builtin_amdgcn_mfma_f32_16x16x32_bf16(At[m][k], Bt[n][k], acc[ai][bj][m][n], 0, 0, 0); \
;     __builtin_amdgcn_s_setprio(0); } while (0)
; #define WAIT_V(n) asm volatile("s_waitcnt vmcnt(" #n ")" ::: "memory")
; #define WAIT_L(n) asm volatile("s_waitcnt lgkmcnt(" #n ")" ::: "memory")
; #define BAR __builtin_amdgcn_s_barrier()
; template <int EPI> ...
;     ...
;     LDB(B1, 1, 1); WAIT_V(0); BAR; WAIT_L(0); MMA(0, 1, At, B1); BAR;
;     LDA(At, 1, 1); BAR; WAIT_L(0); MMA(1, 0, At, B0); MMA(1, 1, At, B1); BAR; }
;   if (wr == 0) BAR;
	ds_read_b128 v[170:173], v154
	ds_read_b128 v[206:209], v154 offset:1024
	ds_read_b128 v[210:213], v154 offset:2048
	ds_read_b128 v[154:157], v154 offset:3072
	s_waitcnt vmcnt(0)
	s_barrier
	s_waitcnt lgkmcnt(0)
	s_setprio 1
	v_mfma_f32_16x16x32_bf16 v[92:95], v[16:19], v[170:173], v[92:95]
	v_mfma_f32_16x16x32_bf16 v[16:19], v[16:19], v[210:213], v[88:91]
	v_mfma_f32_16x16x32_bf16 v[120:123], v[20:23], v[154:157], v[16:19]
	v_mfma_f32_16x16x32_bf16 v[16:19], v[32:35], v[170:173], v[166:169]
	v_mfma_f32_16x16x32_bf16 v[108:111], v[36:39], v[206:209], v[16:19]
	v_mfma_f32_16x16x32_bf16 v[16:19], v[32:35], v[210:213], v[174:177]
	v_mfma_f32_16x16x32_bf16 v[104:107], v[36:39], v[154:157], v[16:19]
	v_mfma_f32_16x16x32_bf16 v[16:19], v[48:51], v[170:173], v[76:79]
	v_mfma_f32_16x16x32_bf16 v[124:127], v[20:23], v[206:209], v[92:95]
	v_mfma_f32_16x16x32_bf16 v[92:95], v[52:55], v[206:209], v[16:19]
	v_mfma_f32_16x16x32_bf16 v[16:19], v[48:51], v[210:213], v[72:75]
	v_mfma_f32_16x16x32_bf16 v[88:91], v[52:55], v[154:157], v[16:19]
	v_mfma_f32_16x16x32_bf16 v[16:19], v[222:225], v[170:173], v[178:181]
	v_mfma_f32_16x16x32_bf16 v[76:79], v[226:229], v[206:209], v[16:19]
	v_mfma_f32_16x16x32_bf16 v[16:19], v[222:225], v[210:213], v[182:185]
	v_mfma_f32_16x16x32_bf16 v[72:75], v[226:229], v[154:157], v[16:19]
	s_setprio 0
	s_barrier
	ds_read_b128 v[166:169], v153 offset:49152
	ds_read_b128 v[174:177], v153 offset:50176
	ds_read_b128 v[178:181], v152 offset:49152
	ds_read_b128 v[182:185], v152 offset:50176
	ds_read_b128 v[214:217], v151 offset:49152
	ds_read_b128 v[222:225], v151 offset:50176
	ds_read_b128 v[226:229], v150 offset:49152
	ds_read_b128 v[150:153], v150 offset:50176
	s_barrier
	s_waitcnt lgkmcnt(0)
	s_setprio 1
	v_mfma_f32_16x16x32_bf16 v[16:19], v[166:169], v[0:3], v[60:63]
	v_mfma_f32_16x16x32_bf16 v[52:55], v[174:177], v[4:7], v[16:19]
	v_mfma_f32_16x16x32_bf16 v[16:19], v[166:169], v[194:197], v[56:59]
	v_mfma_f32_16x16x32_bf16 v[48:51], v[174:177], v[198:201], v[16:19]
	v_mfma_f32_16x16x32_bf16 v[16:19], v[178:181], v[0:3], v[202:205]
	v_mfma_f32_16x16x32_bf16 v[36:39], v[182:185], v[4:7], v[16:19]
	v_mfma_f32_16x16x32_bf16 v[16:19], v[178:181], v[194:197], v[218:221]
	v_mfma_f32_16x16x32_bf16 v[32:35], v[182:185], v[198:201], v[16:19]
	v_mfma_f32_16x16x32_bf16 v[16:19], v[214:217], v[0:3], v[44:47]
	v_mfma_f32_16x16x32_bf16 v[0:3], v[226:229], v[0:3], v[136:139]
	v_mfma_f32_16x16x32_bf16 v[20:23], v[222:225], v[4:7], v[16:19]
	v_mfma_f32_16x16x32_bf16 v[16:19], v[214:217], v[194:197], v[40:43]
	v_mfma_f32_16x16x32_bf16 v[4:7], v[150:153], v[4:7], v[0:3]
	v_mfma_f32_16x16x32_bf16 v[0:3], v[226:229], v[194:197], v[140:143]
	v_mfma_f32_16x16x32_bf16 v[16:19], v[222:225], v[198:201], v[16:19]
	v_mfma_f32_16x16x32_bf16 v[0:3], v[150:153], v[198:201], v[0:3]
	s_setprio 0
	s_setprio 1
	v_mfma_f32_16x16x32_bf16 v[24:27], v[166:169], v[210:213], v[24:27]
	v_mfma_f32_16x16x32_bf16 v[56:59], v[174:177], v[154:157], v[24:27]
	v_mfma_f32_16x16x32_bf16 v[24:27], v[178:181], v[170:173], v[158:161]
	v_mfma_f32_16x16x32_bf16 v[44:47], v[182:185], v[206:209], v[24:27]
	v_mfma_f32_16x16x32_bf16 v[24:27], v[178:181], v[210:213], v[162:165]
	v_mfma_f32_16x16x32_bf16 v[8:11], v[214:217], v[210:213], v[8:11]
	v_mfma_f32_16x16x32_bf16 v[28:31], v[166:169], v[170:173], v[28:31]
	v_mfma_f32_16x16x32_bf16 v[40:43], v[182:185], v[154:157], v[24:27]
	v_mfma_f32_16x16x32_bf16 v[12:15], v[214:217], v[170:173], v[12:15]
	v_mfma_f32_16x16x32_bf16 v[24:27], v[222:225], v[154:157], v[8:11]
	v_mfma_f32_16x16x32_bf16 v[8:11], v[226:229], v[170:173], v[186:189]
	v_mfma_f32_16x16x32_bf16 v[60:63], v[174:177], v[206:209], v[28:31]
	v_mfma_f32_16x16x32_bf16 v[28:31], v[222:225], v[206:209], v[12:15]
	v_mfma_f32_16x16x32_bf16 v[12:15], v[150:153], v[206:209], v[8:11]
	v_mfma_f32_16x16x32_bf16 v[8:11], v[226:229], v[210:213], v[190:193]
	v_mfma_f32_16x16x32_bf16 v[8:11], v[150:153], v[154:157], v[8:11]
	s_setprio 0
	v_cmp_gt_u32_e32 vcc, s84, v144
	s_barrier
	s_and_saveexec_b64 s[56:57], vcc
	s_cbranch_execz .LBB0_821
	s_barrier

; #define STAGE(P, BASE, kt) do { const char* _g = (const char*)(BASE) + (size_t)((kt) * (BK * 2)); \
;     __builtin_amdgcn_global_load_lds((const unsigned*)(_g + (size_t)goff0), (unsigned*)((char*)(P) + tid_ * 16), 16, 0, 0); \
;     __builtin_amdgcn_global_load_lds((const unsigned*)(_g + (size_t)goff1), (unsigned*)((char*)(P) + tid_ * 16 + 8192), 16, 0, 0); } while (0)
; #define STAGEA(P, BASE, kt) do { const char* _g = (const char*)(BASE) + (size_t)((kt) * a_kbytes); \
;     __builtin_amdgcn_global_load_lds((const unsigned*)(_g + (size_t)goffA0), (unsigned*)((char*)(P) + tid_ * 16), 16, 0, 0); \
;     __builtin_amdgcn_global_load_lds((const unsigned*)(_g + (size_t)goffA1), (unsigned*)((char*)(P) + tid_ * 16 + 8192), 16, 0, 0); } while (0)
; #define LDA(dst, b, h) for (int m = 0; m < 4; ++m) for (int k = 0; k < 2; ++k) \
;     dst[m][k] = *reinterpret_cast<const bf16x8*>((char*)SA(b, h) + lds_byte(wr * 64 + m * 16 + fr, k * 32 + fq * 8))
; #define LDB(dst, b, h) for (int n = 0; n < 2; ++n) for (int k = 0; k < 2; ++k) \
;     dst[n][k] = *reinterpret_cast<const bf16x8*>((char*)SB(b, h) + lds_byte(wc * 32 + n * 16 + fr, k * 32 + fq * 8))
; #define MMA(ai, bj, At, Bt) do { __builtin_amdgcn_s_setprio(1); \
;     for (int m = 0; m < 4; ++m) for (int n = 0; n < 2; ++n) for (int k = 0; k < 2; ++k) \
;       acc[ai][bj][m][n] = __builtin_amdgcn_mfma_f32_16x16x32_bf16(At[m][k], Bt[n][k], acc[ai][bj][m][n], 0, 0, 0); \
;     __builtin_amdgcn_s_setprio(0); } while (0)
; #define WAIT_L(n) asm volatile("s_waitcnt lgkmcnt(" #n ")" ::: "memory")
; #define BAR __builtin_amdgcn_s_barrier()
; #define SCHED __builtin_amdgcn_sched_barrier(0)
; template <int EPI> ...
;     ...
;     LDB(B0, 0, 0); SCHED; LDA(At, 0, 0); STAGEA(SA(1, 1), A1, t + 1);
;     WAIT_L(8); BAR; WAIT_L(0); MMA(0, 0, At, B0); BAR; SCHED;
;     LDB(B1, 0, 1); STAGE(SB(0, 0), B0p, t + 2);
;     BAR; WAIT_L(0); MMA(0, 1, At, B1); BAR;
;     LDA(At, 0, 1); STAGEA(SA(0, 0), A0, t + 2);
;     BAR; WAIT_L(0); MMA(1, 0, At, B0); BAR; SCHED;
.LBB0_856:
	ds_read_b128 v[174:177], v171
	ds_read_b128 v[178:181], v171 offset:1024
	ds_read_b128 v[182:185], v171 offset:2048
	ds_read_b128 v[186:189], v171 offset:3072
	v_add_u32_e32 v172, 0xc000, v158
	v_lshl_add_u64 v[238:239], s[56:57], 0, v[140:141]
	v_readfirstlane_b32 s53, v172
	v_add_u32_e32 v173, 0xe000, v158
	v_lshl_add_u64 v[222:223], v[238:239], 0, s[6:7]
	s_mov_b32 m0, s53
	v_lshl_add_u64 v[240:241], s[56:57], 0, v[142:143]
	v_readfirstlane_b32 s53, v173
	ds_read_b128 v[190:193], v153
	ds_read_b128 v[194:197], v153 offset:1024
	ds_read_b128 v[198:201], v152
	ds_read_b128 v[202:205], v152 offset:1024
	ds_read_b128 v[206:209], v151
	ds_read_b128 v[210:213], v151 offset:1024
	ds_read_b128 v[214:217], v150
	ds_read_b128 v[218:221], v150 offset:1024
	global_load_lds_dwordx4 v[222:223], off
	v_lshl_add_u64 v[222:223], v[240:241], 0, s[6:7]
	s_mov_b32 m0, s53
	s_nop 0
	global_load_lds_dwordx4 v[222:223], off
	s_waitcnt lgkmcnt(8)
	s_barrier
	s_waitcnt lgkmcnt(0)
	s_setprio 1
	v_mfma_f32_16x16x32_bf16 v[124:127], v[190:193], v[174:177], v[124:127]
	v_mfma_f32_16x16x32_bf16 v[120:123], v[190:193], v[182:185], v[120:123]
	v_mfma_f32_16x16x32_bf16 v[116:119], v[198:201], v[174:177], v[116:119]
	v_mfma_f32_16x16x32_bf16 v[112:115], v[198:201], v[182:185], v[112:115]
	v_mfma_f32_16x16x32_bf16 v[108:111], v[206:209], v[174:177], v[108:111]
	v_mfma_f32_16x16x32_bf16 v[104:107], v[206:209], v[182:185], v[104:107]
	v_mfma_f32_16x16x32_bf16 v[100:103], v[214:217], v[174:177], v[100:103]
	v_mfma_f32_16x16x32_bf16 v[96:99], v[214:217], v[182:185], v[96:99]
	v_mfma_f32_16x16x32_bf16 v[124:127], v[194:197], v[178:181], v[124:127]
	v_mfma_f32_16x16x32_bf16 v[120:123], v[194:197], v[186:189], v[120:123]
	v_mfma_f32_16x16x32_bf16 v[116:119], v[202:205], v[178:181], v[116:119]
	v_mfma_f32_16x16x32_bf16 v[112:115], v[202:205], v[186:189], v[112:115]
	v_mfma_f32_16x16x32_bf16 v[108:111], v[210:213], v[178:181], v[108:111]
	v_mfma_f32_16x16x32_bf16 v[104:107], v[210:213], v[186:189], v[104:107]
	v_mfma_f32_16x16x32_bf16 v[100:103], v[218:221], v[178:181], v[100:103]
	v_mfma_f32_16x16x32_bf16 v[96:99], v[218:221], v[186:189], v[96:99]
	s_setprio 0
	s_barrier
	v_lshl_add_u64 v[242:243], s[56:57], 0, v[136:137]
	v_readfirstlane_b32 s53, v155
	v_lshl_add_u64 v[244:245], v[242:243], 0, s[8:9]
	s_mov_b32 m0, s53
	ds_read_b128 v[222:225], v168
	ds_read_b128 v[226:229], v168 offset:1024
	ds_read_b128 v[230:233], v168 offset:2048
	ds_read_b128 v[234:237], v168 offset:3072
	global_load_lds_dwordx4 v[244:245], off
	v_lshl_add_u64 v[244:245], s[56:57], 0, v[138:139]
	v_readfirstlane_b32 s53, v156
	v_lshl_add_u64 v[246:247], v[244:245], 0, s[8:9]
	s_mov_b32 m0, s53
	s_nop 0
	global_load_lds_dwordx4 v[246:247], off
	s_barrier
	s_waitcnt lgkmcnt(0)
	s_setprio 1
	v_mfma_f32_16x16x32_bf16 v[92:95], v[190:193], v[222:225], v[92:95]
	v_mfma_f32_16x16x32_bf16 v[88:91], v[190:193], v[230:233], v[88:91]
	v_mfma_f32_16x16x32_bf16 v[84:87], v[198:201], v[222:225], v[84:87]
	v_mfma_f32_16x16x32_bf16 v[80:83], v[198:201], v[230:233], v[80:83]
	v_mfma_f32_16x16x32_bf16 v[76:79], v[206:209], v[222:225], v[76:79]
	v_mfma_f32_16x16x32_bf16 v[72:75], v[206:209], v[230:233], v[72:75]
	v_mfma_f32_16x16x32_bf16 v[68:71], v[214:217], v[222:225], v[68:71]
	v_mfma_f32_16x16x32_bf16 v[64:67], v[214:217], v[230:233], v[64:67]
	v_mfma_f32_16x16x32_bf16 v[92:95], v[194:197], v[226:229], v[92:95]
	v_mfma_f32_16x16x32_bf16 v[88:91], v[194:197], v[234:237], v[88:91]
	v_mfma_f32_16x16x32_bf16 v[84:87], v[202:205], v[226:229], v[84:87]
	v_mfma_f32_16x16x32_bf16 v[80:83], v[202:205], v[234:237], v[80:83]
	v_mfma_f32_16x16x32_bf16 v[76:79], v[210:213], v[226:229], v[76:79]
	v_mfma_f32_16x16x32_bf16 v[72:75], v[210:213], v[234:237], v[72:75]
	v_mfma_f32_16x16x32_bf16 v[68:71], v[218:221], v[226:229], v[68:71]
	v_mfma_f32_16x16x32_bf16 v[64:67], v[218:221], v[234:237], v[64:67]
	s_setprio 0
	v_readfirstlane_b32 s53, v158
	v_lshl_add_u64 v[246:247], v[238:239], 0, s[10:11]
	s_mov_b32 m0, s53
	v_readfirstlane_b32 s53, v159
	s_barrier
	ds_read_b128 v[190:193], v153 offset:16384
	ds_read_b128 v[194:197], v153 offset:17408
	ds_read_b128 v[198:201], v152 offset:16384
	ds_read_b128 v[202:205], v152 offset:17408
	ds_read_b128 v[206:209], v151 offset:16384
	ds_read_b128 v[210:213], v151 offset:17408
	ds_read_b128 v[214:217], v150 offset:16384
	ds_read_b128 v[218:221], v150 offset:17408
	global_load_lds_dwordx4 v[246:247], off
	v_lshl_add_u64 v[246:247], v[240:241], 0, s[10:11]
	s_mov_b32 m0, s53
	s_nop 0
	global_load_lds_dwordx4 v[246:247], off
	s_barrier
	s_waitcnt lgkmcnt(0)
	s_setprio 1
	v_mfma_f32_16x16x32_bf16 v[60:63], v[190:193], v[174:177], v[60:63]
	v_mfma_f32_16x16x32_bf16 v[56:59], v[190:193], v[182:185], v[56:59]
	v_mfma_f32_16x16x32_bf16 v[52:55], v[198:201], v[174:177], v[52:55]
	v_mfma_f32_16x16x32_bf16 v[48:51], v[198:201], v[182:185], v[48:51]
	v_mfma_f32_16x16x32_bf16 v[44:47], v[206:209], v[174:177], v[44:47]
	v_mfma_f32_16x16x32_bf16 v[40:43], v[206:209], v[182:185], v[40:43]
	v_mfma_f32_16x16x32_bf16 v[36:39], v[214:217], v[174:177], v[36:39]
	v_mfma_f32_16x16x32_bf16 v[32:35], v[214:217], v[182:185], v[32:35]
	v_mfma_f32_16x16x32_bf16 v[60:63], v[194:197], v[178:181], v[60:63]
	v_mfma_f32_16x16x32_bf16 v[56:59], v[194:197], v[186:189], v[56:59]
	v_mfma_f32_16x16x32_bf16 v[52:55], v[202:205], v[178:181], v[52:55]
	v_mfma_f32_16x16x32_bf16 v[48:51], v[202:205], v[186:189], v[48:51]
	v_mfma_f32_16x16x32_bf16 v[44:47], v[210:213], v[178:181], v[44:47]
	v_mfma_f32_16x16x32_bf16 v[40:43], v[210:213], v[186:189], v[40:43]
	v_mfma_f32_16x16x32_bf16 v[36:39], v[218:221], v[178:181], v[36:39]
	v_mfma_f32_16x16x32_bf16 v[32:35], v[218:221], v[186:189], v[32:35]
	s_setprio 0
	s_barrier
; #define STAGE(P, BASE, kt) do { const char* _g = (const char*)(BASE) + (size_t)((kt) * (BK * 2)); \
;     __builtin_amdgcn_global_load_lds((const unsigned*)(_g + (size_t)goff0), (unsigned*)((char*)(P) + tid_ * 16), 16, 0, 0); \
;     __builtin_amdgcn_global_load_lds((const unsigned*)(_g + (size_t)goff1), (unsigned*)((char*)(P) + tid_ * 16 + 8192), 16, 0, 0); } while (0)
; #define STAGEA(P, BASE, kt) do { const char* _g = (const char*)(BASE) + (size_t)((kt) * a_kbytes); \
;     __builtin_amdgcn_global_load_lds((const unsigned*)(_g + (size_t)goffA0), (unsigned*)((char*)(P) + tid_ * 16), 16, 0, 0); \
;     __builtin_amdgcn_global_load_lds((const unsigned*)(_g + (size_t)goffA1), (unsigned*)((char*)(P) + tid_ * 16 + 8192), 16, 0, 0); } while (0)
; #define LDA(dst, b, h) for (int m = 0; m < 4; ++m) for (int k = 0; k < 2; ++k) \
;     dst[m][k] = *reinterpret_cast<const bf16x8*>((char*)SA(b, h) + lds_byte(wr * 64 + m * 16 + fr, k * 32 + fq * 8))
; #define LDB(dst, b, h) for (int n = 0; n < 2; ++n) for (int k = 0; k < 2; ++k) \
;     dst[n][k] = *reinterpret_cast<const bf16x8*>((char*)SB(b, h) + lds_byte(wc * 32 + n * 16 + fr, k * 32 + fq * 8))
; #define MMA(ai, bj, At, Bt) do { __builtin_amdgcn_s_setprio(1); \
;     for (int m = 0; m < 4; ++m) for (int n = 0; n < 2; ++n) for (int k = 0; k < 2; ++k) \
;       acc[ai][bj][m][n] = __builtin_amdgcn_mfma_f32_16x16x32_bf16(At[m][k], Bt[n][k], acc[ai][bj][m][n], 0, 0, 0); \
;     __builtin_amdgcn_s_setprio(0); } while (0)
; #define WAIT_V(n) asm volatile("s_waitcnt vmcnt(" #n ")" ::: "memory")
; #define WAIT_L(n) asm volatile("s_waitcnt lgkmcnt(" #n ")" ::: "memory")
; #define BAR __builtin_amdgcn_s_barrier()
; #define SCHED __builtin_amdgcn_sched_barrier(0)
; template <int EPI> ...
;     ...
;     STAGE(SB(0, 1), B1p, t + 2);
;     WAIT_V(6); BAR; MMA(1, 1, At, B1); BAR;
;     LDB(B0, 1, 0); SCHED; LDA(At, 1, 0); STAGEA(SA(0, 1), A1, t + 2);
;     WAIT_L(8); BAR; WAIT_L(0); MMA(0, 0, At, B0); BAR; SCHED;
;     LDB(B1, 1, 1); STAGE(SB(1, 0), B0p, t + 3);
;     BAR; WAIT_L(0); MMA(0, 1, At, B1); BAR;
;     LDA(At, 1, 1); STAGEA(SA(1, 0), A0, t + 3);
	v_readfirstlane_b32 s53, v160
	v_lshl_add_u64 v[174:175], v[242:243], 0, s[12:13]
	s_mov_b32 m0, s53
	v_readfirstlane_b32 s53, v161
	global_load_lds_dwordx4 v[174:175], off
	v_lshl_add_u64 v[174:175], v[244:245], 0, s[12:13]
	s_mov_b32 m0, s53
	s_nop 0
	global_load_lds_dwordx4 v[174:175], off
	s_waitcnt vmcnt(6)
	s_barrier
	s_setprio 1
	v_mfma_f32_16x16x32_bf16 v[28:31], v[190:193], v[222:225], v[28:31]
	v_mfma_f32_16x16x32_bf16 v[24:27], v[190:193], v[230:233], v[24:27]
	v_mfma_f32_16x16x32_bf16 v[20:23], v[198:201], v[222:225], v[20:23]
	v_mfma_f32_16x16x32_bf16 v[16:19], v[198:201], v[230:233], v[16:19]
	v_mfma_f32_16x16x32_bf16 v[12:15], v[206:209], v[222:225], v[12:15]
	v_mfma_f32_16x16x32_bf16 v[8:11], v[206:209], v[230:233], v[8:11]
	v_mfma_f32_16x16x32_bf16 v[4:7], v[214:217], v[222:225], v[4:7]
	v_mfma_f32_16x16x32_bf16 v[0:3], v[214:217], v[230:233], v[0:3]
	v_mfma_f32_16x16x32_bf16 v[28:31], v[194:197], v[226:229], v[28:31]
	v_mfma_f32_16x16x32_bf16 v[24:27], v[194:197], v[234:237], v[24:27]
	v_mfma_f32_16x16x32_bf16 v[20:23], v[202:205], v[226:229], v[20:23]
	v_mfma_f32_16x16x32_bf16 v[16:19], v[202:205], v[234:237], v[16:19]
	v_mfma_f32_16x16x32_bf16 v[12:15], v[210:213], v[226:229], v[12:15]
	v_mfma_f32_16x16x32_bf16 v[8:11], v[210:213], v[234:237], v[8:11]
	v_mfma_f32_16x16x32_bf16 v[4:7], v[218:221], v[226:229], v[4:7]
	v_mfma_f32_16x16x32_bf16 v[0:3], v[218:221], v[234:237], v[0:3]
	s_setprio 0
	s_barrier
	ds_read_b128 v[174:177], v157
	ds_read_b128 v[178:181], v157 offset:1024
	ds_read_b128 v[182:185], v157 offset:2048
	ds_read_b128 v[186:189], v157 offset:3072
	v_readfirstlane_b32 s53, v162
	v_lshl_add_u64 v[222:223], v[238:239], 0, s[14:15]
	s_mov_b32 m0, s53
	v_readfirstlane_b32 s53, v163
	ds_read_b128 v[190:193], v153 offset:32768
	ds_read_b128 v[194:197], v153 offset:33792
	ds_read_b128 v[198:201], v152 offset:32768
	ds_read_b128 v[202:205], v152 offset:33792
	ds_read_b128 v[206:209], v151 offset:32768
	ds_read_b128 v[210:213], v151 offset:33792
	ds_read_b128 v[214:217], v150 offset:32768
	ds_read_b128 v[218:221], v150 offset:33792
	global_load_lds_dwordx4 v[222:223], off
	v_lshl_add_u64 v[222:223], v[240:241], 0, s[14:15]
	s_mov_b32 m0, s53
	s_nop 0
	global_load_lds_dwordx4 v[222:223], off
	s_waitcnt lgkmcnt(8)
	s_barrier
	s_waitcnt lgkmcnt(0)
	s_setprio 1
	v_mfma_f32_16x16x32_bf16 v[124:127], v[190:193], v[174:177], v[124:127]
	v_mfma_f32_16x16x32_bf16 v[120:123], v[190:193], v[182:185], v[120:123]
	v_mfma_f32_16x16x32_bf16 v[116:119], v[198:201], v[174:177], v[116:119]
	v_mfma_f32_16x16x32_bf16 v[112:115], v[198:201], v[182:185], v[112:115]
	v_mfma_f32_16x16x32_bf16 v[108:111], v[206:209], v[174:177], v[108:111]
	v_mfma_f32_16x16x32_bf16 v[104:107], v[206:209], v[182:185], v[104:107]
	v_mfma_f32_16x16x32_bf16 v[100:103], v[214:217], v[174:177], v[100:103]
	v_mfma_f32_16x16x32_bf16 v[96:99], v[214:217], v[182:185], v[96:99]
	v_mfma_f32_16x16x32_bf16 v[124:127], v[194:197], v[178:181], v[124:127]
	v_mfma_f32_16x16x32_bf16 v[120:123], v[194:197], v[186:189], v[120:123]
	v_mfma_f32_16x16x32_bf16 v[116:119], v[202:205], v[178:181], v[116:119]
	v_mfma_f32_16x16x32_bf16 v[112:115], v[202:205], v[186:189], v[112:115]
	v_mfma_f32_16x16x32_bf16 v[108:111], v[210:213], v[178:181], v[108:111]
	v_mfma_f32_16x16x32_bf16 v[104:107], v[210:213], v[186:189], v[104:107]
	v_mfma_f32_16x16x32_bf16 v[100:103], v[218:221], v[178:181], v[100:103]
	v_mfma_f32_16x16x32_bf16 v[96:99], v[218:221], v[186:189], v[96:99]
	s_setprio 0
	s_barrier
	v_readfirstlane_b32 s53, v164
	v_lshl_add_u64 v[246:247], v[242:243], 0, s[24:25]
	s_mov_b32 m0, s53
	v_readfirstlane_b32 s53, v165
	ds_read_b128 v[222:225], v154
	ds_read_b128 v[226:229], v154 offset:1024
	ds_read_b128 v[230:233], v154 offset:2048
	ds_read_b128 v[234:237], v154 offset:3072
	global_load_lds_dwordx4 v[246:247], off
	v_lshl_add_u64 v[246:247], v[244:245], 0, s[24:25]
	s_mov_b32 m0, s53
	s_nop 0
	global_load_lds_dwordx4 v[246:247], off
	s_barrier
	s_waitcnt lgkmcnt(0)
	s_setprio 1
	v_mfma_f32_16x16x32_bf16 v[92:95], v[190:193], v[222:225], v[92:95]
	v_mfma_f32_16x16x32_bf16 v[88:91], v[190:193], v[230:233], v[88:91]
	v_mfma_f32_16x16x32_bf16 v[84:87], v[198:201], v[222:225], v[84:87]
	v_mfma_f32_16x16x32_bf16 v[80:83], v[198:201], v[230:233], v[80:83]
	v_mfma_f32_16x16x32_bf16 v[76:79], v[206:209], v[222:225], v[76:79]
	v_mfma_f32_16x16x32_bf16 v[72:75], v[206:209], v[230:233], v[72:75]
	v_mfma_f32_16x16x32_bf16 v[68:71], v[214:217], v[222:225], v[68:71]
	v_mfma_f32_16x16x32_bf16 v[64:67], v[214:217], v[230:233], v[64:67]
	v_mfma_f32_16x16x32_bf16 v[92:95], v[194:197], v[226:229], v[92:95]
	v_mfma_f32_16x16x32_bf16 v[88:91], v[194:197], v[234:237], v[88:91]
	v_mfma_f32_16x16x32_bf16 v[84:87], v[202:205], v[226:229], v[84:87]
	v_mfma_f32_16x16x32_bf16 v[80:83], v[202:205], v[234:237], v[80:83]
	v_mfma_f32_16x16x32_bf16 v[76:79], v[210:213], v[226:229], v[76:79]
	v_mfma_f32_16x16x32_bf16 v[72:75], v[210:213], v[234:237], v[72:75]
	v_mfma_f32_16x16x32_bf16 v[68:71], v[218:221], v[226:229], v[68:71]
	v_mfma_f32_16x16x32_bf16 v[64:67], v[218:221], v[234:237], v[64:67]
	s_setprio 0
	v_readfirstlane_b32 s53, v166
	v_lshl_add_u64 v[238:239], v[238:239], 0, s[36:37]
	s_mov_b32 m0, s53
	v_readfirstlane_b32 s53, v167
	s_barrier
	ds_read_b128 v[190:193], v153 offset:49152
	ds_read_b128 v[194:197], v153 offset:50176
	ds_read_b128 v[198:201], v152 offset:49152
	ds_read_b128 v[202:205], v152 offset:50176
	ds_read_b128 v[206:209], v151 offset:49152
	ds_read_b128 v[210:213], v151 offset:50176
	ds_read_b128 v[214:217], v150 offset:49152
	ds_read_b128 v[218:221], v150 offset:50176
	global_load_lds_dwordx4 v[238:239], off
	v_lshl_add_u64 v[238:239], v[240:241], 0, s[36:37]
	s_mov_b32 m0, s53
	s_nop 0
	global_load_lds_dwordx4 v[238:239], off
	s_barrier
; #define STAGE(P, BASE, kt) do { const char* _g = (const char*)(BASE) + (size_t)((kt) * (BK * 2)); \
;     __builtin_amdgcn_global_load_lds((const unsigned*)(_g + (size_t)goff0), (unsigned*)((char*)(P) + tid_ * 16), 16, 0, 0); \
;     __builtin_amdgcn_global_load_lds((const unsigned*)(_g + (size_t)goff1), (unsigned*)((char*)(P) + tid_ * 16 + 8192), 16, 0, 0); } while (0)
; #define STAGEA(P, BASE, kt) do { const char* _g = (const char*)(BASE) + (size_t)((kt) * a_kbytes); \
;     __builtin_amdgcn_global_load_lds((const unsigned*)(_g + (size_t)goffA0), (unsigned*)((char*)(P) + tid_ * 16), 16, 0, 0); \
;     __builtin_amdgcn_global_load_lds((const unsigned*)(_g + (size_t)goffA1), (unsigned*)((char*)(P) + tid_ * 16 + 8192), 16, 0, 0); } while (0)
; #define LDA(dst, b, h) for (int m = 0; m < 4; ++m) for (int k = 0; k < 2; ++k) \
;     dst[m][k] = *reinterpret_cast<const bf16x8*>((char*)SA(b, h) + lds_byte(wr * 64 + m * 16 + fr, k * 32 + fq * 8))
; #define LDB(dst, b, h) for (int n = 0; n < 2; ++n) for (int k = 0; k < 2; ++k) \
;     dst[n][k] = *reinterpret_cast<const bf16x8*>((char*)SB(b, h) + lds_byte(wc * 32 + n * 16 + fr, k * 32 + fq * 8))
; #define MMA(ai, bj, At, Bt) do { __builtin_amdgcn_s_setprio(1); \
;     for (int m = 0; m < 4; ++m) for (int n = 0; n < 2; ++n) for (int k = 0; k < 2; ++k) \
;       acc[ai][bj][m][n] = __builtin_amdgcn_mfma_f32_16x16x32_bf16(At[m][k], Bt[n][k], acc[ai][bj][m][n], 0, 0, 0); \
;     __builtin_amdgcn_s_setprio(0); } while (0)
; #define WAIT_V(n) asm volatile("s_waitcnt vmcnt(" #n ")" ::: "memory")
; #define WAIT_L(n) asm volatile("s_waitcnt lgkmcnt(" #n ")" ::: "memory")
; #define BAR __builtin_amdgcn_s_barrier()
; #define SCHED __builtin_amdgcn_sched_barrier(0)
; template <int EPI> ...
;     ...
;     BAR; WAIT_L(0); MMA(1, 0, At, B0); BAR; SCHED;
;     STAGE(SB(1, 1), B1p, t + 3);
;     WAIT_V(6); BAR; MMA(1, 1, At, B1); BAR;
;   }
;   { LDB(B0, 0, 0); LDA(At, 0, 0); STAGEA(SA(1, 1), A1, nt - 1);
;     BAR; WAIT_L(0); MMA(0, 0, At, B0); BAR;
;     LDB(B1, 0, 1); BAR; WAIT_L(0); MMA(0, 1, At, B1); BAR;
	s_waitcnt lgkmcnt(0)
	s_setprio 1
	v_mfma_f32_16x16x32_bf16 v[60:63], v[190:193], v[174:177], v[60:63]
	v_mfma_f32_16x16x32_bf16 v[56:59], v[190:193], v[182:185], v[56:59]
	v_mfma_f32_16x16x32_bf16 v[52:55], v[198:201], v[174:177], v[52:55]
	v_mfma_f32_16x16x32_bf16 v[48:51], v[198:201], v[182:185], v[48:51]
	v_mfma_f32_16x16x32_bf16 v[44:47], v[206:209], v[174:177], v[44:47]
	v_mfma_f32_16x16x32_bf16 v[40:43], v[206:209], v[182:185], v[40:43]
	v_mfma_f32_16x16x32_bf16 v[36:39], v[214:217], v[174:177], v[36:39]
	v_mfma_f32_16x16x32_bf16 v[32:35], v[214:217], v[182:185], v[32:35]
	v_mfma_f32_16x16x32_bf16 v[60:63], v[194:197], v[178:181], v[60:63]
	v_mfma_f32_16x16x32_bf16 v[56:59], v[194:197], v[186:189], v[56:59]
	v_mfma_f32_16x16x32_bf16 v[52:55], v[202:205], v[178:181], v[52:55]
	v_mfma_f32_16x16x32_bf16 v[48:51], v[202:205], v[186:189], v[48:51]
	v_mfma_f32_16x16x32_bf16 v[44:47], v[210:213], v[178:181], v[44:47]
	v_mfma_f32_16x16x32_bf16 v[40:43], v[210:213], v[186:189], v[40:43]
	v_mfma_f32_16x16x32_bf16 v[36:39], v[218:221], v[178:181], v[36:39]
	v_mfma_f32_16x16x32_bf16 v[32:35], v[218:221], v[186:189], v[32:35]
	s_setprio 0
	s_barrier
	v_readfirstlane_b32 s53, v169
	v_lshl_add_u64 v[174:175], v[242:243], 0, s[42:43]
	s_mov_b32 m0, s53
	v_readfirstlane_b32 s53, v170
	global_load_lds_dwordx4 v[174:175], off
	v_lshl_add_u64 v[174:175], v[244:245], 0, s[42:43]
	s_mov_b32 m0, s53
	s_nop 0
	global_load_lds_dwordx4 v[174:175], off
	s_waitcnt vmcnt(6)
	s_barrier
	s_setprio 1
	v_mfma_f32_16x16x32_bf16 v[28:31], v[190:193], v[222:225], v[28:31]
	v_mfma_f32_16x16x32_bf16 v[24:27], v[190:193], v[230:233], v[24:27]
	v_mfma_f32_16x16x32_bf16 v[20:23], v[198:201], v[222:225], v[20:23]
	v_mfma_f32_16x16x32_bf16 v[16:19], v[198:201], v[230:233], v[16:19]
	v_mfma_f32_16x16x32_bf16 v[12:15], v[206:209], v[222:225], v[12:15]
	v_mfma_f32_16x16x32_bf16 v[8:11], v[206:209], v[230:233], v[8:11]
	v_mfma_f32_16x16x32_bf16 v[4:7], v[214:217], v[222:225], v[4:7]
	v_mfma_f32_16x16x32_bf16 v[0:3], v[214:217], v[230:233], v[0:3]
	v_mfma_f32_16x16x32_bf16 v[28:31], v[194:197], v[226:229], v[28:31]
	v_mfma_f32_16x16x32_bf16 v[24:27], v[194:197], v[234:237], v[24:27]
	v_mfma_f32_16x16x32_bf16 v[20:23], v[202:205], v[226:229], v[20:23]
	v_mfma_f32_16x16x32_bf16 v[16:19], v[202:205], v[234:237], v[16:19]
	v_mfma_f32_16x16x32_bf16 v[12:15], v[210:213], v[226:229], v[12:15]
	v_mfma_f32_16x16x32_bf16 v[8:11], v[210:213], v[234:237], v[8:11]
	v_mfma_f32_16x16x32_bf16 v[4:7], v[218:221], v[226:229], v[4:7]
	v_mfma_f32_16x16x32_bf16 v[0:3], v[218:221], v[234:237], v[0:3]
	s_setprio 0
	s_add_i32 s49, s49, 2
	s_add_u32 s56, s56, 0x100
	s_addc_u32 s57, s57, 0
	s_cmp_lt_u32 s49, 28
	s_barrier
	s_cbranch_scc1 .LBB0_856
	s_add_u32 s54, s54, 0x80f80
	s_addc_u32 s55, s55, 0
	v_readfirstlane_b32 s49, v172
	v_lshl_add_u64 v[166:167], s[54:55], 0, v[130:131]
	s_mov_b32 m0, s49
	v_readfirstlane_b32 s49, v173
	ds_read_b128 v[136:139], v171
	ds_read_b128 v[140:143], v171 offset:1024
	ds_read_b128 v[158:161], v171 offset:2048
	ds_read_b128 v[162:165], v171 offset:3072
	ds_read_b128 v[174:177], v153
	ds_read_b128 v[178:181], v153 offset:1024
	ds_read_b128 v[182:185], v152
	ds_read_b128 v[186:189], v152 offset:1024
	ds_read_b128 v[190:193], v151
	ds_read_b128 v[194:197], v151 offset:1024
	ds_read_b128 v[198:201], v150
	ds_read_b128 v[202:205], v150 offset:1024
	global_load_lds_dwordx4 v[166:167], off
	v_lshl_add_u64 v[166:167], s[54:55], 0, v[128:129]
	s_mov_b32 m0, s49
	s_nop 0
	global_load_lds_dwordx4 v[166:167], off
	s_barrier
	s_waitcnt lgkmcnt(0)
	s_setprio 1
	v_mfma_f32_16x16x32_bf16 v[124:127], v[174:177], v[136:139], v[124:127]
	v_mfma_f32_16x16x32_bf16 v[120:123], v[174:177], v[158:161], v[120:123]
	v_mfma_f32_16x16x32_bf16 v[108:111], v[190:193], v[136:139], v[108:111]
	v_mfma_f32_16x16x32_bf16 v[104:107], v[190:193], v[158:161], v[104:107]
	v_mfma_f32_16x16x32_bf16 v[124:127], v[178:181], v[140:143], v[124:127]
	v_mfma_f32_16x16x32_bf16 v[120:123], v[178:181], v[162:165], v[120:123]
	v_mfma_f32_16x16x32_bf16 v[116:119], v[182:185], v[136:139], v[116:119]
	v_mfma_f32_16x16x32_bf16 v[112:115], v[182:185], v[158:161], v[112:115]
	v_mfma_f32_16x16x32_bf16 v[108:111], v[194:197], v[140:143], v[108:111]
	v_mfma_f32_16x16x32_bf16 v[104:107], v[194:197], v[162:165], v[104:107]
	v_mfma_f32_16x16x32_bf16 v[100:103], v[198:201], v[136:139], v[100:103]
	v_mfma_f32_16x16x32_bf16 v[96:99], v[198:201], v[158:161], v[96:99]
	v_mfma_f32_16x16x32_bf16 v[170:173], v[186:189], v[140:143], v[116:119]
	v_mfma_f32_16x16x32_bf16 v[206:209], v[186:189], v[162:165], v[112:115]
	v_mfma_f32_16x16x32_bf16 v[210:213], v[202:205], v[140:143], v[100:103]
	v_mfma_f32_16x16x32_bf16 v[214:217], v[202:205], v[162:165], v[96:99]
	s_setprio 0
	s_barrier
	s_nop 1
	ds_read_b128 v[96:99], v168
	ds_read_b128 v[100:103], v168 offset:1024
	ds_read_b128 v[112:115], v168 offset:2048
	ds_read_b128 v[116:119], v168 offset:3072
	s_barrier
	s_waitcnt lgkmcnt(0)
	s_setprio 1
	v_mfma_f32_16x16x32_bf16 v[92:95], v[174:177], v[96:99], v[92:95]
	v_mfma_f32_16x16x32_bf16 v[88:91], v[174:177], v[112:115], v[88:91]
	v_mfma_f32_16x16x32_bf16 v[76:79], v[190:193], v[96:99], v[76:79]
	v_mfma_f32_16x16x32_bf16 v[72:75], v[190:193], v[112:115], v[72:75]
	v_mfma_f32_16x16x32_bf16 v[92:95], v[178:181], v[100:103], v[92:95]
	v_mfma_f32_16x16x32_bf16 v[88:91], v[178:181], v[116:119], v[88:91]
	v_mfma_f32_16x16x32_bf16 v[84:87], v[182:185], v[96:99], v[84:87]
	v_mfma_f32_16x16x32_bf16 v[80:83], v[182:185], v[112:115], v[80:83]
	v_mfma_f32_16x16x32_bf16 v[76:79], v[194:197], v[100:103], v[76:79]
	v_mfma_f32_16x16x32_bf16 v[72:75], v[194:197], v[116:119], v[72:75]
	v_mfma_f32_16x16x32_bf16 v[68:71], v[198:201], v[96:99], v[68:71]
	v_mfma_f32_16x16x32_bf16 v[64:67], v[198:201], v[112:115], v[64:67]
	v_mfma_f32_16x16x32_bf16 v[166:169], v[186:189], v[100:103], v[84:87]
	v_mfma_f32_16x16x32_bf16 v[174:177], v[186:189], v[116:119], v[80:83]
	v_mfma_f32_16x16x32_bf16 v[178:181], v[202:205], v[100:103], v[68:71]
	v_mfma_f32_16x16x32_bf16 v[182:185], v[202:205], v[116:119], v[64:67]
	s_setprio 0
	s_barrier
; #define STAGEA(P, BASE, kt) do { const char* _g = (const char*)(BASE) + (size_t)((kt) * a_kbytes); \
;     __builtin_amdgcn_global_load_lds((const unsigned*)(_g + (size_t)goffA0), (unsigned*)((char*)(P) + tid_ * 16), 16, 0, 0); \
;     __builtin_amdgcn_global_load_lds((const unsigned*)(_g + (size_t)goffA1), (unsigned*)((char*)(P) + tid_ * 16 + 8192), 16, 0, 0); } while (0)
; #define LDA(dst, b, h) for (int m = 0; m < 4; ++m) for (int k = 0; k < 2; ++k) \
;     dst[m][k] = *reinterpret_cast<const bf16x8*>((char*)SA(b, h) + lds_byte(wr * 64 + m * 16 + fr, k * 32 + fq * 8))
; #define LDB(dst, b, h) for (int n = 0; n < 2; ++n) for (int k = 0; k < 2; ++k) \
;     dst[n][k] = *reinterpret_cast<const bf16x8*>((char*)SB(b, h) + lds_byte(wc * 32 + n * 16 + fr, k * 32 + fq * 8))
; #define MMA(ai, bj, At, Bt) do { __builtin_amdgcn_s_setprio(1); \
;     for (int m = 0; m < 4; ++m) for (int n = 0; n < 2; ++n) for (int k = 0; k < 2; ++k) \
;       acc[ai][bj][m][n] = __builtin_amdgcn_mfma_f32_16x16x32_bf16(At[m][k], Bt[n][k], acc[ai][bj][m][n], 0, 0, 0); \
;     __builtin_amdgcn_s_setprio(0); } while (0)
; #define WAIT_V(n) asm volatile("s_waitcnt vmcnt(" #n ")" ::: "memory")
; #define WAIT_L(n) asm volatile("s_waitcnt lgkmcnt(" #n ")" ::: "memory")
; #define BAR __builtin_amdgcn_s_barrier()
; template <int EPI> ...
;     ...
;   { LDB(B0, 0, 0); LDA(At, 0, 0); STAGEA(SA(1, 1), A1, nt - 1);
;     BAR; WAIT_L(0); MMA(0, 0, At, B0); BAR;
;     LDB(B1, 0, 1); BAR; WAIT_L(0); MMA(0, 1, At, B1); BAR;
;     LDA(At, 0, 1); WAIT_V(4); BAR; WAIT_L(0); MMA(1, 0, At, B0); MMA(1, 1, At, B1); BAR; }
;   { LDB(B0, 1, 0); LDA(At, 1, 0); WAIT_V(2); BAR; WAIT_L(0); MMA(0, 0, At, B0); BAR;
;     LDB(B1, 1, 1); WAIT_V(0); BAR; WAIT_L(0); MMA(0, 1, At, B1); BAR;
;     LDA(At, 1, 1); BAR; WAIT_L(0); MMA(1, 0, At, B0); MMA(1, 1, At, B1); BAR; }
	s_nop 1
	ds_read_b128 v[64:67], v153 offset:16384
	ds_read_b128 v[68:71], v153 offset:17408
	ds_read_b128 v[80:83], v152 offset:16384
	ds_read_b128 v[84:87], v152 offset:17408
	ds_read_b128 v[186:189], v151 offset:16384
	ds_read_b128 v[190:193], v151 offset:17408
	ds_read_b128 v[194:197], v150 offset:16384
	ds_read_b128 v[198:201], v150 offset:17408
	s_waitcnt vmcnt(4)
	s_barrier
	s_waitcnt lgkmcnt(0)
	s_setprio 1
	v_mfma_f32_16x16x32_bf16 v[60:63], v[64:67], v[136:139], v[60:63]
	v_mfma_f32_16x16x32_bf16 v[56:59], v[64:67], v[158:161], v[56:59]
	v_mfma_f32_16x16x32_bf16 v[44:47], v[186:189], v[136:139], v[44:47]
	v_mfma_f32_16x16x32_bf16 v[40:43], v[186:189], v[158:161], v[40:43]
	v_mfma_f32_16x16x32_bf16 v[60:63], v[68:71], v[140:143], v[60:63]
	v_mfma_f32_16x16x32_bf16 v[56:59], v[68:71], v[162:165], v[56:59]
	v_mfma_f32_16x16x32_bf16 v[52:55], v[80:83], v[136:139], v[52:55]
	v_mfma_f32_16x16x32_bf16 v[48:51], v[80:83], v[158:161], v[48:51]
	v_mfma_f32_16x16x32_bf16 v[44:47], v[190:193], v[140:143], v[44:47]
	v_mfma_f32_16x16x32_bf16 v[40:43], v[190:193], v[162:165], v[40:43]
	v_mfma_f32_16x16x32_bf16 v[36:39], v[194:197], v[136:139], v[36:39]
	v_mfma_f32_16x16x32_bf16 v[32:35], v[194:197], v[158:161], v[32:35]
	v_mfma_f32_16x16x32_bf16 v[202:205], v[84:87], v[140:143], v[52:55]
	v_mfma_f32_16x16x32_bf16 v[218:221], v[84:87], v[162:165], v[48:51]
	v_mfma_f32_16x16x32_bf16 v[136:139], v[198:201], v[140:143], v[36:39]
	v_mfma_f32_16x16x32_bf16 v[140:143], v[198:201], v[162:165], v[32:35]
	s_setprio 0
	s_setprio 1
	v_mfma_f32_16x16x32_bf16 v[28:31], v[64:67], v[96:99], v[28:31]
	v_mfma_f32_16x16x32_bf16 v[24:27], v[64:67], v[112:115], v[24:27]
	v_mfma_f32_16x16x32_bf16 v[12:15], v[186:189], v[96:99], v[12:15]
	v_mfma_f32_16x16x32_bf16 v[8:11], v[186:189], v[112:115], v[8:11]
	v_mfma_f32_16x16x32_bf16 v[28:31], v[68:71], v[100:103], v[28:31]
	v_mfma_f32_16x16x32_bf16 v[24:27], v[68:71], v[116:119], v[24:27]
	v_mfma_f32_16x16x32_bf16 v[20:23], v[80:83], v[96:99], v[20:23]
	v_mfma_f32_16x16x32_bf16 v[16:19], v[80:83], v[112:115], v[16:19]
	v_mfma_f32_16x16x32_bf16 v[12:15], v[190:193], v[100:103], v[12:15]
	v_mfma_f32_16x16x32_bf16 v[8:11], v[190:193], v[116:119], v[8:11]
	v_mfma_f32_16x16x32_bf16 v[4:7], v[194:197], v[96:99], v[4:7]
	v_mfma_f32_16x16x32_bf16 v[0:3], v[194:197], v[112:115], v[0:3]
	v_mfma_f32_16x16x32_bf16 v[158:161], v[84:87], v[100:103], v[20:23]
	v_mfma_f32_16x16x32_bf16 v[162:165], v[84:87], v[116:119], v[16:19]
	v_mfma_f32_16x16x32_bf16 v[186:189], v[198:201], v[100:103], v[4:7]
	v_mfma_f32_16x16x32_bf16 v[190:193], v[198:201], v[116:119], v[0:3]
	s_setprio 0
	s_barrier
	s_nop 1
	ds_read_b128 v[0:3], v157
	ds_read_b128 v[4:7], v157 offset:1024
	ds_read_b128 v[194:197], v157 offset:2048
	ds_read_b128 v[198:201], v157 offset:3072
	ds_read_b128 v[16:19], v153 offset:32768
	ds_read_b128 v[20:23], v153 offset:33792
	ds_read_b128 v[32:35], v152 offset:32768
	ds_read_b128 v[36:39], v152 offset:33792
	ds_read_b128 v[48:51], v151 offset:32768
	ds_read_b128 v[52:55], v151 offset:33792
	ds_read_b128 v[222:225], v150 offset:32768
	ds_read_b128 v[226:229], v150 offset:33792
	s_waitcnt vmcnt(2)
	s_barrier
	s_waitcnt lgkmcnt(0)
	s_setprio 1
	v_mfma_f32_16x16x32_bf16 v[64:67], v[16:19], v[0:3], v[124:127]
	v_mfma_f32_16x16x32_bf16 v[116:119], v[20:23], v[4:7], v[64:67]
	v_mfma_f32_16x16x32_bf16 v[64:67], v[16:19], v[194:197], v[120:123]
	v_mfma_f32_16x16x32_bf16 v[112:115], v[20:23], v[198:201], v[64:67]
	v_mfma_f32_16x16x32_bf16 v[64:67], v[32:35], v[0:3], v[170:173]
	v_mfma_f32_16x16x32_bf16 v[100:103], v[36:39], v[4:7], v[64:67]
	v_mfma_f32_16x16x32_bf16 v[64:67], v[32:35], v[194:197], v[206:209]
	v_mfma_f32_16x16x32_bf16 v[96:99], v[36:39], v[198:201], v[64:67]
	v_mfma_f32_16x16x32_bf16 v[64:67], v[48:51], v[0:3], v[108:111]
	v_mfma_f32_16x16x32_bf16 v[84:87], v[52:55], v[4:7], v[64:67]
	v_mfma_f32_16x16x32_bf16 v[64:67], v[48:51], v[194:197], v[104:107]
	v_mfma_f32_16x16x32_bf16 v[80:83], v[52:55], v[198:201], v[64:67]
	v_mfma_f32_16x16x32_bf16 v[64:67], v[222:225], v[0:3], v[210:213]
	v_mfma_f32_16x16x32_bf16 v[68:71], v[226:229], v[4:7], v[64:67]
	v_mfma_f32_16x16x32_bf16 v[64:67], v[222:225], v[194:197], v[214:217]
	v_mfma_f32_16x16x32_bf16 v[64:67], v[226:229], v[198:201], v[64:67]
	s_setprio 0
	s_barrier
; #define LDA(dst, b, h) for (int m = 0; m < 4; ++m) for (int k = 0; k < 2; ++k) \
;     dst[m][k] = *reinterpret_cast<const bf16x8*>((char*)SA(b, h) + lds_byte(wr * 64 + m * 16 + fr, k * 32 + fq * 8))
; #define LDB(dst, b, h) for (int n = 0; n < 2; ++n) for (int k = 0; k < 2; ++k) \
;     dst[n][k] = *reinterpret_cast<const bf16x8*>((char*)SB(b, h) + lds_byte(wc * 32 + n * 16 + fr, k * 32 + fq * 8))
; #define MMA(ai, bj, At, Bt) do { __builtin_amdgcn_s_setprio(1); \
;     for (int m = 0; m < 4; ++m) for (int n = 0; n < 2; ++n) for (int k = 0; k < 2; ++k) \
;       acc[ai][bj][m][n] = __builtin_amdgcn_mfma_f32_16x16x32_bf16(At[m][k], Bt[n][k], acc[ai][bj][m][n], 0, 0, 0); \
;     __builtin_amdgcn_s_setprio(0); } while (0)
; #define WAIT_V(n) asm volatile("s_waitcnt vmcnt(" #n ")" ::: "memory")
; #define WAIT_L(n) asm volatile("s_waitcnt lgkmcnt(" #n ")" ::: "memory")
; #define BAR __builtin_amdgcn_s_barrier()
; template <int EPI> ...
;     ...
;   { LDB(B0, 1, 0); LDA(At, 1, 0); WAIT_V(2); BAR; WAIT_L(0); MMA(0, 0, At, B0); BAR;
;     LDB(B1, 1, 1); WAIT_V(0); BAR; WAIT_L(0); MMA(0, 1, At, B1); BAR;
;     LDA(At, 1, 1); BAR; WAIT_L(0); MMA(1, 0, At, B0); MMA(1, 1, At, B1); BAR; }
;   if (wr == 0) BAR;
	ds_read_b128 v[170:173], v154
	ds_read_b128 v[206:209], v154 offset:1024
	ds_read_b128 v[210:213], v154 offset:2048
	ds_read_b128 v[154:157], v154 offset:3072
	s_waitcnt vmcnt(0)
	s_barrier
	s_waitcnt lgkmcnt(0)
	s_setprio 1
	v_mfma_f32_16x16x32_bf16 v[92:95], v[16:19], v[170:173], v[92:95]
	v_mfma_f32_16x16x32_bf16 v[16:19], v[16:19], v[210:213], v[88:91]
	v_mfma_f32_16x16x32_bf16 v[120:123], v[20:23], v[154:157], v[16:19]
	v_mfma_f32_16x16x32_bf16 v[16:19], v[32:35], v[170:173], v[166:169]
	v_mfma_f32_16x16x32_bf16 v[108:111], v[36:39], v[206:209], v[16:19]
	v_mfma_f32_16x16x32_bf16 v[16:19], v[32:35], v[210:213], v[174:177]
	v_mfma_f32_16x16x32_bf16 v[104:107], v[36:39], v[154:157], v[16:19]
	v_mfma_f32_16x16x32_bf16 v[16:19], v[48:51], v[170:173], v[76:79]
	v_mfma_f32_16x16x32_bf16 v[124:127], v[20:23], v[206:209], v[92:95]
	v_mfma_f32_16x16x32_bf16 v[92:95], v[52:55], v[206:209], v[16:19]
	v_mfma_f32_16x16x32_bf16 v[16:19], v[48:51], v[210:213], v[72:75]
	v_mfma_f32_16x16x32_bf16 v[88:91], v[52:55], v[154:157], v[16:19]
	v_mfma_f32_16x16x32_bf16 v[16:19], v[222:225], v[170:173], v[178:181]
	v_mfma_f32_16x16x32_bf16 v[76:79], v[226:229], v[206:209], v[16:19]
	v_mfma_f32_16x16x32_bf16 v[16:19], v[222:225], v[210:213], v[182:185]
	v_mfma_f32_16x16x32_bf16 v[72:75], v[226:229], v[154:157], v[16:19]
	s_setprio 0
	s_barrier
	ds_read_b128 v[166:169], v153 offset:49152
	ds_read_b128 v[174:177], v153 offset:50176
	ds_read_b128 v[178:181], v152 offset:49152
	ds_read_b128 v[182:185], v152 offset:50176
	ds_read_b128 v[214:217], v151 offset:49152
	ds_read_b128 v[222:225], v151 offset:50176
	ds_read_b128 v[226:229], v150 offset:49152
	ds_read_b128 v[150:153], v150 offset:50176
	s_barrier
	s_waitcnt lgkmcnt(0)
	s_setprio 1
	v_mfma_f32_16x16x32_bf16 v[16:19], v[166:169], v[0:3], v[60:63]
	v_mfma_f32_16x16x32_bf16 v[52:55], v[174:177], v[4:7], v[16:19]
	v_mfma_f32_16x16x32_bf16 v[16:19], v[166:169], v[194:197], v[56:59]
	v_mfma_f32_16x16x32_bf16 v[48:51], v[174:177], v[198:201], v[16:19]
	v_mfma_f32_16x16x32_bf16 v[16:19], v[178:181], v[0:3], v[202:205]
	v_mfma_f32_16x16x32_bf16 v[36:39], v[182:185], v[4:7], v[16:19]
	v_mfma_f32_16x16x32_bf16 v[16:19], v[178:181], v[194:197], v[218:221]
	v_mfma_f32_16x16x32_bf16 v[32:35], v[182:185], v[198:201], v[16:19]
	v_mfma_f32_16x16x32_bf16 v[16:19], v[214:217], v[0:3], v[44:47]
	v_mfma_f32_16x16x32_bf16 v[0:3], v[226:229], v[0:3], v[136:139]
	v_mfma_f32_16x16x32_bf16 v[20:23], v[222:225], v[4:7], v[16:19]
	v_mfma_f32_16x16x32_bf16 v[16:19], v[214:217], v[194:197], v[40:43]
	v_mfma_f32_16x16x32_bf16 v[4:7], v[150:153], v[4:7], v[0:3]
	v_mfma_f32_16x16x32_bf16 v[0:3], v[226:229], v[194:197], v[140:143]
	v_mfma_f32_16x16x32_bf16 v[16:19], v[222:225], v[198:201], v[16:19]
	v_mfma_f32_16x16x32_bf16 v[0:3], v[150:153], v[198:201], v[0:3]
	s_setprio 0
	s_setprio 1
	v_mfma_f32_16x16x32_bf16 v[24:27], v[166:169], v[210:213], v[24:27]
	v_mfma_f32_16x16x32_bf16 v[56:59], v[174:177], v[154:157], v[24:27]
	v_mfma_f32_16x16x32_bf16 v[24:27], v[178:181], v[170:173], v[158:161]
	v_mfma_f32_16x16x32_bf16 v[44:47], v[182:185], v[206:209], v[24:27]
	v_mfma_f32_16x16x32_bf16 v[24:27], v[178:181], v[210:213], v[162:165]
	v_mfma_f32_16x16x32_bf16 v[8:11], v[214:217], v[210:213], v[8:11]
	v_mfma_f32_16x16x32_bf16 v[28:31], v[166:169], v[170:173], v[28:31]
	v_mfma_f32_16x16x32_bf16 v[40:43], v[182:185], v[154:157], v[24:27]
	v_mfma_f32_16x16x32_bf16 v[12:15], v[214:217], v[170:173], v[12:15]
	v_mfma_f32_16x16x32_bf16 v[24:27], v[222:225], v[154:157], v[8:11]
	v_mfma_f32_16x16x32_bf16 v[8:11], v[226:229], v[170:173], v[186:189]
	v_mfma_f32_16x16x32_bf16 v[60:63], v[174:177], v[206:209], v[28:31]
	v_mfma_f32_16x16x32_bf16 v[28:31], v[222:225], v[206:209], v[12:15]
	v_mfma_f32_16x16x32_bf16 v[12:15], v[150:153], v[206:209], v[8:11]
	v_mfma_f32_16x16x32_bf16 v[8:11], v[226:229], v[210:213], v[190:193]
	v_mfma_f32_16x16x32_bf16 v[8:11], v[150:153], v[154:157], v[8:11]
	s_setprio 0
	v_cmp_gt_u32_e32 vcc, s81, v144
	s_barrier
	s_and_saveexec_b64 s[54:55], vcc
	s_cbranch_execz .LBB0_859
	s_barrier

; #define STAGE(P, BASE, kt) do { const char* _g = (const char*)(BASE) + (size_t)((kt) * (BK * 2)); \
;     __builtin_amdgcn_global_load_lds((const unsigned*)(_g + (size_t)goff0), (unsigned*)((char*)(P) + tid_ * 16), 16, 0, 0); \
;     __builtin_amdgcn_global_load_lds((const unsigned*)(_g + (size_t)goff1), (unsigned*)((char*)(P) + tid_ * 16 + 8192), 16, 0, 0); } while (0)
; #define STAGEA(P, BASE, kt) do { const char* _g = (const char*)(BASE) + (size_t)((kt) * a_kbytes); \
;     __builtin_amdgcn_global_load_lds((const unsigned*)(_g + (size_t)goffA0), (unsigned*)((char*)(P) + tid_ * 16), 16, 0, 0); \
;     __builtin_amdgcn_global_load_lds((const unsigned*)(_g + (size_t)goffA1), (unsigned*)((char*)(P) + tid_ * 16 + 8192), 16, 0, 0); } while (0)
; #define LDA(dst, b, h) for (int m = 0; m < 4; ++m) for (int k = 0; k < 2; ++k) \
;     dst[m][k] = *reinterpret_cast<const bf16x8*>((char*)SA(b, h) + lds_byte(wr * 64 + m * 16 + fr, k * 32 + fq * 8))
; #define LDB(dst, b, h) for (int n = 0; n < 2; ++n) for (int k = 0; k < 2; ++k) \
;     dst[n][k] = *reinterpret_cast<const bf16x8*>((char*)SB(b, h) + lds_byte(wc * 32 + n * 16 + fr, k * 32 + fq * 8))
; #define MMA(ai, bj, At, Bt) do { __builtin_amdgcn_s_setprio(1); \
;     for (int m = 0; m < 4; ++m) for (int n = 0; n < 2; ++n) for (int k = 0; k < 2; ++k) \
;       acc[ai][bj][m][n] = __builtin_amdgcn_mfma_f32_16x16x32_bf16(At[m][k], Bt[n][k], acc[ai][bj][m][n], 0, 0, 0); \
;     __builtin_amdgcn_s_setprio(0); } while (0)
; #define WAIT_L(n) asm volatile("s_waitcnt lgkmcnt(" #n ")" ::: "memory")
; #define BAR __builtin_amdgcn_s_barrier()
; #define SCHED __builtin_amdgcn_sched_barrier(0)
; template <int EPI> ...
;     ...
;   for (int t = 0; t < nt - 2; t += 2) {
;     LDB(B0, 0, 0); SCHED; LDA(At, 0, 0); STAGEA(SA(1, 1), A1, t + 1);
;     WAIT_L(8); BAR; WAIT_L(0); MMA(0, 0, At, B0); BAR; SCHED;
;     LDB(B1, 0, 1); STAGE(SB(0, 0), B0p, t + 2);
;     BAR; WAIT_L(0); MMA(0, 1, At, B1); BAR;
;     LDA(At, 0, 1); STAGEA(SA(0, 0), A0, t + 2);
;     BAR; WAIT_L(0); MMA(1, 0, At, B0); BAR; SCHED;
.LBB0_1382:
	ds_read_b128 v[174:177], v171
	ds_read_b128 v[178:181], v171 offset:1024
	ds_read_b128 v[182:185], v171 offset:2048
	ds_read_b128 v[186:189], v171 offset:3072
	v_add_u32_e32 v172, 0xc000, v158
	v_lshl_add_u64 v[238:239], s[38:39], 0, v[140:141]
	v_readfirstlane_b32 s40, v172
	v_add_u32_e32 v173, 0xe000, v158
	v_lshl_add_u64 v[222:223], v[238:239], 0, s[4:5]
	s_mov_b32 m0, s40
	v_lshl_add_u64 v[240:241], s[38:39], 0, v[142:143]
	v_readfirstlane_b32 s40, v173
	ds_read_b128 v[190:193], v153
	ds_read_b128 v[194:197], v153 offset:1024
	ds_read_b128 v[198:201], v152
	ds_read_b128 v[202:205], v152 offset:1024
	ds_read_b128 v[206:209], v151
	ds_read_b128 v[210:213], v151 offset:1024
	ds_read_b128 v[214:217], v150
	ds_read_b128 v[218:221], v150 offset:1024
	global_load_lds_dwordx4 v[222:223], off
	v_lshl_add_u64 v[222:223], v[240:241], 0, s[4:5]
	s_mov_b32 m0, s40
	s_nop 0
	global_load_lds_dwordx4 v[222:223], off
	s_waitcnt lgkmcnt(8)
	s_barrier
	s_waitcnt lgkmcnt(0)
	s_setprio 1
	v_mfma_f32_16x16x32_bf16 v[124:127], v[190:193], v[174:177], v[124:127]
	v_mfma_f32_16x16x32_bf16 v[120:123], v[190:193], v[182:185], v[120:123]
	v_mfma_f32_16x16x32_bf16 v[116:119], v[198:201], v[174:177], v[116:119]
	v_mfma_f32_16x16x32_bf16 v[112:115], v[198:201], v[182:185], v[112:115]
	v_mfma_f32_16x16x32_bf16 v[108:111], v[206:209], v[174:177], v[108:111]
	v_mfma_f32_16x16x32_bf16 v[104:107], v[206:209], v[182:185], v[104:107]
	v_mfma_f32_16x16x32_bf16 v[100:103], v[214:217], v[174:177], v[100:103]
	v_mfma_f32_16x16x32_bf16 v[96:99], v[214:217], v[182:185], v[96:99]
	v_mfma_f32_16x16x32_bf16 v[124:127], v[194:197], v[178:181], v[124:127]
	v_mfma_f32_16x16x32_bf16 v[120:123], v[194:197], v[186:189], v[120:123]
	v_mfma_f32_16x16x32_bf16 v[116:119], v[202:205], v[178:181], v[116:119]
	v_mfma_f32_16x16x32_bf16 v[112:115], v[202:205], v[186:189], v[112:115]
	v_mfma_f32_16x16x32_bf16 v[108:111], v[210:213], v[178:181], v[108:111]
	v_mfma_f32_16x16x32_bf16 v[104:107], v[210:213], v[186:189], v[104:107]
	v_mfma_f32_16x16x32_bf16 v[100:103], v[218:221], v[178:181], v[100:103]
	v_mfma_f32_16x16x32_bf16 v[96:99], v[218:221], v[186:189], v[96:99]
	s_setprio 0
	s_barrier
	v_lshl_add_u64 v[242:243], s[38:39], 0, v[136:137]
	v_readfirstlane_b32 s40, v155
	v_lshl_add_u64 v[244:245], v[242:243], 0, s[6:7]
	s_mov_b32 m0, s40
	ds_read_b128 v[222:225], v168
	ds_read_b128 v[226:229], v168 offset:1024
	ds_read_b128 v[230:233], v168 offset:2048
	ds_read_b128 v[234:237], v168 offset:3072
	global_load_lds_dwordx4 v[244:245], off
	v_lshl_add_u64 v[244:245], s[38:39], 0, v[138:139]
	v_readfirstlane_b32 s40, v156
	v_lshl_add_u64 v[246:247], v[244:245], 0, s[6:7]
	s_mov_b32 m0, s40
	s_nop 0
	global_load_lds_dwordx4 v[246:247], off
	s_barrier
	s_waitcnt lgkmcnt(0)
	s_setprio 1
	v_mfma_f32_16x16x32_bf16 v[92:95], v[190:193], v[222:225], v[92:95]
	v_mfma_f32_16x16x32_bf16 v[88:91], v[190:193], v[230:233], v[88:91]
	v_mfma_f32_16x16x32_bf16 v[84:87], v[198:201], v[222:225], v[84:87]
	v_mfma_f32_16x16x32_bf16 v[80:83], v[198:201], v[230:233], v[80:83]
	v_mfma_f32_16x16x32_bf16 v[76:79], v[206:209], v[222:225], v[76:79]
	v_mfma_f32_16x16x32_bf16 v[72:75], v[206:209], v[230:233], v[72:75]
	v_mfma_f32_16x16x32_bf16 v[68:71], v[214:217], v[222:225], v[68:71]
	v_mfma_f32_16x16x32_bf16 v[64:67], v[214:217], v[230:233], v[64:67]
	v_mfma_f32_16x16x32_bf16 v[92:95], v[194:197], v[226:229], v[92:95]
	v_mfma_f32_16x16x32_bf16 v[88:91], v[194:197], v[234:237], v[88:91]
	v_mfma_f32_16x16x32_bf16 v[84:87], v[202:205], v[226:229], v[84:87]
	v_mfma_f32_16x16x32_bf16 v[80:83], v[202:205], v[234:237], v[80:83]
	v_mfma_f32_16x16x32_bf16 v[76:79], v[210:213], v[226:229], v[76:79]
	v_mfma_f32_16x16x32_bf16 v[72:75], v[210:213], v[234:237], v[72:75]
	v_mfma_f32_16x16x32_bf16 v[68:71], v[218:221], v[226:229], v[68:71]
	v_mfma_f32_16x16x32_bf16 v[64:67], v[218:221], v[234:237], v[64:67]
	s_setprio 0
	v_readfirstlane_b32 s40, v158
	v_lshl_add_u64 v[246:247], v[238:239], 0, s[8:9]
	s_mov_b32 m0, s40
	v_readfirstlane_b32 s40, v159
	s_barrier
	ds_read_b128 v[190:193], v153 offset:16384
	ds_read_b128 v[194:197], v153 offset:17408
	ds_read_b128 v[198:201], v152 offset:16384
	ds_read_b128 v[202:205], v152 offset:17408
	ds_read_b128 v[206:209], v151 offset:16384
	ds_read_b128 v[210:213], v151 offset:17408
	ds_read_b128 v[214:217], v150 offset:16384
	ds_read_b128 v[218:221], v150 offset:17408
	global_load_lds_dwordx4 v[246:247], off
	v_lshl_add_u64 v[246:247], v[240:241], 0, s[8:9]
	s_mov_b32 m0, s40
	s_nop 0
	global_load_lds_dwordx4 v[246:247], off
	s_barrier
	s_waitcnt lgkmcnt(0)
	s_setprio 1
	v_mfma_f32_16x16x32_bf16 v[60:63], v[190:193], v[174:177], v[60:63]
	v_mfma_f32_16x16x32_bf16 v[56:59], v[190:193], v[182:185], v[56:59]
	v_mfma_f32_16x16x32_bf16 v[52:55], v[198:201], v[174:177], v[52:55]
	v_mfma_f32_16x16x32_bf16 v[48:51], v[198:201], v[182:185], v[48:51]
	v_mfma_f32_16x16x32_bf16 v[44:47], v[206:209], v[174:177], v[44:47]
	v_mfma_f32_16x16x32_bf16 v[40:43], v[206:209], v[182:185], v[40:43]
	v_mfma_f32_16x16x32_bf16 v[36:39], v[214:217], v[174:177], v[36:39]
	v_mfma_f32_16x16x32_bf16 v[32:35], v[214:217], v[182:185], v[32:35]
	v_mfma_f32_16x16x32_bf16 v[60:63], v[194:197], v[178:181], v[60:63]
	v_mfma_f32_16x16x32_bf16 v[56:59], v[194:197], v[186:189], v[56:59]
	v_mfma_f32_16x16x32_bf16 v[52:55], v[202:205], v[178:181], v[52:55]
	v_mfma_f32_16x16x32_bf16 v[48:51], v[202:205], v[186:189], v[48:51]
	v_mfma_f32_16x16x32_bf16 v[44:47], v[210:213], v[178:181], v[44:47]
	v_mfma_f32_16x16x32_bf16 v[40:43], v[210:213], v[186:189], v[40:43]
	v_mfma_f32_16x16x32_bf16 v[36:39], v[218:221], v[178:181], v[36:39]
	v_mfma_f32_16x16x32_bf16 v[32:35], v[218:221], v[186:189], v[32:35]
	s_setprio 0
	s_barrier
; #define STAGE(P, BASE, kt) do { const char* _g = (const char*)(BASE) + (size_t)((kt) * (BK * 2)); \
;     __builtin_amdgcn_global_load_lds((const unsigned*)(_g + (size_t)goff0), (unsigned*)((char*)(P) + tid_ * 16), 16, 0, 0); \
;     __builtin_amdgcn_global_load_lds((const unsigned*)(_g + (size_t)goff1), (unsigned*)((char*)(P) + tid_ * 16 + 8192), 16, 0, 0); } while (0)
; #define STAGEA(P, BASE, kt) do { const char* _g = (const char*)(BASE) + (size_t)((kt) * a_kbytes); \
;     __builtin_amdgcn_global_load_lds((const unsigned*)(_g + (size_t)goffA0), (unsigned*)((char*)(P) + tid_ * 16), 16, 0, 0); \
;     __builtin_amdgcn_global_load_lds((const unsigned*)(_g + (size_t)goffA1), (unsigned*)((char*)(P) + tid_ * 16 + 8192), 16, 0, 0); } while (0)
; #define LDA(dst, b, h) for (int m = 0; m < 4; ++m) for (int k = 0; k < 2; ++k) \
;     dst[m][k] = *reinterpret_cast<const bf16x8*>((char*)SA(b, h) + lds_byte(wr * 64 + m * 16 + fr, k * 32 + fq * 8))
; #define LDB(dst, b, h) for (int n = 0; n < 2; ++n) for (int k = 0; k < 2; ++k) \
;     dst[n][k] = *reinterpret_cast<const bf16x8*>((char*)SB(b, h) + lds_byte(wc * 32 + n * 16 + fr, k * 32 + fq * 8))
; #define MMA(ai, bj, At, Bt) do { __builtin_amdgcn_s_setprio(1); \
;     for (int m = 0; m < 4; ++m) for (int n = 0; n < 2; ++n) for (int k = 0; k < 2; ++k) \
;       acc[ai][bj][m][n] = __builtin_amdgcn_mfma_f32_16x16x32_bf16(At[m][k], Bt[n][k], acc[ai][bj][m][n], 0, 0, 0); \
;     __builtin_amdgcn_s_setprio(0); } while (0)
; #define WAIT_V(n) asm volatile("s_waitcnt vmcnt(" #n ")" ::: "memory")
; #define WAIT_L(n) asm volatile("s_waitcnt lgkmcnt(" #n ")" ::: "memory")
; #define BAR __builtin_amdgcn_s_barrier()
; #define SCHED __builtin_amdgcn_sched_barrier(0)
; template <int EPI> ...
;     ...
;     STAGE(SB(0, 1), B1p, t + 2);
;     WAIT_V(6); BAR; MMA(1, 1, At, B1); BAR;
;     LDB(B0, 1, 0); SCHED; LDA(At, 1, 0); STAGEA(SA(0, 1), A1, t + 2);
;     WAIT_L(8); BAR; WAIT_L(0); MMA(0, 0, At, B0); BAR; SCHED;
;     LDB(B1, 1, 1); STAGE(SB(1, 0), B0p, t + 3);
;     BAR; WAIT_L(0); MMA(0, 1, At, B1); BAR;
;     LDA(At, 1, 1); STAGEA(SA(1, 0), A0, t + 3);
;     BAR; WAIT_L(0); MMA(1, 0, At, B0); BAR; SCHED;
	v_readfirstlane_b32 s40, v160
	v_lshl_add_u64 v[174:175], v[242:243], 0, s[10:11]
	s_mov_b32 m0, s40
	v_readfirstlane_b32 s40, v161
	global_load_lds_dwordx4 v[174:175], off
	v_lshl_add_u64 v[174:175], v[244:245], 0, s[10:11]
	s_mov_b32 m0, s40
	s_nop 0
	global_load_lds_dwordx4 v[174:175], off
	s_waitcnt vmcnt(6)
	s_barrier
	s_setprio 1
	v_mfma_f32_16x16x32_bf16 v[28:31], v[190:193], v[222:225], v[28:31]
	v_mfma_f32_16x16x32_bf16 v[24:27], v[190:193], v[230:233], v[24:27]
	v_mfma_f32_16x16x32_bf16 v[20:23], v[198:201], v[222:225], v[20:23]
	v_mfma_f32_16x16x32_bf16 v[16:19], v[198:201], v[230:233], v[16:19]
	v_mfma_f32_16x16x32_bf16 v[12:15], v[206:209], v[222:225], v[12:15]
	v_mfma_f32_16x16x32_bf16 v[8:11], v[206:209], v[230:233], v[8:11]
	v_mfma_f32_16x16x32_bf16 v[4:7], v[214:217], v[222:225], v[4:7]
	v_mfma_f32_16x16x32_bf16 v[0:3], v[214:217], v[230:233], v[0:3]
	v_mfma_f32_16x16x32_bf16 v[28:31], v[194:197], v[226:229], v[28:31]
	v_mfma_f32_16x16x32_bf16 v[24:27], v[194:197], v[234:237], v[24:27]
	v_mfma_f32_16x16x32_bf16 v[20:23], v[202:205], v[226:229], v[20:23]
	v_mfma_f32_16x16x32_bf16 v[16:19], v[202:205], v[234:237], v[16:19]
	v_mfma_f32_16x16x32_bf16 v[12:15], v[210:213], v[226:229], v[12:15]
	v_mfma_f32_16x16x32_bf16 v[8:11], v[210:213], v[234:237], v[8:11]
	v_mfma_f32_16x16x32_bf16 v[4:7], v[218:221], v[226:229], v[4:7]
	v_mfma_f32_16x16x32_bf16 v[0:3], v[218:221], v[234:237], v[0:3]
	s_setprio 0
	s_barrier
	ds_read_b128 v[174:177], v157
	ds_read_b128 v[178:181], v157 offset:1024
	ds_read_b128 v[182:185], v157 offset:2048
	ds_read_b128 v[186:189], v157 offset:3072
	v_readfirstlane_b32 s40, v162
	v_lshl_add_u64 v[222:223], v[238:239], 0, s[12:13]
	s_mov_b32 m0, s40
	v_readfirstlane_b32 s40, v163
	ds_read_b128 v[190:193], v153 offset:32768
	ds_read_b128 v[194:197], v153 offset:33792
	ds_read_b128 v[198:201], v152 offset:32768
	ds_read_b128 v[202:205], v152 offset:33792
	ds_read_b128 v[206:209], v151 offset:32768
	ds_read_b128 v[210:213], v151 offset:33792
	ds_read_b128 v[214:217], v150 offset:32768
	ds_read_b128 v[218:221], v150 offset:33792
	global_load_lds_dwordx4 v[222:223], off
	v_lshl_add_u64 v[222:223], v[240:241], 0, s[12:13]
	s_mov_b32 m0, s40
	s_nop 0
	global_load_lds_dwordx4 v[222:223], off
	s_waitcnt lgkmcnt(8)
	s_barrier
	s_waitcnt lgkmcnt(0)
	s_setprio 1
	v_mfma_f32_16x16x32_bf16 v[124:127], v[190:193], v[174:177], v[124:127]
	v_mfma_f32_16x16x32_bf16 v[120:123], v[190:193], v[182:185], v[120:123]
	v_mfma_f32_16x16x32_bf16 v[116:119], v[198:201], v[174:177], v[116:119]
	v_mfma_f32_16x16x32_bf16 v[112:115], v[198:201], v[182:185], v[112:115]
	v_mfma_f32_16x16x32_bf16 v[108:111], v[206:209], v[174:177], v[108:111]
	v_mfma_f32_16x16x32_bf16 v[104:107], v[206:209], v[182:185], v[104:107]
	v_mfma_f32_16x16x32_bf16 v[100:103], v[214:217], v[174:177], v[100:103]
	v_mfma_f32_16x16x32_bf16 v[96:99], v[214:217], v[182:185], v[96:99]
	v_mfma_f32_16x16x32_bf16 v[124:127], v[194:197], v[178:181], v[124:127]
	v_mfma_f32_16x16x32_bf16 v[120:123], v[194:197], v[186:189], v[120:123]
	v_mfma_f32_16x16x32_bf16 v[116:119], v[202:205], v[178:181], v[116:119]
	v_mfma_f32_16x16x32_bf16 v[112:115], v[202:205], v[186:189], v[112:115]
	v_mfma_f32_16x16x32_bf16 v[108:111], v[210:213], v[178:181], v[108:111]
	v_mfma_f32_16x16x32_bf16 v[104:107], v[210:213], v[186:189], v[104:107]
	v_mfma_f32_16x16x32_bf16 v[100:103], v[218:221], v[178:181], v[100:103]
	v_mfma_f32_16x16x32_bf16 v[96:99], v[218:221], v[186:189], v[96:99]
	s_setprio 0
	s_barrier
	v_readfirstlane_b32 s40, v164
	v_lshl_add_u64 v[246:247], v[242:243], 0, s[14:15]
	s_mov_b32 m0, s40
	v_readfirstlane_b32 s40, v165
	ds_read_b128 v[222:225], v154
	ds_read_b128 v[226:229], v154 offset:1024
	ds_read_b128 v[230:233], v154 offset:2048
	ds_read_b128 v[234:237], v154 offset:3072
	global_load_lds_dwordx4 v[246:247], off
	v_lshl_add_u64 v[246:247], v[244:245], 0, s[14:15]
	s_mov_b32 m0, s40
	s_nop 0
	global_load_lds_dwordx4 v[246:247], off
	s_barrier
	s_waitcnt lgkmcnt(0)
	s_setprio 1
	v_mfma_f32_16x16x32_bf16 v[92:95], v[190:193], v[222:225], v[92:95]
	v_mfma_f32_16x16x32_bf16 v[88:91], v[190:193], v[230:233], v[88:91]
	v_mfma_f32_16x16x32_bf16 v[84:87], v[198:201], v[222:225], v[84:87]
	v_mfma_f32_16x16x32_bf16 v[80:83], v[198:201], v[230:233], v[80:83]
	v_mfma_f32_16x16x32_bf16 v[76:79], v[206:209], v[222:225], v[76:79]
	v_mfma_f32_16x16x32_bf16 v[72:75], v[206:209], v[230:233], v[72:75]
	v_mfma_f32_16x16x32_bf16 v[68:71], v[214:217], v[222:225], v[68:71]
	v_mfma_f32_16x16x32_bf16 v[64:67], v[214:217], v[230:233], v[64:67]
	v_mfma_f32_16x16x32_bf16 v[92:95], v[194:197], v[226:229], v[92:95]
	v_mfma_f32_16x16x32_bf16 v[88:91], v[194:197], v[234:237], v[88:91]
	v_mfma_f32_16x16x32_bf16 v[84:87], v[202:205], v[226:229], v[84:87]
	v_mfma_f32_16x16x32_bf16 v[80:83], v[202:205], v[234:237], v[80:83]
	v_mfma_f32_16x16x32_bf16 v[76:79], v[210:213], v[226:229], v[76:79]
	v_mfma_f32_16x16x32_bf16 v[72:75], v[210:213], v[234:237], v[72:75]
	v_mfma_f32_16x16x32_bf16 v[68:71], v[218:221], v[226:229], v[68:71]
	v_mfma_f32_16x16x32_bf16 v[64:67], v[218:221], v[234:237], v[64:67]
	s_setprio 0
	v_readfirstlane_b32 s40, v166
	v_lshl_add_u64 v[238:239], v[238:239], 0, s[16:17]
	s_mov_b32 m0, s40
	v_readfirstlane_b32 s40, v167
	s_barrier
	ds_read_b128 v[190:193], v153 offset:49152
	ds_read_b128 v[194:197], v153 offset:50176
	ds_read_b128 v[198:201], v152 offset:49152
	ds_read_b128 v[202:205], v152 offset:50176
	ds_read_b128 v[206:209], v151 offset:49152
	ds_read_b128 v[210:213], v151 offset:50176
	ds_read_b128 v[214:217], v150 offset:49152
	ds_read_b128 v[218:221], v150 offset:50176
	global_load_lds_dwordx4 v[238:239], off
	v_lshl_add_u64 v[238:239], v[240:241], 0, s[16:17]
	s_mov_b32 m0, s40
	s_nop 0
	global_load_lds_dwordx4 v[238:239], off
	s_barrier
; #define STAGE(P, BASE, kt) do { const char* _g = (const char*)(BASE) + (size_t)((kt) * (BK * 2)); \
;     __builtin_amdgcn_global_load_lds((const unsigned*)(_g + (size_t)goff0), (unsigned*)((char*)(P) + tid_ * 16), 16, 0, 0); \
;     __builtin_amdgcn_global_load_lds((const unsigned*)(_g + (size_t)goff1), (unsigned*)((char*)(P) + tid_ * 16 + 8192), 16, 0, 0); } while (0)
; #define STAGEA(P, BASE, kt) do { const char* _g = (const char*)(BASE) + (size_t)((kt) * a_kbytes); \
;     __builtin_amdgcn_global_load_lds((const unsigned*)(_g + (size_t)goffA0), (unsigned*)((char*)(P) + tid_ * 16), 16, 0, 0); \
;     __builtin_amdgcn_global_load_lds((const unsigned*)(_g + (size_t)goffA1), (unsigned*)((char*)(P) + tid_ * 16 + 8192), 16, 0, 0); } while (0)
; #define LDA(dst, b, h) for (int m = 0; m < 4; ++m) for (int k = 0; k < 2; ++k) \
;     dst[m][k] = *reinterpret_cast<const bf16x8*>((char*)SA(b, h) + lds_byte(wr * 64 + m * 16 + fr, k * 32 + fq * 8))
; #define LDB(dst, b, h) for (int n = 0; n < 2; ++n) for (int k = 0; k < 2; ++k) \
;     dst[n][k] = *reinterpret_cast<const bf16x8*>((char*)SB(b, h) + lds_byte(wc * 32 + n * 16 + fr, k * 32 + fq * 8))
; #define MMA(ai, bj, At, Bt) do { __builtin_amdgcn_s_setprio(1); \
;     for (int m = 0; m < 4; ++m) for (int n = 0; n < 2; ++n) for (int k = 0; k < 2; ++k) \
;       acc[ai][bj][m][n] = __builtin_amdgcn_mfma_f32_16x16x32_bf16(At[m][k], Bt[n][k], acc[ai][bj][m][n], 0, 0, 0); \
;     __builtin_amdgcn_s_setprio(0); } while (0)
; #define WAIT_V(n) asm volatile("s_waitcnt vmcnt(" #n ")" ::: "memory")
; #define WAIT_L(n) asm volatile("s_waitcnt lgkmcnt(" #n ")" ::: "memory")
; #define BAR __builtin_amdgcn_s_barrier()
; #define SCHED __builtin_amdgcn_sched_barrier(0)
; template <int EPI> ...
;     ...
;     WAIT_L(8); BAR; WAIT_L(0); MMA(0, 0, At, B0); BAR; SCHED;
;     LDB(B1, 1, 1); STAGE(SB(1, 0), B0p, t + 3);
;     BAR; WAIT_L(0); MMA(0, 1, At, B1); BAR;
;     LDA(At, 1, 1); STAGEA(SA(1, 0), A0, t + 3);
;     BAR; WAIT_L(0); MMA(1, 0, At, B0); BAR; SCHED;
;     STAGE(SB(1, 1), B1p, t + 3);
;     WAIT_V(6); BAR; MMA(1, 1, At, B1); BAR;
;   }
;   { LDB(B0, 0, 0); LDA(At, 0, 0); STAGEA(SA(1, 1), A1, nt - 1);
;     BAR; WAIT_L(0); MMA(0, 0, At, B0); BAR;
;     LDB(B1, 0, 1); BAR; WAIT_L(0); MMA(0, 1, At, B1); BAR;
	s_waitcnt lgkmcnt(0)
	s_setprio 1
	v_mfma_f32_16x16x32_bf16 v[60:63], v[190:193], v[174:177], v[60:63]
	v_mfma_f32_16x16x32_bf16 v[56:59], v[190:193], v[182:185], v[56:59]
	v_mfma_f32_16x16x32_bf16 v[52:55], v[198:201], v[174:177], v[52:55]
	v_mfma_f32_16x16x32_bf16 v[48:51], v[198:201], v[182:185], v[48:51]
	v_mfma_f32_16x16x32_bf16 v[44:47], v[206:209], v[174:177], v[44:47]
	v_mfma_f32_16x16x32_bf16 v[40:43], v[206:209], v[182:185], v[40:43]
	v_mfma_f32_16x16x32_bf16 v[36:39], v[214:217], v[174:177], v[36:39]
	v_mfma_f32_16x16x32_bf16 v[32:35], v[214:217], v[182:185], v[32:35]
	v_mfma_f32_16x16x32_bf16 v[60:63], v[194:197], v[178:181], v[60:63]
	v_mfma_f32_16x16x32_bf16 v[56:59], v[194:197], v[186:189], v[56:59]
	v_mfma_f32_16x16x32_bf16 v[52:55], v[202:205], v[178:181], v[52:55]
	v_mfma_f32_16x16x32_bf16 v[48:51], v[202:205], v[186:189], v[48:51]
	v_mfma_f32_16x16x32_bf16 v[44:47], v[210:213], v[178:181], v[44:47]
	v_mfma_f32_16x16x32_bf16 v[40:43], v[210:213], v[186:189], v[40:43]
	v_mfma_f32_16x16x32_bf16 v[36:39], v[218:221], v[178:181], v[36:39]
	v_mfma_f32_16x16x32_bf16 v[32:35], v[218:221], v[186:189], v[32:35]
	s_setprio 0
	s_barrier
	v_readfirstlane_b32 s40, v169
	v_lshl_add_u64 v[174:175], v[242:243], 0, s[18:19]
	s_mov_b32 m0, s40
	v_readfirstlane_b32 s40, v170
	global_load_lds_dwordx4 v[174:175], off
	v_lshl_add_u64 v[174:175], v[244:245], 0, s[18:19]
	s_mov_b32 m0, s40
	s_nop 0
	global_load_lds_dwordx4 v[174:175], off
	s_waitcnt vmcnt(6)
	s_barrier
	s_setprio 1
	v_mfma_f32_16x16x32_bf16 v[28:31], v[190:193], v[222:225], v[28:31]
	v_mfma_f32_16x16x32_bf16 v[24:27], v[190:193], v[230:233], v[24:27]
	v_mfma_f32_16x16x32_bf16 v[20:23], v[198:201], v[222:225], v[20:23]
	v_mfma_f32_16x16x32_bf16 v[16:19], v[198:201], v[230:233], v[16:19]
	v_mfma_f32_16x16x32_bf16 v[12:15], v[206:209], v[222:225], v[12:15]
	v_mfma_f32_16x16x32_bf16 v[8:11], v[206:209], v[230:233], v[8:11]
	v_mfma_f32_16x16x32_bf16 v[4:7], v[214:217], v[222:225], v[4:7]
	v_mfma_f32_16x16x32_bf16 v[0:3], v[214:217], v[230:233], v[0:3]
	v_mfma_f32_16x16x32_bf16 v[28:31], v[194:197], v[226:229], v[28:31]
	v_mfma_f32_16x16x32_bf16 v[24:27], v[194:197], v[234:237], v[24:27]
	v_mfma_f32_16x16x32_bf16 v[20:23], v[202:205], v[226:229], v[20:23]
	v_mfma_f32_16x16x32_bf16 v[16:19], v[202:205], v[234:237], v[16:19]
	v_mfma_f32_16x16x32_bf16 v[12:15], v[210:213], v[226:229], v[12:15]
	v_mfma_f32_16x16x32_bf16 v[8:11], v[210:213], v[234:237], v[8:11]
	v_mfma_f32_16x16x32_bf16 v[4:7], v[218:221], v[226:229], v[4:7]
	v_mfma_f32_16x16x32_bf16 v[0:3], v[218:221], v[234:237], v[0:3]
	s_setprio 0
	s_add_i32 s23, s23, 2
	s_add_u32 s38, s38, 0x100
	s_addc_u32 s39, s39, 0
	s_cmp_lt_u32 s23, 28
	s_barrier
	s_cbranch_scc1 .LBB0_1382
	s_add_u32 s36, s36, 0x80f80
	s_addc_u32 s37, s37, 0
	v_readfirstlane_b32 s23, v172
	v_lshl_add_u64 v[166:167], s[36:37], 0, v[130:131]
	s_mov_b32 m0, s23
	v_readfirstlane_b32 s23, v173
	ds_read_b128 v[136:139], v171
	ds_read_b128 v[140:143], v171 offset:1024
	ds_read_b128 v[158:161], v171 offset:2048
	ds_read_b128 v[162:165], v171 offset:3072
	ds_read_b128 v[174:177], v153
	ds_read_b128 v[178:181], v153 offset:1024
	ds_read_b128 v[182:185], v152
	ds_read_b128 v[186:189], v152 offset:1024
	ds_read_b128 v[190:193], v151
	ds_read_b128 v[194:197], v151 offset:1024
	ds_read_b128 v[198:201], v150
	ds_read_b128 v[202:205], v150 offset:1024
	global_load_lds_dwordx4 v[166:167], off
	v_lshl_add_u64 v[166:167], s[36:37], 0, v[128:129]
	s_mov_b32 m0, s23
	s_nop 0
	global_load_lds_dwordx4 v[166:167], off
	s_barrier
	s_waitcnt lgkmcnt(0)
	s_setprio 1
	v_mfma_f32_16x16x32_bf16 v[124:127], v[174:177], v[136:139], v[124:127]
	v_mfma_f32_16x16x32_bf16 v[120:123], v[174:177], v[158:161], v[120:123]
	v_mfma_f32_16x16x32_bf16 v[108:111], v[190:193], v[136:139], v[108:111]
	v_mfma_f32_16x16x32_bf16 v[104:107], v[190:193], v[158:161], v[104:107]
	v_mfma_f32_16x16x32_bf16 v[124:127], v[178:181], v[140:143], v[124:127]
	v_mfma_f32_16x16x32_bf16 v[120:123], v[178:181], v[162:165], v[120:123]
	v_mfma_f32_16x16x32_bf16 v[116:119], v[182:185], v[136:139], v[116:119]
	v_mfma_f32_16x16x32_bf16 v[112:115], v[182:185], v[158:161], v[112:115]
	v_mfma_f32_16x16x32_bf16 v[108:111], v[194:197], v[140:143], v[108:111]
	v_mfma_f32_16x16x32_bf16 v[104:107], v[194:197], v[162:165], v[104:107]
	v_mfma_f32_16x16x32_bf16 v[100:103], v[198:201], v[136:139], v[100:103]
	v_mfma_f32_16x16x32_bf16 v[96:99], v[198:201], v[158:161], v[96:99]
	v_mfma_f32_16x16x32_bf16 v[170:173], v[186:189], v[140:143], v[116:119]
	v_mfma_f32_16x16x32_bf16 v[206:209], v[186:189], v[162:165], v[112:115]
	v_mfma_f32_16x16x32_bf16 v[210:213], v[202:205], v[140:143], v[100:103]
	v_mfma_f32_16x16x32_bf16 v[214:217], v[202:205], v[162:165], v[96:99]
	s_setprio 0
	s_barrier
	s_nop 1
	ds_read_b128 v[96:99], v168
	ds_read_b128 v[100:103], v168 offset:1024
	ds_read_b128 v[112:115], v168 offset:2048
	ds_read_b128 v[116:119], v168 offset:3072
	s_barrier
	s_waitcnt lgkmcnt(0)
	s_setprio 1
	v_mfma_f32_16x16x32_bf16 v[92:95], v[174:177], v[96:99], v[92:95]
	v_mfma_f32_16x16x32_bf16 v[88:91], v[174:177], v[112:115], v[88:91]
	v_mfma_f32_16x16x32_bf16 v[76:79], v[190:193], v[96:99], v[76:79]
	v_mfma_f32_16x16x32_bf16 v[72:75], v[190:193], v[112:115], v[72:75]
	v_mfma_f32_16x16x32_bf16 v[92:95], v[178:181], v[100:103], v[92:95]
	v_mfma_f32_16x16x32_bf16 v[88:91], v[178:181], v[116:119], v[88:91]
	v_mfma_f32_16x16x32_bf16 v[84:87], v[182:185], v[96:99], v[84:87]
	v_mfma_f32_16x16x32_bf16 v[80:83], v[182:185], v[112:115], v[80:83]
	v_mfma_f32_16x16x32_bf16 v[76:79], v[194:197], v[100:103], v[76:79]
	v_mfma_f32_16x16x32_bf16 v[72:75], v[194:197], v[116:119], v[72:75]
	v_mfma_f32_16x16x32_bf16 v[68:71], v[198:201], v[96:99], v[68:71]
	v_mfma_f32_16x16x32_bf16 v[64:67], v[198:201], v[112:115], v[64:67]
	v_mfma_f32_16x16x32_bf16 v[166:169], v[186:189], v[100:103], v[84:87]
	v_mfma_f32_16x16x32_bf16 v[174:177], v[186:189], v[116:119], v[80:83]
	v_mfma_f32_16x16x32_bf16 v[178:181], v[202:205], v[100:103], v[68:71]
	v_mfma_f32_16x16x32_bf16 v[182:185], v[202:205], v[116:119], v[64:67]
	s_setprio 0
	s_barrier
; #define LDA(dst, b, h) for (int m = 0; m < 4; ++m) for (int k = 0; k < 2; ++k) \
;     dst[m][k] = *reinterpret_cast<const bf16x8*>((char*)SA(b, h) + lds_byte(wr * 64 + m * 16 + fr, k * 32 + fq * 8))
; #define LDB(dst, b, h) for (int n = 0; n < 2; ++n) for (int k = 0; k < 2; ++k) \
;     dst[n][k] = *reinterpret_cast<const bf16x8*>((char*)SB(b, h) + lds_byte(wc * 32 + n * 16 + fr, k * 32 + fq * 8))
; #define MMA(ai, bj, At, Bt) do { __builtin_amdgcn_s_setprio(1); \
;     for (int m = 0; m < 4; ++m) for (int n = 0; n < 2; ++n) for (int k = 0; k < 2; ++k) \
;       acc[ai][bj][m][n] = __builtin_amdgcn_mfma_f32_16x16x32_bf16(At[m][k], Bt[n][k], acc[ai][bj][m][n], 0, 0, 0); \
;     __builtin_amdgcn_s_setprio(0); } while (0)
; #define WAIT_V(n) asm volatile("s_waitcnt vmcnt(" #n ")" ::: "memory")
; #define WAIT_L(n) asm volatile("s_waitcnt lgkmcnt(" #n ")" ::: "memory")
; #define BAR __builtin_amdgcn_s_barrier()
; template <int EPI> ...
;     ...
;     LDA(At, 0, 1); WAIT_V(4); BAR; WAIT_L(0); MMA(1, 0, At, B0); MMA(1, 1, At, B1); BAR; }
;   { LDB(B0, 1, 0); LDA(At, 1, 0); WAIT_V(2); BAR; WAIT_L(0); MMA(0, 0, At, B0); BAR;
	s_nop 1
	ds_read_b128 v[64:67], v153 offset:16384
	ds_read_b128 v[68:71], v153 offset:17408
	ds_read_b128 v[80:83], v152 offset:16384
	ds_read_b128 v[84:87], v152 offset:17408
	ds_read_b128 v[186:189], v151 offset:16384
	ds_read_b128 v[190:193], v151 offset:17408
	ds_read_b128 v[194:197], v150 offset:16384
	ds_read_b128 v[198:201], v150 offset:17408
	s_waitcnt vmcnt(4)
	s_barrier
	s_waitcnt lgkmcnt(0)
	s_setprio 1
	v_mfma_f32_16x16x32_bf16 v[60:63], v[64:67], v[136:139], v[60:63]
	v_mfma_f32_16x16x32_bf16 v[56:59], v[64:67], v[158:161], v[56:59]
	v_mfma_f32_16x16x32_bf16 v[44:47], v[186:189], v[136:139], v[44:47]
	v_mfma_f32_16x16x32_bf16 v[40:43], v[186:189], v[158:161], v[40:43]
	v_mfma_f32_16x16x32_bf16 v[60:63], v[68:71], v[140:143], v[60:63]
	v_mfma_f32_16x16x32_bf16 v[56:59], v[68:71], v[162:165], v[56:59]
	v_mfma_f32_16x16x32_bf16 v[52:55], v[80:83], v[136:139], v[52:55]
	v_mfma_f32_16x16x32_bf16 v[48:51], v[80:83], v[158:161], v[48:51]
	v_mfma_f32_16x16x32_bf16 v[44:47], v[190:193], v[140:143], v[44:47]
	v_mfma_f32_16x16x32_bf16 v[40:43], v[190:193], v[162:165], v[40:43]
	v_mfma_f32_16x16x32_bf16 v[36:39], v[194:197], v[136:139], v[36:39]
	v_mfma_f32_16x16x32_bf16 v[32:35], v[194:197], v[158:161], v[32:35]
	v_mfma_f32_16x16x32_bf16 v[202:205], v[84:87], v[140:143], v[52:55]
	v_mfma_f32_16x16x32_bf16 v[218:221], v[84:87], v[162:165], v[48:51]
	v_mfma_f32_16x16x32_bf16 v[136:139], v[198:201], v[140:143], v[36:39]
	v_mfma_f32_16x16x32_bf16 v[140:143], v[198:201], v[162:165], v[32:35]
	s_setprio 0
	s_setprio 1
	v_mfma_f32_16x16x32_bf16 v[28:31], v[64:67], v[96:99], v[28:31]
	v_mfma_f32_16x16x32_bf16 v[24:27], v[64:67], v[112:115], v[24:27]
	v_mfma_f32_16x16x32_bf16 v[12:15], v[186:189], v[96:99], v[12:15]
	v_mfma_f32_16x16x32_bf16 v[8:11], v[186:189], v[112:115], v[8:11]
	v_mfma_f32_16x16x32_bf16 v[28:31], v[68:71], v[100:103], v[28:31]
	v_mfma_f32_16x16x32_bf16 v[24:27], v[68:71], v[116:119], v[24:27]
	v_mfma_f32_16x16x32_bf16 v[20:23], v[80:83], v[96:99], v[20:23]
	v_mfma_f32_16x16x32_bf16 v[16:19], v[80:83], v[112:115], v[16:19]
	v_mfma_f32_16x16x32_bf16 v[12:15], v[190:193], v[100:103], v[12:15]
	v_mfma_f32_16x16x32_bf16 v[8:11], v[190:193], v[116:119], v[8:11]
	v_mfma_f32_16x16x32_bf16 v[4:7], v[194:197], v[96:99], v[4:7]
	v_mfma_f32_16x16x32_bf16 v[0:3], v[194:197], v[112:115], v[0:3]
	v_mfma_f32_16x16x32_bf16 v[158:161], v[84:87], v[100:103], v[20:23]
	v_mfma_f32_16x16x32_bf16 v[162:165], v[84:87], v[116:119], v[16:19]
	v_mfma_f32_16x16x32_bf16 v[186:189], v[198:201], v[100:103], v[4:7]
	v_mfma_f32_16x16x32_bf16 v[190:193], v[198:201], v[116:119], v[0:3]
	s_setprio 0
	s_barrier
	s_nop 1
	ds_read_b128 v[0:3], v157
	ds_read_b128 v[4:7], v157 offset:1024
	ds_read_b128 v[194:197], v157 offset:2048
	ds_read_b128 v[198:201], v157 offset:3072
	ds_read_b128 v[16:19], v153 offset:32768
	ds_read_b128 v[20:23], v153 offset:33792
	ds_read_b128 v[32:35], v152 offset:32768
	ds_read_b128 v[36:39], v152 offset:33792
	ds_read_b128 v[48:51], v151 offset:32768
	ds_read_b128 v[52:55], v151 offset:33792
	ds_read_b128 v[222:225], v150 offset:32768
	ds_read_b128 v[226:229], v150 offset:33792
	s_waitcnt vmcnt(2)
	s_barrier
	s_waitcnt lgkmcnt(0)
	s_setprio 1
	v_mfma_f32_16x16x32_bf16 v[64:67], v[16:19], v[0:3], v[124:127]
	v_mfma_f32_16x16x32_bf16 v[116:119], v[20:23], v[4:7], v[64:67]
	v_mfma_f32_16x16x32_bf16 v[64:67], v[16:19], v[194:197], v[120:123]
	v_mfma_f32_16x16x32_bf16 v[112:115], v[20:23], v[198:201], v[64:67]
	v_mfma_f32_16x16x32_bf16 v[64:67], v[32:35], v[0:3], v[170:173]
	v_mfma_f32_16x16x32_bf16 v[100:103], v[36:39], v[4:7], v[64:67]
	v_mfma_f32_16x16x32_bf16 v[64:67], v[32:35], v[194:197], v[206:209]
	v_mfma_f32_16x16x32_bf16 v[96:99], v[36:39], v[198:201], v[64:67]
	v_mfma_f32_16x16x32_bf16 v[64:67], v[48:51], v[0:3], v[108:111]
	v_mfma_f32_16x16x32_bf16 v[84:87], v[52:55], v[4:7], v[64:67]
	v_mfma_f32_16x16x32_bf16 v[64:67], v[48:51], v[194:197], v[104:107]
	v_mfma_f32_16x16x32_bf16 v[80:83], v[52:55], v[198:201], v[64:67]
	v_mfma_f32_16x16x32_bf16 v[64:67], v[222:225], v[0:3], v[210:213]
	v_mfma_f32_16x16x32_bf16 v[68:71], v[226:229], v[4:7], v[64:67]
	v_mfma_f32_16x16x32_bf16 v[64:67], v[222:225], v[194:197], v[214:217]
	v_mfma_f32_16x16x32_bf16 v[64:67], v[226:229], v[198:201], v[64:67]
	s_setprio 0
	s_barrier
; #define LDA(dst, b, h) for (int m = 0; m < 4; ++m) for (int k = 0; k < 2; ++k) \
;     dst[m][k] = *reinterpret_cast<const bf16x8*>((char*)SA(b, h) + lds_byte(wr * 64 + m * 16 + fr, k * 32 + fq * 8))
; #define LDB(dst, b, h) for (int n = 0; n < 2; ++n) for (int k = 0; k < 2; ++k) \
;     dst[n][k] = *reinterpret_cast<const bf16x8*>((char*)SB(b, h) + lds_byte(wc * 32 + n * 16 + fr, k * 32 + fq * 8))
; #define MMA(ai, bj, At, Bt) do { __builtin_amdgcn_s_setprio(1); \
;     for (int m = 0; m < 4; ++m) for (int n = 0; n < 2; ++n) for (int k = 0; k < 2; ++k) \
;       acc[ai][bj][m][n] = __builtin_amdgcn_mfma_f32_16x16x32_bf16(At[m][k], Bt[n][k], acc[ai][bj][m][n], 0, 0, 0); \
;     __builtin_amdgcn_s_setprio(0); } while (0)
; #define WAIT_V(n) asm volatile("s_waitcnt vmcnt(" #n ")" ::: "memory")
; #define WAIT_L(n) asm volatile("s_waitcnt lgkmcnt(" #n ")" ::: "memory")
; #define BAR __builtin_amdgcn_s_barrier()
; template <int EPI> ...
;     ...
;   { LDB(B0, 1, 0); LDA(At, 1, 0); WAIT_V(2); BAR; WAIT_L(0); MMA(0, 0, At, B0); BAR;
;     LDB(B1, 1, 1); WAIT_V(0); BAR; WAIT_L(0); MMA(0, 1, At, B1); BAR;
;     LDA(At, 1, 1); BAR; WAIT_L(0); MMA(1, 0, At, B0); MMA(1, 1, At, B1); BAR; }
;   if (wr == 0) BAR;
	ds_read_b128 v[170:173], v154
	ds_read_b128 v[206:209], v154 offset:1024
	ds_read_b128 v[210:213], v154 offset:2048
	ds_read_b128 v[154:157], v154 offset:3072
	s_waitcnt vmcnt(0)
	s_barrier
	s_waitcnt lgkmcnt(0)
	s_setprio 1
	v_mfma_f32_16x16x32_bf16 v[92:95], v[16:19], v[170:173], v[92:95]
	v_mfma_f32_16x16x32_bf16 v[16:19], v[16:19], v[210:213], v[88:91]
	v_mfma_f32_16x16x32_bf16 v[120:123], v[20:23], v[154:157], v[16:19]
	v_mfma_f32_16x16x32_bf16 v[16:19], v[32:35], v[170:173], v[166:169]
	v_mfma_f32_16x16x32_bf16 v[108:111], v[36:39], v[206:209], v[16:19]
	v_mfma_f32_16x16x32_bf16 v[16:19], v[32:35], v[210:213], v[174:177]
	v_mfma_f32_16x16x32_bf16 v[104:107], v[36:39], v[154:157], v[16:19]
	v_mfma_f32_16x16x32_bf16 v[16:19], v[48:51], v[170:173], v[76:79]
	v_mfma_f32_16x16x32_bf16 v[124:127], v[20:23], v[206:209], v[92:95]
	v_mfma_f32_16x16x32_bf16 v[92:95], v[52:55], v[206:209], v[16:19]
	v_mfma_f32_16x16x32_bf16 v[16:19], v[48:51], v[210:213], v[72:75]
	v_mfma_f32_16x16x32_bf16 v[88:91], v[52:55], v[154:157], v[16:19]
	v_mfma_f32_16x16x32_bf16 v[16:19], v[222:225], v[170:173], v[178:181]
	v_mfma_f32_16x16x32_bf16 v[76:79], v[226:229], v[206:209], v[16:19]
	v_mfma_f32_16x16x32_bf16 v[16:19], v[222:225], v[210:213], v[182:185]
	v_mfma_f32_16x16x32_bf16 v[72:75], v[226:229], v[154:157], v[16:19]
	s_setprio 0
	s_barrier
	ds_read_b128 v[166:169], v153 offset:49152
	ds_read_b128 v[174:177], v153 offset:50176
	ds_read_b128 v[178:181], v152 offset:49152
	ds_read_b128 v[182:185], v152 offset:50176
	ds_read_b128 v[214:217], v151 offset:49152
	ds_read_b128 v[222:225], v151 offset:50176
	ds_read_b128 v[226:229], v150 offset:49152
	ds_read_b128 v[150:153], v150 offset:50176
	s_barrier
	s_waitcnt lgkmcnt(0)
	s_setprio 1
	v_mfma_f32_16x16x32_bf16 v[16:19], v[166:169], v[0:3], v[60:63]
	v_mfma_f32_16x16x32_bf16 v[52:55], v[174:177], v[4:7], v[16:19]
	v_mfma_f32_16x16x32_bf16 v[16:19], v[166:169], v[194:197], v[56:59]
	v_mfma_f32_16x16x32_bf16 v[48:51], v[174:177], v[198:201], v[16:19]
	v_mfma_f32_16x16x32_bf16 v[16:19], v[178:181], v[0:3], v[202:205]
	v_mfma_f32_16x16x32_bf16 v[36:39], v[182:185], v[4:7], v[16:19]
	v_mfma_f32_16x16x32_bf16 v[16:19], v[178:181], v[194:197], v[218:221]
	v_mfma_f32_16x16x32_bf16 v[32:35], v[182:185], v[198:201], v[16:19]
	v_mfma_f32_16x16x32_bf16 v[16:19], v[214:217], v[0:3], v[44:47]
	v_mfma_f32_16x16x32_bf16 v[0:3], v[226:229], v[0:3], v[136:139]
	v_mfma_f32_16x16x32_bf16 v[20:23], v[222:225], v[4:7], v[16:19]
	v_mfma_f32_16x16x32_bf16 v[16:19], v[214:217], v[194:197], v[40:43]
	v_mfma_f32_16x16x32_bf16 v[4:7], v[150:153], v[4:7], v[0:3]
	v_mfma_f32_16x16x32_bf16 v[0:3], v[226:229], v[194:197], v[140:143]
	v_mfma_f32_16x16x32_bf16 v[16:19], v[222:225], v[198:201], v[16:19]
	v_mfma_f32_16x16x32_bf16 v[0:3], v[150:153], v[198:201], v[0:3]
	s_setprio 0
	s_setprio 1
	v_mfma_f32_16x16x32_bf16 v[24:27], v[166:169], v[210:213], v[24:27]
	v_mfma_f32_16x16x32_bf16 v[56:59], v[174:177], v[154:157], v[24:27]
	v_mfma_f32_16x16x32_bf16 v[24:27], v[178:181], v[170:173], v[158:161]
	v_mfma_f32_16x16x32_bf16 v[44:47], v[182:185], v[206:209], v[24:27]
	v_mfma_f32_16x16x32_bf16 v[24:27], v[178:181], v[210:213], v[162:165]
	v_mfma_f32_16x16x32_bf16 v[8:11], v[214:217], v[210:213], v[8:11]
	v_mfma_f32_16x16x32_bf16 v[28:31], v[166:169], v[170:173], v[28:31]
	v_mfma_f32_16x16x32_bf16 v[40:43], v[182:185], v[154:157], v[24:27]
	v_mfma_f32_16x16x32_bf16 v[12:15], v[214:217], v[170:173], v[12:15]
	v_mfma_f32_16x16x32_bf16 v[24:27], v[222:225], v[154:157], v[8:11]
	v_mfma_f32_16x16x32_bf16 v[8:11], v[226:229], v[170:173], v[186:189]
	v_mfma_f32_16x16x32_bf16 v[60:63], v[174:177], v[206:209], v[28:31]
	v_mfma_f32_16x16x32_bf16 v[28:31], v[222:225], v[206:209], v[12:15]
	v_mfma_f32_16x16x32_bf16 v[12:15], v[150:153], v[206:209], v[8:11]
	v_mfma_f32_16x16x32_bf16 v[8:11], v[226:229], v[210:213], v[190:193]
	v_mfma_f32_16x16x32_bf16 v[8:11], v[150:153], v[154:157], v[8:11]
	s_setprio 0
	v_cmp_gt_u32_e32 vcc, s55, v144
	s_barrier
	s_and_saveexec_b64 s[36:37], vcc
	s_cbranch_execz .LBB0_1385
	s_barrier

; #define STAGE(P, BASE, kt) do { const char* _g = (const char*)(BASE) + (size_t)((kt) * (BK * 2)); \
;     __builtin_amdgcn_global_load_lds((const unsigned*)(_g + (size_t)goff0), (unsigned*)((char*)(P) + tid_ * 16), 16, 0, 0); \
;     __builtin_amdgcn_global_load_lds((const unsigned*)(_g + (size_t)goff1), (unsigned*)((char*)(P) + tid_ * 16 + 8192), 16, 0, 0); } while (0)
; #define STAGEA(P, BASE, kt) do { const char* _g = (const char*)(BASE) + (size_t)((kt) * a_kbytes); \
;     __builtin_amdgcn_global_load_lds((const unsigned*)(_g + (size_t)goffA0), (unsigned*)((char*)(P) + tid_ * 16), 16, 0, 0); \
;     __builtin_amdgcn_global_load_lds((const unsigned*)(_g + (size_t)goffA1), (unsigned*)((char*)(P) + tid_ * 16 + 8192), 16, 0, 0); } while (0)
; #define LDA(dst, b, h) for (int m = 0; m < 4; ++m) for (int k = 0; k < 2; ++k) \
;     dst[m][k] = *reinterpret_cast<const bf16x8*>((char*)SA(b, h) + lds_byte(wr * 64 + m * 16 + fr, k * 32 + fq * 8))
; #define LDB(dst, b, h) for (int n = 0; n < 2; ++n) for (int k = 0; k < 2; ++k) \
;     dst[n][k] = *reinterpret_cast<const bf16x8*>((char*)SB(b, h) + lds_byte(wc * 32 + n * 16 + fr, k * 32 + fq * 8))
; #define MMA(ai, bj, At, Bt) do { __builtin_amdgcn_s_setprio(1); \
;     for (int m = 0; m < 4; ++m) for (int n = 0; n < 2; ++n) for (int k = 0; k < 2; ++k) \
;       acc[ai][bj][m][n] = __builtin_amdgcn_mfma_f32_16x16x32_bf16(At[m][k], Bt[n][k], acc[ai][bj][m][n], 0, 0, 0); \
;     __builtin_amdgcn_s_setprio(0); } while (0)
; #define WAIT_L(n) asm volatile("s_waitcnt lgkmcnt(" #n ")" ::: "memory")
; #define BAR __builtin_amdgcn_s_barrier()
; #define SCHED __builtin_amdgcn_sched_barrier(0)
; template <int EPI> ...
;     ...
;   for (int t = 0; t < nt - 2; t += 2) {
;     LDB(B0, 0, 0); SCHED; LDA(At, 0, 0); STAGEA(SA(1, 1), A1, t + 1);
;     WAIT_L(8); BAR; WAIT_L(0); MMA(0, 0, At, B0); BAR; SCHED;
;     LDB(B1, 0, 1); STAGE(SB(0, 0), B0p, t + 2);
;     BAR; WAIT_L(0); MMA(0, 1, At, B1); BAR;
;     LDA(At, 0, 1); STAGEA(SA(0, 0), A0, t + 2);
;     BAR; WAIT_L(0); MMA(1, 0, At, B0); BAR; SCHED;
.LBB0_1716:
	ds_read_b128 v[176:179], v172
	ds_read_b128 v[180:183], v172 offset:1024
	ds_read_b128 v[184:187], v172 offset:2048
	ds_read_b128 v[188:191], v172 offset:3072
	v_add_u32_e32 v173, 0xc000, v159
	v_lshl_add_u64 v[240:241], s[30:31], 0, v[142:143]
	v_readfirstlane_b32 s27, v173
	v_lshl_add_u64 v[174:175], v[240:241], 0, s[6:7]
	s_mov_b32 m0, s27
	ds_read_b128 v[192:195], v154
	ds_read_b128 v[196:199], v154 offset:1024
	ds_read_b128 v[200:203], v153
	ds_read_b128 v[204:207], v153 offset:1024
	ds_read_b128 v[208:211], v152
	ds_read_b128 v[212:215], v152 offset:1024
	ds_read_b128 v[216:219], v151
	ds_read_b128 v[220:223], v151 offset:1024
	global_load_lds_dwordx4 v[174:175], off
	v_add_u32_e32 v174, 0xe000, v159
	v_lshl_add_u64 v[242:243], s[30:31], 0, v[144:145]
	v_readfirstlane_b32 s27, v174
	v_lshl_add_u64 v[224:225], v[242:243], 0, s[6:7]
	s_mov_b32 m0, s27
	s_nop 0
	global_load_lds_dwordx4 v[224:225], off
	s_waitcnt lgkmcnt(8)
	s_barrier
	s_waitcnt lgkmcnt(0)
	s_setprio 1
	v_mfma_f32_16x16x32_bf16 v[124:127], v[192:195], v[176:179], v[124:127]
	v_mfma_f32_16x16x32_bf16 v[120:123], v[192:195], v[184:187], v[120:123]
	v_mfma_f32_16x16x32_bf16 v[116:119], v[200:203], v[176:179], v[116:119]
	v_mfma_f32_16x16x32_bf16 v[112:115], v[200:203], v[184:187], v[112:115]
	v_mfma_f32_16x16x32_bf16 v[108:111], v[208:211], v[176:179], v[108:111]
	v_mfma_f32_16x16x32_bf16 v[104:107], v[208:211], v[184:187], v[104:107]
	v_mfma_f32_16x16x32_bf16 v[100:103], v[216:219], v[176:179], v[100:103]
	v_mfma_f32_16x16x32_bf16 v[96:99], v[216:219], v[184:187], v[96:99]
	v_mfma_f32_16x16x32_bf16 v[124:127], v[196:199], v[180:183], v[124:127]
	v_mfma_f32_16x16x32_bf16 v[120:123], v[196:199], v[188:191], v[120:123]
	v_mfma_f32_16x16x32_bf16 v[116:119], v[204:207], v[180:183], v[116:119]
	v_mfma_f32_16x16x32_bf16 v[112:115], v[204:207], v[188:191], v[112:115]
	v_mfma_f32_16x16x32_bf16 v[108:111], v[212:215], v[180:183], v[108:111]
	v_mfma_f32_16x16x32_bf16 v[104:107], v[212:215], v[188:191], v[104:107]
	v_mfma_f32_16x16x32_bf16 v[100:103], v[220:223], v[180:183], v[100:103]
	v_mfma_f32_16x16x32_bf16 v[96:99], v[220:223], v[188:191], v[96:99]
	s_setprio 0
	s_barrier
	v_lshl_add_u64 v[244:245], s[30:31], 0, v[128:129]
	v_readfirstlane_b32 s27, v156
	v_lshl_add_u64 v[246:247], v[244:245], 0, s[8:9]
	s_mov_b32 m0, s27
	ds_read_b128 v[224:227], v169
	ds_read_b128 v[228:231], v169 offset:1024
	ds_read_b128 v[232:235], v169 offset:2048
	ds_read_b128 v[236:239], v169 offset:3072
	global_load_lds_dwordx4 v[246:247], off
	v_lshl_add_u64 v[246:247], s[30:31], 0, v[130:131]
	v_readfirstlane_b32 s27, v158
	v_lshl_add_u64 v[248:249], v[246:247], 0, s[8:9]
	s_mov_b32 m0, s27
	s_nop 0
	global_load_lds_dwordx4 v[248:249], off
	s_barrier
	s_waitcnt lgkmcnt(0)
	s_setprio 1
	v_mfma_f32_16x16x32_bf16 v[92:95], v[192:195], v[224:227], v[92:95]
	v_mfma_f32_16x16x32_bf16 v[88:91], v[192:195], v[232:235], v[88:91]
	v_mfma_f32_16x16x32_bf16 v[84:87], v[200:203], v[224:227], v[84:87]
	v_mfma_f32_16x16x32_bf16 v[80:83], v[200:203], v[232:235], v[80:83]
	v_mfma_f32_16x16x32_bf16 v[76:79], v[208:211], v[224:227], v[76:79]
	v_mfma_f32_16x16x32_bf16 v[72:75], v[208:211], v[232:235], v[72:75]
	v_mfma_f32_16x16x32_bf16 v[68:71], v[216:219], v[224:227], v[68:71]
	v_mfma_f32_16x16x32_bf16 v[64:67], v[216:219], v[232:235], v[64:67]
	v_mfma_f32_16x16x32_bf16 v[92:95], v[196:199], v[228:231], v[92:95]
	v_mfma_f32_16x16x32_bf16 v[88:91], v[196:199], v[236:239], v[88:91]
	v_mfma_f32_16x16x32_bf16 v[84:87], v[204:207], v[228:231], v[84:87]
	v_mfma_f32_16x16x32_bf16 v[80:83], v[204:207], v[236:239], v[80:83]
	v_mfma_f32_16x16x32_bf16 v[76:79], v[212:215], v[228:231], v[76:79]
	v_mfma_f32_16x16x32_bf16 v[72:75], v[212:215], v[236:239], v[72:75]
	v_mfma_f32_16x16x32_bf16 v[68:71], v[220:223], v[228:231], v[68:71]
	v_mfma_f32_16x16x32_bf16 v[64:67], v[220:223], v[236:239], v[64:67]
	s_setprio 0
	v_readfirstlane_b32 s27, v159
	v_lshl_add_u64 v[248:249], v[240:241], 0, s[10:11]
	s_mov_b32 m0, s27
	v_readfirstlane_b32 s27, v160
	s_barrier
	ds_read_b128 v[192:195], v154 offset:16384
	ds_read_b128 v[196:199], v154 offset:17408
	ds_read_b128 v[200:203], v153 offset:16384
	ds_read_b128 v[204:207], v153 offset:17408
	ds_read_b128 v[208:211], v152 offset:16384
	ds_read_b128 v[212:215], v152 offset:17408
	ds_read_b128 v[216:219], v151 offset:16384
	ds_read_b128 v[220:223], v151 offset:17408
	global_load_lds_dwordx4 v[248:249], off
	v_lshl_add_u64 v[248:249], v[242:243], 0, s[10:11]
	s_mov_b32 m0, s27
	s_nop 0
	global_load_lds_dwordx4 v[248:249], off
	s_barrier
	s_waitcnt lgkmcnt(0)
	s_setprio 1
	v_mfma_f32_16x16x32_bf16 v[60:63], v[192:195], v[176:179], v[60:63]
	v_mfma_f32_16x16x32_bf16 v[56:59], v[192:195], v[184:187], v[56:59]
	v_mfma_f32_16x16x32_bf16 v[52:55], v[200:203], v[176:179], v[52:55]
	v_mfma_f32_16x16x32_bf16 v[48:51], v[200:203], v[184:187], v[48:51]
	v_mfma_f32_16x16x32_bf16 v[44:47], v[208:211], v[176:179], v[44:47]
	v_mfma_f32_16x16x32_bf16 v[40:43], v[208:211], v[184:187], v[40:43]
	v_mfma_f32_16x16x32_bf16 v[36:39], v[216:219], v[176:179], v[36:39]
	v_mfma_f32_16x16x32_bf16 v[32:35], v[216:219], v[184:187], v[32:35]
	v_mfma_f32_16x16x32_bf16 v[60:63], v[196:199], v[180:183], v[60:63]
	v_mfma_f32_16x16x32_bf16 v[56:59], v[196:199], v[188:191], v[56:59]
	v_mfma_f32_16x16x32_bf16 v[52:55], v[204:207], v[180:183], v[52:55]
	v_mfma_f32_16x16x32_bf16 v[48:51], v[204:207], v[188:191], v[48:51]
	v_mfma_f32_16x16x32_bf16 v[44:47], v[212:215], v[180:183], v[44:47]
	v_mfma_f32_16x16x32_bf16 v[40:43], v[212:215], v[188:191], v[40:43]
	v_mfma_f32_16x16x32_bf16 v[36:39], v[220:223], v[180:183], v[36:39]
	v_mfma_f32_16x16x32_bf16 v[32:35], v[220:223], v[188:191], v[32:35]
	s_setprio 0
	s_barrier
; #define STAGE(P, BASE, kt) do { const char* _g = (const char*)(BASE) + (size_t)((kt) * (BK * 2)); \
;     __builtin_amdgcn_global_load_lds((const unsigned*)(_g + (size_t)goff0), (unsigned*)((char*)(P) + tid_ * 16), 16, 0, 0); \
;     __builtin_amdgcn_global_load_lds((const unsigned*)(_g + (size_t)goff1), (unsigned*)((char*)(P) + tid_ * 16 + 8192), 16, 0, 0); } while (0)
; #define STAGEA(P, BASE, kt) do { const char* _g = (const char*)(BASE) + (size_t)((kt) * a_kbytes); \
;     __builtin_amdgcn_global_load_lds((const unsigned*)(_g + (size_t)goffA0), (unsigned*)((char*)(P) + tid_ * 16), 16, 0, 0); \
;     __builtin_amdgcn_global_load_lds((const unsigned*)(_g + (size_t)goffA1), (unsigned*)((char*)(P) + tid_ * 16 + 8192), 16, 0, 0); } while (0)
; #define LDA(dst, b, h) for (int m = 0; m < 4; ++m) for (int k = 0; k < 2; ++k) \
;     dst[m][k] = *reinterpret_cast<const bf16x8*>((char*)SA(b, h) + lds_byte(wr * 64 + m * 16 + fr, k * 32 + fq * 8))
; #define LDB(dst, b, h) for (int n = 0; n < 2; ++n) for (int k = 0; k < 2; ++k) \
;     dst[n][k] = *reinterpret_cast<const bf16x8*>((char*)SB(b, h) + lds_byte(wc * 32 + n * 16 + fr, k * 32 + fq * 8))
; #define MMA(ai, bj, At, Bt) do { __builtin_amdgcn_s_setprio(1); \
;     for (int m = 0; m < 4; ++m) for (int n = 0; n < 2; ++n) for (int k = 0; k < 2; ++k) \
;       acc[ai][bj][m][n] = __builtin_amdgcn_mfma_f32_16x16x32_bf16(At[m][k], Bt[n][k], acc[ai][bj][m][n], 0, 0, 0); \
;     __builtin_amdgcn_s_setprio(0); } while (0)
; #define WAIT_V(n) asm volatile("s_waitcnt vmcnt(" #n ")" ::: "memory")
; #define WAIT_L(n) asm volatile("s_waitcnt lgkmcnt(" #n ")" ::: "memory")
; #define BAR __builtin_amdgcn_s_barrier()
; #define SCHED __builtin_amdgcn_sched_barrier(0)
; template <int EPI> ...
;     ...
;     STAGE(SB(0, 1), B1p, t + 2);
;     WAIT_V(6); BAR; MMA(1, 1, At, B1); BAR;
;     LDB(B0, 1, 0); SCHED; LDA(At, 1, 0); STAGEA(SA(0, 1), A1, t + 2);
;     WAIT_L(8); BAR; WAIT_L(0); MMA(0, 0, At, B0); BAR; SCHED;
;     LDB(B1, 1, 1); STAGE(SB(1, 0), B0p, t + 3);
;     BAR; WAIT_L(0); MMA(0, 1, At, B1); BAR;
;     LDA(At, 1, 1); STAGEA(SA(1, 0), A0, t + 3);
;     BAR; WAIT_L(0); MMA(1, 0, At, B0); BAR; SCHED;
	v_readfirstlane_b32 s27, v161
	v_lshl_add_u64 v[176:177], v[244:245], 0, s[12:13]
	s_mov_b32 m0, s27
	v_readfirstlane_b32 s27, v162
	global_load_lds_dwordx4 v[176:177], off
	v_lshl_add_u64 v[176:177], v[246:247], 0, s[12:13]
	s_mov_b32 m0, s27
	s_nop 0
	global_load_lds_dwordx4 v[176:177], off
	s_waitcnt vmcnt(6)
	s_barrier
	s_setprio 1
	v_mfma_f32_16x16x32_bf16 v[28:31], v[192:195], v[224:227], v[28:31]
	v_mfma_f32_16x16x32_bf16 v[24:27], v[192:195], v[232:235], v[24:27]
	v_mfma_f32_16x16x32_bf16 v[20:23], v[200:203], v[224:227], v[20:23]
	v_mfma_f32_16x16x32_bf16 v[16:19], v[200:203], v[232:235], v[16:19]
	v_mfma_f32_16x16x32_bf16 v[12:15], v[208:211], v[224:227], v[12:15]
	v_mfma_f32_16x16x32_bf16 v[8:11], v[208:211], v[232:235], v[8:11]
	v_mfma_f32_16x16x32_bf16 v[4:7], v[216:219], v[224:227], v[4:7]
	v_mfma_f32_16x16x32_bf16 v[0:3], v[216:219], v[232:235], v[0:3]
	v_mfma_f32_16x16x32_bf16 v[28:31], v[196:199], v[228:231], v[28:31]
	v_mfma_f32_16x16x32_bf16 v[24:27], v[196:199], v[236:239], v[24:27]
	v_mfma_f32_16x16x32_bf16 v[20:23], v[204:207], v[228:231], v[20:23]
	v_mfma_f32_16x16x32_bf16 v[16:19], v[204:207], v[236:239], v[16:19]
	v_mfma_f32_16x16x32_bf16 v[12:15], v[212:215], v[228:231], v[12:15]
	v_mfma_f32_16x16x32_bf16 v[8:11], v[212:215], v[236:239], v[8:11]
	v_mfma_f32_16x16x32_bf16 v[4:7], v[220:223], v[228:231], v[4:7]
	v_mfma_f32_16x16x32_bf16 v[0:3], v[220:223], v[236:239], v[0:3]
	s_setprio 0
	s_barrier
	ds_read_b128 v[176:179], v157
	ds_read_b128 v[180:183], v157 offset:1024
	ds_read_b128 v[184:187], v157 offset:2048
	ds_read_b128 v[188:191], v157 offset:3072
	v_readfirstlane_b32 s27, v163
	v_lshl_add_u64 v[224:225], v[240:241], 0, s[14:15]
	s_mov_b32 m0, s27
	v_readfirstlane_b32 s27, v164
	ds_read_b128 v[192:195], v154 offset:32768
	ds_read_b128 v[196:199], v154 offset:33792
	ds_read_b128 v[200:203], v153 offset:32768
	ds_read_b128 v[204:207], v153 offset:33792
	ds_read_b128 v[208:211], v152 offset:32768
	ds_read_b128 v[212:215], v152 offset:33792
	ds_read_b128 v[216:219], v151 offset:32768
	ds_read_b128 v[220:223], v151 offset:33792
	global_load_lds_dwordx4 v[224:225], off
	v_lshl_add_u64 v[224:225], v[242:243], 0, s[14:15]
	s_mov_b32 m0, s27
	s_nop 0
	global_load_lds_dwordx4 v[224:225], off
	s_waitcnt lgkmcnt(8)
	s_barrier
	s_waitcnt lgkmcnt(0)
	s_setprio 1
	v_mfma_f32_16x16x32_bf16 v[124:127], v[192:195], v[176:179], v[124:127]
	v_mfma_f32_16x16x32_bf16 v[120:123], v[192:195], v[184:187], v[120:123]
	v_mfma_f32_16x16x32_bf16 v[116:119], v[200:203], v[176:179], v[116:119]
	v_mfma_f32_16x16x32_bf16 v[112:115], v[200:203], v[184:187], v[112:115]
	v_mfma_f32_16x16x32_bf16 v[108:111], v[208:211], v[176:179], v[108:111]
	v_mfma_f32_16x16x32_bf16 v[104:107], v[208:211], v[184:187], v[104:107]
	v_mfma_f32_16x16x32_bf16 v[100:103], v[216:219], v[176:179], v[100:103]
	v_mfma_f32_16x16x32_bf16 v[96:99], v[216:219], v[184:187], v[96:99]
	v_mfma_f32_16x16x32_bf16 v[124:127], v[196:199], v[180:183], v[124:127]
	v_mfma_f32_16x16x32_bf16 v[120:123], v[196:199], v[188:191], v[120:123]
	v_mfma_f32_16x16x32_bf16 v[116:119], v[204:207], v[180:183], v[116:119]
	v_mfma_f32_16x16x32_bf16 v[112:115], v[204:207], v[188:191], v[112:115]
	v_mfma_f32_16x16x32_bf16 v[108:111], v[212:215], v[180:183], v[108:111]
	v_mfma_f32_16x16x32_bf16 v[104:107], v[212:215], v[188:191], v[104:107]
	v_mfma_f32_16x16x32_bf16 v[100:103], v[220:223], v[180:183], v[100:103]
	v_mfma_f32_16x16x32_bf16 v[96:99], v[220:223], v[188:191], v[96:99]
	s_setprio 0
	s_barrier
	v_readfirstlane_b32 s27, v165
	v_lshl_add_u64 v[248:249], v[244:245], 0, s[16:17]
	s_mov_b32 m0, s27
	v_readfirstlane_b32 s27, v166
	ds_read_b128 v[224:227], v155
	ds_read_b128 v[228:231], v155 offset:1024
	ds_read_b128 v[232:235], v155 offset:2048
	ds_read_b128 v[236:239], v155 offset:3072
	global_load_lds_dwordx4 v[248:249], off
	v_lshl_add_u64 v[248:249], v[246:247], 0, s[16:17]
	s_mov_b32 m0, s27
	s_nop 0
	global_load_lds_dwordx4 v[248:249], off
	s_barrier
	s_waitcnt lgkmcnt(0)
	s_setprio 1
	v_mfma_f32_16x16x32_bf16 v[92:95], v[192:195], v[224:227], v[92:95]
	v_mfma_f32_16x16x32_bf16 v[88:91], v[192:195], v[232:235], v[88:91]
	v_mfma_f32_16x16x32_bf16 v[84:87], v[200:203], v[224:227], v[84:87]
	v_mfma_f32_16x16x32_bf16 v[80:83], v[200:203], v[232:235], v[80:83]
	v_mfma_f32_16x16x32_bf16 v[76:79], v[208:211], v[224:227], v[76:79]
	v_mfma_f32_16x16x32_bf16 v[72:75], v[208:211], v[232:235], v[72:75]
	v_mfma_f32_16x16x32_bf16 v[68:71], v[216:219], v[224:227], v[68:71]
	v_mfma_f32_16x16x32_bf16 v[64:67], v[216:219], v[232:235], v[64:67]
	v_mfma_f32_16x16x32_bf16 v[92:95], v[196:199], v[228:231], v[92:95]
	v_mfma_f32_16x16x32_bf16 v[88:91], v[196:199], v[236:239], v[88:91]
	v_mfma_f32_16x16x32_bf16 v[84:87], v[204:207], v[228:231], v[84:87]
	v_mfma_f32_16x16x32_bf16 v[80:83], v[204:207], v[236:239], v[80:83]
	v_mfma_f32_16x16x32_bf16 v[76:79], v[212:215], v[228:231], v[76:79]
	v_mfma_f32_16x16x32_bf16 v[72:75], v[212:215], v[236:239], v[72:75]
	v_mfma_f32_16x16x32_bf16 v[68:71], v[220:223], v[228:231], v[68:71]
	v_mfma_f32_16x16x32_bf16 v[64:67], v[220:223], v[236:239], v[64:67]
	s_setprio 0
	v_readfirstlane_b32 s27, v167
	v_lshl_add_u64 v[240:241], v[240:241], 0, s[18:19]
	s_mov_b32 m0, s27
	v_readfirstlane_b32 s27, v168
	s_barrier
	ds_read_b128 v[192:195], v154 offset:49152
	ds_read_b128 v[196:199], v154 offset:50176
	ds_read_b128 v[200:203], v153 offset:49152
	ds_read_b128 v[204:207], v153 offset:50176
	ds_read_b128 v[208:211], v152 offset:49152
	ds_read_b128 v[212:215], v152 offset:50176
	ds_read_b128 v[216:219], v151 offset:49152
	ds_read_b128 v[220:223], v151 offset:50176
	global_load_lds_dwordx4 v[240:241], off
	v_lshl_add_u64 v[240:241], v[242:243], 0, s[18:19]
	s_mov_b32 m0, s27
	s_nop 0
	global_load_lds_dwordx4 v[240:241], off
	s_barrier
; #define STAGE(P, BASE, kt) do { const char* _g = (const char*)(BASE) + (size_t)((kt) * (BK * 2)); \
;     __builtin_amdgcn_global_load_lds((const unsigned*)(_g + (size_t)goff0), (unsigned*)((char*)(P) + tid_ * 16), 16, 0, 0); \
;     __builtin_amdgcn_global_load_lds((const unsigned*)(_g + (size_t)goff1), (unsigned*)((char*)(P) + tid_ * 16 + 8192), 16, 0, 0); } while (0)
; #define STAGEA(P, BASE, kt) do { const char* _g = (const char*)(BASE) + (size_t)((kt) * a_kbytes); \
;     __builtin_amdgcn_global_load_lds((const unsigned*)(_g + (size_t)goffA0), (unsigned*)((char*)(P) + tid_ * 16), 16, 0, 0); \
;     __builtin_amdgcn_global_load_lds((const unsigned*)(_g + (size_t)goffA1), (unsigned*)((char*)(P) + tid_ * 16 + 8192), 16, 0, 0); } while (0)
; #define LDA(dst, b, h) for (int m = 0; m < 4; ++m) for (int k = 0; k < 2; ++k) \
;     dst[m][k] = *reinterpret_cast<const bf16x8*>((char*)SA(b, h) + lds_byte(wr * 64 + m * 16 + fr, k * 32 + fq * 8))
; #define LDB(dst, b, h) for (int n = 0; n < 2; ++n) for (int k = 0; k < 2; ++k) \
;     dst[n][k] = *reinterpret_cast<const bf16x8*>((char*)SB(b, h) + lds_byte(wc * 32 + n * 16 + fr, k * 32 + fq * 8))
; #define MMA(ai, bj, At, Bt) do { __builtin_amdgcn_s_setprio(1); \
;     for (int m = 0; m < 4; ++m) for (int n = 0; n < 2; ++n) for (int k = 0; k < 2; ++k) \
;       acc[ai][bj][m][n] = __builtin_amdgcn_mfma_f32_16x16x32_bf16(At[m][k], Bt[n][k], acc[ai][bj][m][n], 0, 0, 0); \
;     __builtin_amdgcn_s_setprio(0); } while (0)
; #define WAIT_V(n) asm volatile("s_waitcnt vmcnt(" #n ")" ::: "memory")
; #define WAIT_L(n) asm volatile("s_waitcnt lgkmcnt(" #n ")" ::: "memory")
; #define BAR __builtin_amdgcn_s_barrier()
; #define SCHED __builtin_amdgcn_sched_barrier(0)
; template <int EPI> ...
;     ...
;     WAIT_L(8); BAR; WAIT_L(0); MMA(0, 0, At, B0); BAR; SCHED;
;     LDB(B1, 1, 1); STAGE(SB(1, 0), B0p, t + 3);
;     BAR; WAIT_L(0); MMA(0, 1, At, B1); BAR;
;     LDA(At, 1, 1); STAGEA(SA(1, 0), A0, t + 3);
;     BAR; WAIT_L(0); MMA(1, 0, At, B0); BAR; SCHED;
;     STAGE(SB(1, 1), B1p, t + 3);
;     WAIT_V(6); BAR; MMA(1, 1, At, B1); BAR;
;   }
;   { LDB(B0, 0, 0); LDA(At, 0, 0); STAGEA(SA(1, 1), A1, nt - 1);
;     BAR; WAIT_L(0); MMA(0, 0, At, B0); BAR;
;     LDB(B1, 0, 1); BAR; WAIT_L(0); MMA(0, 1, At, B1); BAR;
	s_waitcnt lgkmcnt(0)
	s_setprio 1
	v_mfma_f32_16x16x32_bf16 v[60:63], v[192:195], v[176:179], v[60:63]
	v_mfma_f32_16x16x32_bf16 v[56:59], v[192:195], v[184:187], v[56:59]
	v_mfma_f32_16x16x32_bf16 v[52:55], v[200:203], v[176:179], v[52:55]
	v_mfma_f32_16x16x32_bf16 v[48:51], v[200:203], v[184:187], v[48:51]
	v_mfma_f32_16x16x32_bf16 v[44:47], v[208:211], v[176:179], v[44:47]
	v_mfma_f32_16x16x32_bf16 v[40:43], v[208:211], v[184:187], v[40:43]
	v_mfma_f32_16x16x32_bf16 v[36:39], v[216:219], v[176:179], v[36:39]
	v_mfma_f32_16x16x32_bf16 v[32:35], v[216:219], v[184:187], v[32:35]
	v_mfma_f32_16x16x32_bf16 v[60:63], v[196:199], v[180:183], v[60:63]
	v_mfma_f32_16x16x32_bf16 v[56:59], v[196:199], v[188:191], v[56:59]
	v_mfma_f32_16x16x32_bf16 v[52:55], v[204:207], v[180:183], v[52:55]
	v_mfma_f32_16x16x32_bf16 v[48:51], v[204:207], v[188:191], v[48:51]
	v_mfma_f32_16x16x32_bf16 v[44:47], v[212:215], v[180:183], v[44:47]
	v_mfma_f32_16x16x32_bf16 v[40:43], v[212:215], v[188:191], v[40:43]
	v_mfma_f32_16x16x32_bf16 v[36:39], v[220:223], v[180:183], v[36:39]
	v_mfma_f32_16x16x32_bf16 v[32:35], v[220:223], v[188:191], v[32:35]
	s_setprio 0
	s_barrier
	v_readfirstlane_b32 s27, v170
	v_lshl_add_u64 v[176:177], v[244:245], 0, s[20:21]
	s_mov_b32 m0, s27
	v_readfirstlane_b32 s27, v171
	global_load_lds_dwordx4 v[176:177], off
	v_lshl_add_u64 v[176:177], v[246:247], 0, s[20:21]
	s_mov_b32 m0, s27
	s_nop 0
	global_load_lds_dwordx4 v[176:177], off
	s_waitcnt vmcnt(6)
	s_barrier
	s_setprio 1
	v_mfma_f32_16x16x32_bf16 v[28:31], v[192:195], v[224:227], v[28:31]
	v_mfma_f32_16x16x32_bf16 v[24:27], v[192:195], v[232:235], v[24:27]
	v_mfma_f32_16x16x32_bf16 v[20:23], v[200:203], v[224:227], v[20:23]
	v_mfma_f32_16x16x32_bf16 v[16:19], v[200:203], v[232:235], v[16:19]
	v_mfma_f32_16x16x32_bf16 v[12:15], v[208:211], v[224:227], v[12:15]
	v_mfma_f32_16x16x32_bf16 v[8:11], v[208:211], v[232:235], v[8:11]
	v_mfma_f32_16x16x32_bf16 v[4:7], v[216:219], v[224:227], v[4:7]
	v_mfma_f32_16x16x32_bf16 v[0:3], v[216:219], v[232:235], v[0:3]
	v_mfma_f32_16x16x32_bf16 v[28:31], v[196:199], v[228:231], v[28:31]
	v_mfma_f32_16x16x32_bf16 v[24:27], v[196:199], v[236:239], v[24:27]
	v_mfma_f32_16x16x32_bf16 v[20:23], v[204:207], v[228:231], v[20:23]
	v_mfma_f32_16x16x32_bf16 v[16:19], v[204:207], v[236:239], v[16:19]
	v_mfma_f32_16x16x32_bf16 v[12:15], v[212:215], v[228:231], v[12:15]
	v_mfma_f32_16x16x32_bf16 v[8:11], v[212:215], v[236:239], v[8:11]
	v_mfma_f32_16x16x32_bf16 v[4:7], v[220:223], v[228:231], v[4:7]
	v_mfma_f32_16x16x32_bf16 v[0:3], v[220:223], v[236:239], v[0:3]
	s_setprio 0
	s_add_i32 s25, s25, 2
	s_add_u32 s30, s30, 0x100
	s_addc_u32 s31, s31, 0
	s_cmp_lt_u32 s25, 28
	s_barrier
	s_cbranch_scc1 .LBB0_1716
	s_add_u32 s28, s28, 0x80f80
	s_addc_u32 s29, s29, 0
	v_readfirstlane_b32 s25, v173
	v_lshl_add_u64 v[166:167], s[28:29], 0, v[134:135]
	s_mov_b32 m0, s25
	v_readfirstlane_b32 s25, v174
	ds_read_b128 v[128:131], v172
	ds_read_b128 v[142:145], v172 offset:1024
	ds_read_b128 v[158:161], v172 offset:2048
	ds_read_b128 v[162:165], v172 offset:3072
	ds_read_b128 v[176:179], v154
	ds_read_b128 v[180:183], v154 offset:1024
	ds_read_b128 v[184:187], v153
	ds_read_b128 v[188:191], v153 offset:1024
	ds_read_b128 v[192:195], v152
	ds_read_b128 v[196:199], v152 offset:1024
	ds_read_b128 v[200:203], v151
	ds_read_b128 v[204:207], v151 offset:1024
	global_load_lds_dwordx4 v[166:167], off
	v_lshl_add_u64 v[166:167], s[28:29], 0, v[132:133]
	s_mov_b32 m0, s25
	s_nop 0
	global_load_lds_dwordx4 v[166:167], off
	s_barrier
	s_waitcnt lgkmcnt(0)
	s_setprio 1
	v_mfma_f32_16x16x32_bf16 v[124:127], v[176:179], v[128:131], v[124:127]
	v_mfma_f32_16x16x32_bf16 v[120:123], v[176:179], v[158:161], v[120:123]
	v_mfma_f32_16x16x32_bf16 v[108:111], v[192:195], v[128:131], v[108:111]
	v_mfma_f32_16x16x32_bf16 v[104:107], v[192:195], v[158:161], v[104:107]
	v_mfma_f32_16x16x32_bf16 v[124:127], v[180:183], v[142:145], v[124:127]
	v_mfma_f32_16x16x32_bf16 v[120:123], v[180:183], v[162:165], v[120:123]
	v_mfma_f32_16x16x32_bf16 v[116:119], v[184:187], v[128:131], v[116:119]
	v_mfma_f32_16x16x32_bf16 v[112:115], v[184:187], v[158:161], v[112:115]
	v_mfma_f32_16x16x32_bf16 v[108:111], v[196:199], v[142:145], v[108:111]
	v_mfma_f32_16x16x32_bf16 v[104:107], v[196:199], v[162:165], v[104:107]
	v_mfma_f32_16x16x32_bf16 v[100:103], v[200:203], v[128:131], v[100:103]
	v_mfma_f32_16x16x32_bf16 v[96:99], v[200:203], v[158:161], v[96:99]
	v_mfma_f32_16x16x32_bf16 v[170:173], v[188:191], v[142:145], v[116:119]
	v_mfma_f32_16x16x32_bf16 v[208:211], v[188:191], v[162:165], v[112:115]
	v_mfma_f32_16x16x32_bf16 v[212:215], v[204:207], v[142:145], v[100:103]
	v_mfma_f32_16x16x32_bf16 v[216:219], v[204:207], v[162:165], v[96:99]
	s_setprio 0
	s_barrier
	s_nop 1
	ds_read_b128 v[96:99], v169
	ds_read_b128 v[100:103], v169 offset:1024
	ds_read_b128 v[112:115], v169 offset:2048
	ds_read_b128 v[116:119], v169 offset:3072
	s_barrier
	s_waitcnt lgkmcnt(0)
	s_setprio 1
	v_mfma_f32_16x16x32_bf16 v[92:95], v[176:179], v[96:99], v[92:95]
	v_mfma_f32_16x16x32_bf16 v[88:91], v[176:179], v[112:115], v[88:91]
	v_mfma_f32_16x16x32_bf16 v[76:79], v[192:195], v[96:99], v[76:79]
	v_mfma_f32_16x16x32_bf16 v[72:75], v[192:195], v[112:115], v[72:75]
	v_mfma_f32_16x16x32_bf16 v[92:95], v[180:183], v[100:103], v[92:95]
	v_mfma_f32_16x16x32_bf16 v[88:91], v[180:183], v[116:119], v[88:91]
	v_mfma_f32_16x16x32_bf16 v[84:87], v[184:187], v[96:99], v[84:87]
	v_mfma_f32_16x16x32_bf16 v[80:83], v[184:187], v[112:115], v[80:83]
	v_mfma_f32_16x16x32_bf16 v[76:79], v[196:199], v[100:103], v[76:79]
	v_mfma_f32_16x16x32_bf16 v[72:75], v[196:199], v[116:119], v[72:75]
	v_mfma_f32_16x16x32_bf16 v[68:71], v[200:203], v[96:99], v[68:71]
	v_mfma_f32_16x16x32_bf16 v[64:67], v[200:203], v[112:115], v[64:67]
	v_mfma_f32_16x16x32_bf16 v[166:169], v[188:191], v[100:103], v[84:87]
	v_mfma_f32_16x16x32_bf16 v[174:177], v[188:191], v[116:119], v[80:83]
	v_mfma_f32_16x16x32_bf16 v[178:181], v[204:207], v[100:103], v[68:71]
	v_mfma_f32_16x16x32_bf16 v[182:185], v[204:207], v[116:119], v[64:67]
	s_setprio 0
	s_barrier
; #define LDA(dst, b, h) for (int m = 0; m < 4; ++m) for (int k = 0; k < 2; ++k) \
;     dst[m][k] = *reinterpret_cast<const bf16x8*>((char*)SA(b, h) + lds_byte(wr * 64 + m * 16 + fr, k * 32 + fq * 8))
; #define LDB(dst, b, h) for (int n = 0; n < 2; ++n) for (int k = 0; k < 2; ++k) \
;     dst[n][k] = *reinterpret_cast<const bf16x8*>((char*)SB(b, h) + lds_byte(wc * 32 + n * 16 + fr, k * 32 + fq * 8))
; #define MMA(ai, bj, At, Bt) do { __builtin_amdgcn_s_setprio(1); \
;     for (int m = 0; m < 4; ++m) for (int n = 0; n < 2; ++n) for (int k = 0; k < 2; ++k) \
;       acc[ai][bj][m][n] = __builtin_amdgcn_mfma_f32_16x16x32_bf16(At[m][k], Bt[n][k], acc[ai][bj][m][n], 0, 0, 0); \
;     __builtin_amdgcn_s_setprio(0); } while (0)
; #define WAIT_V(n) asm volatile("s_waitcnt vmcnt(" #n ")" ::: "memory")
; #define WAIT_L(n) asm volatile("s_waitcnt lgkmcnt(" #n ")" ::: "memory")
; #define BAR __builtin_amdgcn_s_barrier()
; template <int EPI> ...
;     ...
;     LDA(At, 0, 1); WAIT_V(4); BAR; WAIT_L(0); MMA(1, 0, At, B0); MMA(1, 1, At, B1); BAR; }
;   { LDB(B0, 1, 0); LDA(At, 1, 0); WAIT_V(2); BAR; WAIT_L(0); MMA(0, 0, At, B0); BAR;
	s_nop 1
	ds_read_b128 v[64:67], v154 offset:16384
	ds_read_b128 v[68:71], v154 offset:17408
	ds_read_b128 v[80:83], v153 offset:16384
	ds_read_b128 v[84:87], v153 offset:17408
	ds_read_b128 v[186:189], v152 offset:16384
	ds_read_b128 v[190:193], v152 offset:17408
	ds_read_b128 v[194:197], v151 offset:16384
	ds_read_b128 v[198:201], v151 offset:17408
	s_waitcnt vmcnt(4)
	s_barrier
	s_waitcnt lgkmcnt(0)
	s_setprio 1
	v_mfma_f32_16x16x32_bf16 v[60:63], v[64:67], v[128:131], v[60:63]
	v_mfma_f32_16x16x32_bf16 v[52:55], v[80:83], v[128:131], v[52:55]
	v_mfma_f32_16x16x32_bf16 v[44:47], v[186:189], v[128:131], v[44:47]
	v_mfma_f32_16x16x32_bf16 v[36:39], v[194:197], v[128:131], v[36:39]
	v_mfma_f32_16x16x32_bf16 v[60:63], v[68:71], v[142:145], v[60:63]
	v_mfma_f32_16x16x32_bf16 v[56:59], v[64:67], v[158:161], v[56:59]
	v_mfma_f32_16x16x32_bf16 v[52:55], v[84:87], v[142:145], v[52:55]
	v_mfma_f32_16x16x32_bf16 v[48:51], v[80:83], v[158:161], v[48:51]
	v_mfma_f32_16x16x32_bf16 v[44:47], v[190:193], v[142:145], v[44:47]
	v_mfma_f32_16x16x32_bf16 v[40:43], v[186:189], v[158:161], v[40:43]
	v_mfma_f32_16x16x32_bf16 v[36:39], v[198:201], v[142:145], v[36:39]
	v_mfma_f32_16x16x32_bf16 v[32:35], v[194:197], v[158:161], v[32:35]
	v_mfma_f32_16x16x32_bf16 v[202:205], v[68:71], v[162:165], v[56:59]
	v_mfma_f32_16x16x32_bf16 v[220:223], v[84:87], v[162:165], v[48:51]
	v_mfma_f32_16x16x32_bf16 v[224:227], v[190:193], v[162:165], v[40:43]
	v_mfma_f32_16x16x32_bf16 v[128:131], v[198:201], v[162:165], v[32:35]
	s_setprio 0
	s_setprio 1
	v_mfma_f32_16x16x32_bf16 v[28:31], v[64:67], v[96:99], v[28:31]
	v_mfma_f32_16x16x32_bf16 v[20:23], v[80:83], v[96:99], v[20:23]
	v_mfma_f32_16x16x32_bf16 v[12:15], v[186:189], v[96:99], v[12:15]
	v_mfma_f32_16x16x32_bf16 v[4:7], v[194:197], v[96:99], v[4:7]
	v_mfma_f32_16x16x32_bf16 v[28:31], v[68:71], v[100:103], v[28:31]
	v_mfma_f32_16x16x32_bf16 v[24:27], v[64:67], v[112:115], v[24:27]
	v_mfma_f32_16x16x32_bf16 v[20:23], v[84:87], v[100:103], v[20:23]
	v_mfma_f32_16x16x32_bf16 v[16:19], v[80:83], v[112:115], v[16:19]
	v_mfma_f32_16x16x32_bf16 v[12:15], v[190:193], v[100:103], v[12:15]
	v_mfma_f32_16x16x32_bf16 v[8:11], v[186:189], v[112:115], v[8:11]
	v_mfma_f32_16x16x32_bf16 v[4:7], v[198:201], v[100:103], v[4:7]
	v_mfma_f32_16x16x32_bf16 v[0:3], v[194:197], v[112:115], v[0:3]
	v_mfma_f32_16x16x32_bf16 v[142:145], v[68:71], v[116:119], v[24:27]
	v_mfma_f32_16x16x32_bf16 v[158:161], v[84:87], v[116:119], v[16:19]
	v_mfma_f32_16x16x32_bf16 v[162:165], v[190:193], v[116:119], v[8:11]
	v_mfma_f32_16x16x32_bf16 v[186:189], v[198:201], v[116:119], v[0:3]
	s_setprio 0
	s_barrier
	s_nop 1
	ds_read_b128 v[0:3], v157
	ds_read_b128 v[8:11], v157 offset:1024
	ds_read_b128 v[190:193], v157 offset:2048
	ds_read_b128 v[194:197], v157 offset:3072
	ds_read_b128 v[16:19], v154 offset:32768
	ds_read_b128 v[24:27], v154 offset:33792
	ds_read_b128 v[32:35], v153 offset:32768
	ds_read_b128 v[40:43], v153 offset:33792
	ds_read_b128 v[48:51], v152 offset:32768
	ds_read_b128 v[56:59], v152 offset:33792
	ds_read_b128 v[198:201], v151 offset:32768
	ds_read_b128 v[228:231], v151 offset:33792
	s_waitcnt vmcnt(2)
	s_barrier
	s_waitcnt lgkmcnt(0)
	s_setprio 1
	v_mfma_f32_16x16x32_bf16 v[64:67], v[16:19], v[0:3], v[124:127]
	v_mfma_f32_16x16x32_bf16 v[116:119], v[24:27], v[8:11], v[64:67]
	v_mfma_f32_16x16x32_bf16 v[64:67], v[16:19], v[190:193], v[120:123]
	v_mfma_f32_16x16x32_bf16 v[112:115], v[24:27], v[194:197], v[64:67]
	v_mfma_f32_16x16x32_bf16 v[64:67], v[32:35], v[0:3], v[170:173]
	v_mfma_f32_16x16x32_bf16 v[100:103], v[40:43], v[8:11], v[64:67]
	v_mfma_f32_16x16x32_bf16 v[64:67], v[32:35], v[190:193], v[208:211]
	v_mfma_f32_16x16x32_bf16 v[96:99], v[40:43], v[194:197], v[64:67]
	v_mfma_f32_16x16x32_bf16 v[64:67], v[48:51], v[0:3], v[108:111]
	v_mfma_f32_16x16x32_bf16 v[84:87], v[56:59], v[8:11], v[64:67]
	v_mfma_f32_16x16x32_bf16 v[64:67], v[48:51], v[190:193], v[104:107]
	v_mfma_f32_16x16x32_bf16 v[80:83], v[56:59], v[194:197], v[64:67]
	v_mfma_f32_16x16x32_bf16 v[64:67], v[198:201], v[0:3], v[212:215]
	v_mfma_f32_16x16x32_bf16 v[68:71], v[228:231], v[8:11], v[64:67]
	v_mfma_f32_16x16x32_bf16 v[64:67], v[198:201], v[190:193], v[216:219]
	v_mfma_f32_16x16x32_bf16 v[64:67], v[228:231], v[194:197], v[64:67]
	s_setprio 0
	s_barrier
; #define LDA(dst, b, h) for (int m = 0; m < 4; ++m) for (int k = 0; k < 2; ++k) \
;     dst[m][k] = *reinterpret_cast<const bf16x8*>((char*)SA(b, h) + lds_byte(wr * 64 + m * 16 + fr, k * 32 + fq * 8))
; #define LDB(dst, b, h) for (int n = 0; n < 2; ++n) for (int k = 0; k < 2; ++k) \
;     dst[n][k] = *reinterpret_cast<const bf16x8*>((char*)SB(b, h) + lds_byte(wc * 32 + n * 16 + fr, k * 32 + fq * 8))
; #define MMA(ai, bj, At, Bt) do { __builtin_amdgcn_s_setprio(1); \
;     for (int m = 0; m < 4; ++m) for (int n = 0; n < 2; ++n) for (int k = 0; k < 2; ++k) \
;       acc[ai][bj][m][n] = __builtin_amdgcn_mfma_f32_16x16x32_bf16(At[m][k], Bt[n][k], acc[ai][bj][m][n], 0, 0, 0); \
;     __builtin_amdgcn_s_setprio(0); } while (0)
; #define WAIT_V(n) asm volatile("s_waitcnt vmcnt(" #n ")" ::: "memory")
; #define WAIT_L(n) asm volatile("s_waitcnt lgkmcnt(" #n ")" ::: "memory")
; #define BAR __builtin_amdgcn_s_barrier()
; template <int EPI> ...
;     ...
;   { LDB(B0, 1, 0); LDA(At, 1, 0); WAIT_V(2); BAR; WAIT_L(0); MMA(0, 0, At, B0); BAR;
;     LDB(B1, 1, 1); WAIT_V(0); BAR; WAIT_L(0); MMA(0, 1, At, B1); BAR;
;     LDA(At, 1, 1); BAR; WAIT_L(0); MMA(1, 0, At, B0); MMA(1, 1, At, B1); BAR; }
;   if (wr == 0) BAR;
	ds_read_b128 v[170:173], v155
	ds_read_b128 v[206:209], v155 offset:1024
	ds_read_b128 v[210:213], v155 offset:2048
	ds_read_b128 v[214:217], v155 offset:3072
	s_waitcnt vmcnt(0)
	s_barrier
	s_waitcnt lgkmcnt(0)
	s_setprio 1
	v_mfma_f32_16x16x32_bf16 v[92:95], v[16:19], v[170:173], v[92:95]
	v_mfma_f32_16x16x32_bf16 v[16:19], v[16:19], v[210:213], v[88:91]
	v_mfma_f32_16x16x32_bf16 v[120:123], v[24:27], v[214:217], v[16:19]
	v_mfma_f32_16x16x32_bf16 v[16:19], v[32:35], v[170:173], v[166:169]
	v_mfma_f32_16x16x32_bf16 v[108:111], v[40:43], v[206:209], v[16:19]
	v_mfma_f32_16x16x32_bf16 v[16:19], v[32:35], v[210:213], v[174:177]
	v_mfma_f32_16x16x32_bf16 v[104:107], v[40:43], v[214:217], v[16:19]
	v_mfma_f32_16x16x32_bf16 v[16:19], v[48:51], v[170:173], v[76:79]
	v_mfma_f32_16x16x32_bf16 v[124:127], v[24:27], v[206:209], v[92:95]
	v_mfma_f32_16x16x32_bf16 v[92:95], v[56:59], v[206:209], v[16:19]
	v_mfma_f32_16x16x32_bf16 v[16:19], v[48:51], v[210:213], v[72:75]
	v_mfma_f32_16x16x32_bf16 v[88:91], v[56:59], v[214:217], v[16:19]
	v_mfma_f32_16x16x32_bf16 v[16:19], v[198:201], v[170:173], v[178:181]
	v_mfma_f32_16x16x32_bf16 v[76:79], v[228:231], v[206:209], v[16:19]
	v_mfma_f32_16x16x32_bf16 v[16:19], v[198:201], v[210:213], v[182:185]
	v_mfma_f32_16x16x32_bf16 v[72:75], v[228:231], v[214:217], v[16:19]
	s_setprio 0
	s_barrier
	ds_read_b128 v[166:169], v154 offset:49152
	ds_read_b128 v[154:157], v154 offset:50176
	ds_read_b128 v[174:177], v153 offset:49152
	ds_read_b128 v[178:181], v153 offset:50176
	ds_read_b128 v[182:185], v152 offset:49152
	ds_read_b128 v[198:201], v152 offset:50176
	ds_read_b128 v[228:231], v151 offset:49152
	ds_read_b128 v[232:235], v151 offset:50176
	s_barrier
	s_waitcnt lgkmcnt(0)
	s_setprio 1
	v_mfma_f32_16x16x32_bf16 v[16:19], v[166:169], v[0:3], v[60:63]
	v_mfma_f32_16x16x32_bf16 v[56:59], v[154:157], v[8:11], v[16:19]
	v_mfma_f32_16x16x32_bf16 v[16:19], v[166:169], v[190:193], v[202:205]
	v_mfma_f32_16x16x32_bf16 v[48:51], v[154:157], v[194:197], v[16:19]
	v_mfma_f32_16x16x32_bf16 v[16:19], v[174:177], v[0:3], v[52:55]
	v_mfma_f32_16x16x32_bf16 v[40:43], v[178:181], v[8:11], v[16:19]
	v_mfma_f32_16x16x32_bf16 v[16:19], v[174:177], v[190:193], v[220:223]
	v_mfma_f32_16x16x32_bf16 v[32:35], v[178:181], v[194:197], v[16:19]
	v_mfma_f32_16x16x32_bf16 v[16:19], v[182:185], v[0:3], v[44:47]
	v_mfma_f32_16x16x32_bf16 v[0:3], v[228:231], v[0:3], v[36:39]
	v_mfma_f32_16x16x32_bf16 v[24:27], v[198:201], v[8:11], v[16:19]
	v_mfma_f32_16x16x32_bf16 v[16:19], v[182:185], v[190:193], v[224:227]
	v_mfma_f32_16x16x32_bf16 v[8:11], v[232:235], v[8:11], v[0:3]
	v_mfma_f32_16x16x32_bf16 v[0:3], v[228:231], v[190:193], v[128:131]
	v_mfma_f32_16x16x32_bf16 v[16:19], v[198:201], v[194:197], v[16:19]
	v_mfma_f32_16x16x32_bf16 v[0:3], v[232:235], v[194:197], v[0:3]
	s_setprio 0
	s_setprio 1
	v_mfma_f32_16x16x32_bf16 v[28:31], v[166:169], v[170:173], v[28:31]
	v_mfma_f32_16x16x32_bf16 v[60:63], v[154:157], v[206:209], v[28:31]
	v_mfma_f32_16x16x32_bf16 v[28:31], v[166:169], v[210:213], v[142:145]
	v_mfma_f32_16x16x32_bf16 v[20:23], v[174:177], v[170:173], v[20:23]
	v_mfma_f32_16x16x32_bf16 v[12:15], v[182:185], v[170:173], v[12:15]
	v_mfma_f32_16x16x32_bf16 v[52:55], v[154:157], v[214:217], v[28:31]
	v_mfma_f32_16x16x32_bf16 v[44:47], v[178:181], v[206:209], v[20:23]
	v_mfma_f32_16x16x32_bf16 v[20:23], v[174:177], v[210:213], v[158:161]
	v_mfma_f32_16x16x32_bf16 v[28:31], v[198:201], v[206:209], v[12:15]
	v_mfma_f32_16x16x32_bf16 v[12:15], v[182:185], v[210:213], v[162:165]
	v_mfma_f32_16x16x32_bf16 v[4:7], v[228:231], v[170:173], v[4:7]
	v_mfma_f32_16x16x32_bf16 v[36:39], v[178:181], v[214:217], v[20:23]
	v_mfma_f32_16x16x32_bf16 v[20:23], v[198:201], v[214:217], v[12:15]
	v_mfma_f32_16x16x32_bf16 v[12:15], v[232:235], v[206:209], v[4:7]
	v_mfma_f32_16x16x32_bf16 v[4:7], v[228:231], v[210:213], v[186:189]
	v_mfma_f32_16x16x32_bf16 v[4:7], v[232:235], v[214:217], v[4:7]
	s_setprio 0
	v_cmp_gt_u32_e32 vcc, s50, v136
	s_barrier
	s_and_saveexec_b64 s[28:29], vcc
	s_cbranch_execz .LBB0_1719
	s_barrier

; #define STAGE(P, BASE, kt) do { const char* _g = (const char*)(BASE) + (size_t)((kt) * (BK * 2)); \
;     __builtin_amdgcn_global_load_lds((const unsigned*)(_g + (size_t)goff0), (unsigned*)((char*)(P) + tid_ * 16), 16, 0, 0); \
;     __builtin_amdgcn_global_load_lds((const unsigned*)(_g + (size_t)goff1), (unsigned*)((char*)(P) + tid_ * 16 + 8192), 16, 0, 0); } while (0)
; #define STAGEA(P, BASE, kt) do { const char* _g = (const char*)(BASE) + (size_t)((kt) * a_kbytes); \
;     __builtin_amdgcn_global_load_lds((const unsigned*)(_g + (size_t)goffA0), (unsigned*)((char*)(P) + tid_ * 16), 16, 0, 0); \
;     __builtin_amdgcn_global_load_lds((const unsigned*)(_g + (size_t)goffA1), (unsigned*)((char*)(P) + tid_ * 16 + 8192), 16, 0, 0); } while (0)
; #define LDA(dst, b, h) for (int m = 0; m < 4; ++m) for (int k = 0; k < 2; ++k) \
;     dst[m][k] = *reinterpret_cast<const bf16x8*>((char*)SA(b, h) + lds_byte(wr * 64 + m * 16 + fr, k * 32 + fq * 8))
; #define LDB(dst, b, h) for (int n = 0; n < 2; ++n) for (int k = 0; k < 2; ++k) \
;     dst[n][k] = *reinterpret_cast<const bf16x8*>((char*)SB(b, h) + lds_byte(wc * 32 + n * 16 + fr, k * 32 + fq * 8))
; #define MMA(ai, bj, At, Bt) do { __builtin_amdgcn_s_setprio(1); \
;     for (int m = 0; m < 4; ++m) for (int n = 0; n < 2; ++n) for (int k = 0; k < 2; ++k) \
;       acc[ai][bj][m][n] = __builtin_amdgcn_mfma_f32_16x16x32_bf16(At[m][k], Bt[n][k], acc[ai][bj][m][n], 0, 0, 0); \
;     __builtin_amdgcn_s_setprio(0); } while (0)
; #define WAIT_L(n) asm volatile("s_waitcnt lgkmcnt(" #n ")" ::: "memory")
; #define BAR __builtin_amdgcn_s_barrier()
; #define SCHED __builtin_amdgcn_sched_barrier(0)
; template <int EPI> ...
;     ...
;   for (int t = 0; t < nt - 2; t += 2) {
;     LDB(B0, 0, 0); SCHED; LDA(At, 0, 0); STAGEA(SA(1, 1), A1, t + 1);
;     WAIT_L(8); BAR; WAIT_L(0); MMA(0, 0, At, B0); BAR; SCHED;
;     LDB(B1, 0, 1); STAGE(SB(0, 0), B0p, t + 2);
;     BAR; WAIT_L(0); MMA(0, 1, At, B1); BAR;
;     LDA(At, 0, 1); STAGEA(SA(0, 0), A0, t + 2);
;     BAR; WAIT_L(0); MMA(1, 0, At, B0); BAR; SCHED;
.LBB0_1738:
	ds_read_b128 v[174:177], v171
	ds_read_b128 v[178:181], v171 offset:1024
	ds_read_b128 v[182:185], v171 offset:2048
	ds_read_b128 v[186:189], v171 offset:3072
	v_add_u32_e32 v172, 0xc000, v158
	v_lshl_add_u64 v[238:239], s[26:27], 0, v[136:137]
	v_readfirstlane_b32 s51, v172
	v_add_u32_e32 v173, 0xe000, v158
	v_lshl_add_u64 v[222:223], v[238:239], 0, s[4:5]
	s_mov_b32 m0, s51
	v_lshl_add_u64 v[240:241], s[26:27], 0, v[138:139]
	v_readfirstlane_b32 s51, v173
	ds_read_b128 v[190:193], v153
	ds_read_b128 v[194:197], v153 offset:1024
	ds_read_b128 v[198:201], v152
	ds_read_b128 v[202:205], v152 offset:1024
	ds_read_b128 v[206:209], v151
	ds_read_b128 v[210:213], v151 offset:1024
	ds_read_b128 v[214:217], v150
	ds_read_b128 v[218:221], v150 offset:1024
	global_load_lds_dwordx4 v[222:223], off
	v_lshl_add_u64 v[222:223], v[240:241], 0, s[4:5]
	s_mov_b32 m0, s51
	s_nop 0
	global_load_lds_dwordx4 v[222:223], off
	s_waitcnt lgkmcnt(8)
	s_barrier
	s_waitcnt lgkmcnt(0)
	s_setprio 1
	v_mfma_f32_16x16x32_bf16 v[124:127], v[190:193], v[174:177], v[124:127]
	v_mfma_f32_16x16x32_bf16 v[120:123], v[190:193], v[182:185], v[120:123]
	v_mfma_f32_16x16x32_bf16 v[116:119], v[198:201], v[174:177], v[116:119]
	v_mfma_f32_16x16x32_bf16 v[112:115], v[198:201], v[182:185], v[112:115]
	v_mfma_f32_16x16x32_bf16 v[108:111], v[206:209], v[174:177], v[108:111]
	v_mfma_f32_16x16x32_bf16 v[104:107], v[206:209], v[182:185], v[104:107]
	v_mfma_f32_16x16x32_bf16 v[100:103], v[214:217], v[174:177], v[100:103]
	v_mfma_f32_16x16x32_bf16 v[96:99], v[214:217], v[182:185], v[96:99]
	v_mfma_f32_16x16x32_bf16 v[124:127], v[194:197], v[178:181], v[124:127]
	v_mfma_f32_16x16x32_bf16 v[120:123], v[194:197], v[186:189], v[120:123]
	v_mfma_f32_16x16x32_bf16 v[116:119], v[202:205], v[178:181], v[116:119]
	v_mfma_f32_16x16x32_bf16 v[112:115], v[202:205], v[186:189], v[112:115]
	v_mfma_f32_16x16x32_bf16 v[108:111], v[210:213], v[178:181], v[108:111]
	v_mfma_f32_16x16x32_bf16 v[104:107], v[210:213], v[186:189], v[104:107]
	v_mfma_f32_16x16x32_bf16 v[100:103], v[218:221], v[178:181], v[100:103]
	v_mfma_f32_16x16x32_bf16 v[96:99], v[218:221], v[186:189], v[96:99]
	s_setprio 0
	s_barrier
	v_lshl_add_u64 v[242:243], s[24:25], 0, v[140:141]
	v_readfirstlane_b32 s51, v155
	v_lshl_add_u64 v[244:245], v[242:243], 0, s[6:7]
	s_mov_b32 m0, s51
	ds_read_b128 v[222:225], v167
	ds_read_b128 v[226:229], v167 offset:1024
	ds_read_b128 v[230:233], v167 offset:2048
	ds_read_b128 v[234:237], v167 offset:3072
	global_load_lds_dwordx4 v[244:245], off
	v_lshl_add_u64 v[244:245], s[24:25], 0, v[142:143]
	v_readfirstlane_b32 s51, v157
	v_lshl_add_u64 v[246:247], v[244:245], 0, s[6:7]
	s_mov_b32 m0, s51
	s_nop 0
	global_load_lds_dwordx4 v[246:247], off
	s_barrier
	s_waitcnt lgkmcnt(0)
	s_setprio 1
	v_mfma_f32_16x16x32_bf16 v[92:95], v[190:193], v[222:225], v[92:95]
	v_mfma_f32_16x16x32_bf16 v[88:91], v[190:193], v[230:233], v[88:91]
	v_mfma_f32_16x16x32_bf16 v[84:87], v[198:201], v[222:225], v[84:87]
	v_mfma_f32_16x16x32_bf16 v[80:83], v[198:201], v[230:233], v[80:83]
	v_mfma_f32_16x16x32_bf16 v[76:79], v[206:209], v[222:225], v[76:79]
	v_mfma_f32_16x16x32_bf16 v[72:75], v[206:209], v[230:233], v[72:75]
	v_mfma_f32_16x16x32_bf16 v[68:71], v[214:217], v[222:225], v[68:71]
	v_mfma_f32_16x16x32_bf16 v[64:67], v[214:217], v[230:233], v[64:67]
	v_mfma_f32_16x16x32_bf16 v[92:95], v[194:197], v[226:229], v[92:95]
	v_mfma_f32_16x16x32_bf16 v[88:91], v[194:197], v[234:237], v[88:91]
	v_mfma_f32_16x16x32_bf16 v[84:87], v[202:205], v[226:229], v[84:87]
	v_mfma_f32_16x16x32_bf16 v[80:83], v[202:205], v[234:237], v[80:83]
	v_mfma_f32_16x16x32_bf16 v[76:79], v[210:213], v[226:229], v[76:79]
	v_mfma_f32_16x16x32_bf16 v[72:75], v[210:213], v[234:237], v[72:75]
	v_mfma_f32_16x16x32_bf16 v[68:71], v[218:221], v[226:229], v[68:71]
	v_mfma_f32_16x16x32_bf16 v[64:67], v[218:221], v[234:237], v[64:67]
	s_setprio 0
	v_readfirstlane_b32 s51, v158
	v_lshl_add_u64 v[246:247], v[238:239], 0, s[8:9]
	s_mov_b32 m0, s51
	v_readfirstlane_b32 s51, v159
	s_barrier
	ds_read_b128 v[190:193], v153 offset:16384
	ds_read_b128 v[194:197], v153 offset:17408
	ds_read_b128 v[198:201], v152 offset:16384
	ds_read_b128 v[202:205], v152 offset:17408
	ds_read_b128 v[206:209], v151 offset:16384
	ds_read_b128 v[210:213], v151 offset:17408
	ds_read_b128 v[214:217], v150 offset:16384
	ds_read_b128 v[218:221], v150 offset:17408
	global_load_lds_dwordx4 v[246:247], off
	v_lshl_add_u64 v[246:247], v[240:241], 0, s[8:9]
	s_mov_b32 m0, s51
	s_nop 0
	global_load_lds_dwordx4 v[246:247], off
	s_barrier
	s_waitcnt lgkmcnt(0)
	s_setprio 1
	v_mfma_f32_16x16x32_bf16 v[60:63], v[190:193], v[174:177], v[60:63]
	v_mfma_f32_16x16x32_bf16 v[56:59], v[190:193], v[182:185], v[56:59]
	v_mfma_f32_16x16x32_bf16 v[52:55], v[198:201], v[174:177], v[52:55]
	v_mfma_f32_16x16x32_bf16 v[48:51], v[198:201], v[182:185], v[48:51]
	v_mfma_f32_16x16x32_bf16 v[44:47], v[206:209], v[174:177], v[44:47]
	v_mfma_f32_16x16x32_bf16 v[40:43], v[206:209], v[182:185], v[40:43]
	v_mfma_f32_16x16x32_bf16 v[36:39], v[214:217], v[174:177], v[36:39]
	v_mfma_f32_16x16x32_bf16 v[32:35], v[214:217], v[182:185], v[32:35]
	v_mfma_f32_16x16x32_bf16 v[60:63], v[194:197], v[178:181], v[60:63]
	v_mfma_f32_16x16x32_bf16 v[56:59], v[194:197], v[186:189], v[56:59]
	v_mfma_f32_16x16x32_bf16 v[52:55], v[202:205], v[178:181], v[52:55]
	v_mfma_f32_16x16x32_bf16 v[48:51], v[202:205], v[186:189], v[48:51]
	v_mfma_f32_16x16x32_bf16 v[44:47], v[210:213], v[178:181], v[44:47]
	v_mfma_f32_16x16x32_bf16 v[40:43], v[210:213], v[186:189], v[40:43]
	v_mfma_f32_16x16x32_bf16 v[36:39], v[218:221], v[178:181], v[36:39]
	v_mfma_f32_16x16x32_bf16 v[32:35], v[218:221], v[186:189], v[32:35]
	s_setprio 0
	s_barrier
; #define STAGE(P, BASE, kt) do { const char* _g = (const char*)(BASE) + (size_t)((kt) * (BK * 2)); \
;     __builtin_amdgcn_global_load_lds((const unsigned*)(_g + (size_t)goff0), (unsigned*)((char*)(P) + tid_ * 16), 16, 0, 0); \
;     __builtin_amdgcn_global_load_lds((const unsigned*)(_g + (size_t)goff1), (unsigned*)((char*)(P) + tid_ * 16 + 8192), 16, 0, 0); } while (0)
; #define STAGEA(P, BASE, kt) do { const char* _g = (const char*)(BASE) + (size_t)((kt) * a_kbytes); \
;     __builtin_amdgcn_global_load_lds((const unsigned*)(_g + (size_t)goffA0), (unsigned*)((char*)(P) + tid_ * 16), 16, 0, 0); \
;     __builtin_amdgcn_global_load_lds((const unsigned*)(_g + (size_t)goffA1), (unsigned*)((char*)(P) + tid_ * 16 + 8192), 16, 0, 0); } while (0)
; #define LDA(dst, b, h) for (int m = 0; m < 4; ++m) for (int k = 0; k < 2; ++k) \
;     dst[m][k] = *reinterpret_cast<const bf16x8*>((char*)SA(b, h) + lds_byte(wr * 64 + m * 16 + fr, k * 32 + fq * 8))
; #define LDB(dst, b, h) for (int n = 0; n < 2; ++n) for (int k = 0; k < 2; ++k) \
;     dst[n][k] = *reinterpret_cast<const bf16x8*>((char*)SB(b, h) + lds_byte(wc * 32 + n * 16 + fr, k * 32 + fq * 8))
; #define MMA(ai, bj, At, Bt) do { __builtin_amdgcn_s_setprio(1); \
;     for (int m = 0; m < 4; ++m) for (int n = 0; n < 2; ++n) for (int k = 0; k < 2; ++k) \
;       acc[ai][bj][m][n] = __builtin_amdgcn_mfma_f32_16x16x32_bf16(At[m][k], Bt[n][k], acc[ai][bj][m][n], 0, 0, 0); \
;     __builtin_amdgcn_s_setprio(0); } while (0)
; #define WAIT_V(n) asm volatile("s_waitcnt vmcnt(" #n ")" ::: "memory")
; #define WAIT_L(n) asm volatile("s_waitcnt lgkmcnt(" #n ")" ::: "memory")
; #define BAR __builtin_amdgcn_s_barrier()
; #define SCHED __builtin_amdgcn_sched_barrier(0)
; template <int EPI> ...
;     ...
;     STAGE(SB(0, 1), B1p, t + 2);
;     WAIT_V(6); BAR; MMA(1, 1, At, B1); BAR;
;     LDB(B0, 1, 0); SCHED; LDA(At, 1, 0); STAGEA(SA(0, 1), A1, t + 2);
;     WAIT_L(8); BAR; WAIT_L(0); MMA(0, 0, At, B0); BAR; SCHED;
;     LDB(B1, 1, 1); STAGE(SB(1, 0), B0p, t + 3);
;     BAR; WAIT_L(0); MMA(0, 1, At, B1); BAR;
;     LDA(At, 1, 1); STAGEA(SA(1, 0), A0, t + 3);
;     BAR; WAIT_L(0); MMA(1, 0, At, B0); BAR; SCHED;
	v_readfirstlane_b32 s51, v160
	v_lshl_add_u64 v[174:175], v[242:243], 0, s[10:11]
	s_mov_b32 m0, s51
	v_readfirstlane_b32 s51, v161
	global_load_lds_dwordx4 v[174:175], off
	v_lshl_add_u64 v[174:175], v[244:245], 0, s[10:11]
	s_mov_b32 m0, s51
	s_nop 0
	global_load_lds_dwordx4 v[174:175], off
	s_waitcnt vmcnt(6)
	s_barrier
	s_setprio 1
	v_mfma_f32_16x16x32_bf16 v[28:31], v[190:193], v[222:225], v[28:31]
	v_mfma_f32_16x16x32_bf16 v[24:27], v[190:193], v[230:233], v[24:27]
	v_mfma_f32_16x16x32_bf16 v[20:23], v[198:201], v[222:225], v[20:23]
	v_mfma_f32_16x16x32_bf16 v[16:19], v[198:201], v[230:233], v[16:19]
	v_mfma_f32_16x16x32_bf16 v[12:15], v[206:209], v[222:225], v[12:15]
	v_mfma_f32_16x16x32_bf16 v[8:11], v[206:209], v[230:233], v[8:11]
	v_mfma_f32_16x16x32_bf16 v[4:7], v[214:217], v[222:225], v[4:7]
	v_mfma_f32_16x16x32_bf16 v[0:3], v[214:217], v[230:233], v[0:3]
	v_mfma_f32_16x16x32_bf16 v[28:31], v[194:197], v[226:229], v[28:31]
	v_mfma_f32_16x16x32_bf16 v[24:27], v[194:197], v[234:237], v[24:27]
	v_mfma_f32_16x16x32_bf16 v[20:23], v[202:205], v[226:229], v[20:23]
	v_mfma_f32_16x16x32_bf16 v[16:19], v[202:205], v[234:237], v[16:19]
	v_mfma_f32_16x16x32_bf16 v[12:15], v[210:213], v[226:229], v[12:15]
	v_mfma_f32_16x16x32_bf16 v[8:11], v[210:213], v[234:237], v[8:11]
	v_mfma_f32_16x16x32_bf16 v[4:7], v[218:221], v[226:229], v[4:7]
	v_mfma_f32_16x16x32_bf16 v[0:3], v[218:221], v[234:237], v[0:3]
	s_setprio 0
	s_barrier
	ds_read_b128 v[174:177], v156
	ds_read_b128 v[178:181], v156 offset:1024
	ds_read_b128 v[182:185], v156 offset:2048
	ds_read_b128 v[186:189], v156 offset:3072
	v_readfirstlane_b32 s51, v162
	v_lshl_add_u64 v[222:223], v[238:239], 0, s[12:13]
	s_mov_b32 m0, s51
	v_readfirstlane_b32 s51, v163
	ds_read_b128 v[190:193], v153 offset:32768
	ds_read_b128 v[194:197], v153 offset:33792
	ds_read_b128 v[198:201], v152 offset:32768
	ds_read_b128 v[202:205], v152 offset:33792
	ds_read_b128 v[206:209], v151 offset:32768
	ds_read_b128 v[210:213], v151 offset:33792
	ds_read_b128 v[214:217], v150 offset:32768
	ds_read_b128 v[218:221], v150 offset:33792
	global_load_lds_dwordx4 v[222:223], off
	v_lshl_add_u64 v[222:223], v[240:241], 0, s[12:13]
	s_mov_b32 m0, s51
	s_nop 0
	global_load_lds_dwordx4 v[222:223], off
	s_waitcnt lgkmcnt(8)
	s_barrier
	s_waitcnt lgkmcnt(0)
	s_setprio 1
	v_mfma_f32_16x16x32_bf16 v[124:127], v[190:193], v[174:177], v[124:127]
	v_mfma_f32_16x16x32_bf16 v[120:123], v[190:193], v[182:185], v[120:123]
	v_mfma_f32_16x16x32_bf16 v[116:119], v[198:201], v[174:177], v[116:119]
	v_mfma_f32_16x16x32_bf16 v[112:115], v[198:201], v[182:185], v[112:115]
	v_mfma_f32_16x16x32_bf16 v[108:111], v[206:209], v[174:177], v[108:111]
	v_mfma_f32_16x16x32_bf16 v[104:107], v[206:209], v[182:185], v[104:107]
	v_mfma_f32_16x16x32_bf16 v[100:103], v[214:217], v[174:177], v[100:103]
	v_mfma_f32_16x16x32_bf16 v[96:99], v[214:217], v[182:185], v[96:99]
	v_mfma_f32_16x16x32_bf16 v[124:127], v[194:197], v[178:181], v[124:127]
	v_mfma_f32_16x16x32_bf16 v[120:123], v[194:197], v[186:189], v[120:123]
	v_mfma_f32_16x16x32_bf16 v[116:119], v[202:205], v[178:181], v[116:119]
	v_mfma_f32_16x16x32_bf16 v[112:115], v[202:205], v[186:189], v[112:115]
	v_mfma_f32_16x16x32_bf16 v[108:111], v[210:213], v[178:181], v[108:111]
	v_mfma_f32_16x16x32_bf16 v[104:107], v[210:213], v[186:189], v[104:107]
	v_mfma_f32_16x16x32_bf16 v[100:103], v[218:221], v[178:181], v[100:103]
	v_mfma_f32_16x16x32_bf16 v[96:99], v[218:221], v[186:189], v[96:99]
	s_setprio 0
	s_barrier
	v_readfirstlane_b32 s51, v164
	v_lshl_add_u64 v[246:247], v[242:243], 0, s[14:15]
	s_mov_b32 m0, s51
	v_readfirstlane_b32 s51, v165
	ds_read_b128 v[222:225], v154
	ds_read_b128 v[226:229], v154 offset:1024
	ds_read_b128 v[230:233], v154 offset:2048
	ds_read_b128 v[234:237], v154 offset:3072
	global_load_lds_dwordx4 v[246:247], off
	v_lshl_add_u64 v[246:247], v[244:245], 0, s[14:15]
	s_mov_b32 m0, s51
	s_nop 0
	global_load_lds_dwordx4 v[246:247], off
	s_barrier
	s_waitcnt lgkmcnt(0)
	s_setprio 1
	v_mfma_f32_16x16x32_bf16 v[92:95], v[190:193], v[222:225], v[92:95]
	v_mfma_f32_16x16x32_bf16 v[88:91], v[190:193], v[230:233], v[88:91]
	v_mfma_f32_16x16x32_bf16 v[84:87], v[198:201], v[222:225], v[84:87]
	v_mfma_f32_16x16x32_bf16 v[80:83], v[198:201], v[230:233], v[80:83]
	v_mfma_f32_16x16x32_bf16 v[76:79], v[206:209], v[222:225], v[76:79]
	v_mfma_f32_16x16x32_bf16 v[72:75], v[206:209], v[230:233], v[72:75]
	v_mfma_f32_16x16x32_bf16 v[68:71], v[214:217], v[222:225], v[68:71]
	v_mfma_f32_16x16x32_bf16 v[64:67], v[214:217], v[230:233], v[64:67]
	v_mfma_f32_16x16x32_bf16 v[92:95], v[194:197], v[226:229], v[92:95]
	v_mfma_f32_16x16x32_bf16 v[88:91], v[194:197], v[234:237], v[88:91]
	v_mfma_f32_16x16x32_bf16 v[84:87], v[202:205], v[226:229], v[84:87]
	v_mfma_f32_16x16x32_bf16 v[80:83], v[202:205], v[234:237], v[80:83]
	v_mfma_f32_16x16x32_bf16 v[76:79], v[210:213], v[226:229], v[76:79]
	v_mfma_f32_16x16x32_bf16 v[72:75], v[210:213], v[234:237], v[72:75]
	v_mfma_f32_16x16x32_bf16 v[68:71], v[218:221], v[226:229], v[68:71]
	v_mfma_f32_16x16x32_bf16 v[64:67], v[218:221], v[234:237], v[64:67]
	s_setprio 0
	v_readfirstlane_b32 s51, v166
	v_lshl_add_u64 v[238:239], v[238:239], 0, s[16:17]
	s_mov_b32 m0, s51
	v_readfirstlane_b32 s51, v168
	s_barrier
	ds_read_b128 v[190:193], v153 offset:49152
	ds_read_b128 v[194:197], v153 offset:50176
	ds_read_b128 v[198:201], v152 offset:49152
	ds_read_b128 v[202:205], v152 offset:50176
	ds_read_b128 v[206:209], v151 offset:49152
	ds_read_b128 v[210:213], v151 offset:50176
	ds_read_b128 v[214:217], v150 offset:49152
	ds_read_b128 v[218:221], v150 offset:50176
	global_load_lds_dwordx4 v[238:239], off
	v_lshl_add_u64 v[238:239], v[240:241], 0, s[16:17]
	s_mov_b32 m0, s51
	s_nop 0
	global_load_lds_dwordx4 v[238:239], off
	s_barrier
; #define STAGE(P, BASE, kt) do { const char* _g = (const char*)(BASE) + (size_t)((kt) * (BK * 2)); \
;     __builtin_amdgcn_global_load_lds((const unsigned*)(_g + (size_t)goff0), (unsigned*)((char*)(P) + tid_ * 16), 16, 0, 0); \
;     __builtin_amdgcn_global_load_lds((const unsigned*)(_g + (size_t)goff1), (unsigned*)((char*)(P) + tid_ * 16 + 8192), 16, 0, 0); } while (0)
; #define STAGEA(P, BASE, kt) do { const char* _g = (const char*)(BASE) + (size_t)((kt) * a_kbytes); \
;     __builtin_amdgcn_global_load_lds((const unsigned*)(_g + (size_t)goffA0), (unsigned*)((char*)(P) + tid_ * 16), 16, 0, 0); \
;     __builtin_amdgcn_global_load_lds((const unsigned*)(_g + (size_t)goffA1), (unsigned*)((char*)(P) + tid_ * 16 + 8192), 16, 0, 0); } while (0)
; #define LDA(dst, b, h) for (int m = 0; m < 4; ++m) for (int k = 0; k < 2; ++k) \
;     dst[m][k] = *reinterpret_cast<const bf16x8*>((char*)SA(b, h) + lds_byte(wr * 64 + m * 16 + fr, k * 32 + fq * 8))
; #define LDB(dst, b, h) for (int n = 0; n < 2; ++n) for (int k = 0; k < 2; ++k) \
;     dst[n][k] = *reinterpret_cast<const bf16x8*>((char*)SB(b, h) + lds_byte(wc * 32 + n * 16 + fr, k * 32 + fq * 8))
; #define MMA(ai, bj, At, Bt) do { __builtin_amdgcn_s_setprio(1); \
;     for (int m = 0; m < 4; ++m) for (int n = 0; n < 2; ++n) for (int k = 0; k < 2; ++k) \
;       acc[ai][bj][m][n] = __builtin_amdgcn_mfma_f32_16x16x32_bf16(At[m][k], Bt[n][k], acc[ai][bj][m][n], 0, 0, 0); \
;     __builtin_amdgcn_s_setprio(0); } while (0)
; #define WAIT_V(n) asm volatile("s_waitcnt vmcnt(" #n ")" ::: "memory")
; #define WAIT_L(n) asm volatile("s_waitcnt lgkmcnt(" #n ")" ::: "memory")
; #define BAR __builtin_amdgcn_s_barrier()
; #define SCHED __builtin_amdgcn_sched_barrier(0)
; template <int EPI> ...
;     ...
;     WAIT_L(8); BAR; WAIT_L(0); MMA(0, 0, At, B0); BAR; SCHED;
;     LDB(B1, 1, 1); STAGE(SB(1, 0), B0p, t + 3);
;     BAR; WAIT_L(0); MMA(0, 1, At, B1); BAR;
;     LDA(At, 1, 1); STAGEA(SA(1, 0), A0, t + 3);
;     BAR; WAIT_L(0); MMA(1, 0, At, B0); BAR; SCHED;
;     STAGE(SB(1, 1), B1p, t + 3);
;     WAIT_V(6); BAR; MMA(1, 1, At, B1); BAR;
;   }
;   { LDB(B0, 0, 0); LDA(At, 0, 0); STAGEA(SA(1, 1), A1, nt - 1);
;     BAR; WAIT_L(0); MMA(0, 0, At, B0); BAR;
;     LDB(B1, 0, 1); BAR; WAIT_L(0); MMA(0, 1, At, B1); BAR;
	s_waitcnt lgkmcnt(0)
	s_setprio 1
	v_mfma_f32_16x16x32_bf16 v[60:63], v[190:193], v[174:177], v[60:63]
	v_mfma_f32_16x16x32_bf16 v[56:59], v[190:193], v[182:185], v[56:59]
	v_mfma_f32_16x16x32_bf16 v[52:55], v[198:201], v[174:177], v[52:55]
	v_mfma_f32_16x16x32_bf16 v[48:51], v[198:201], v[182:185], v[48:51]
	v_mfma_f32_16x16x32_bf16 v[44:47], v[206:209], v[174:177], v[44:47]
	v_mfma_f32_16x16x32_bf16 v[40:43], v[206:209], v[182:185], v[40:43]
	v_mfma_f32_16x16x32_bf16 v[36:39], v[214:217], v[174:177], v[36:39]
	v_mfma_f32_16x16x32_bf16 v[32:35], v[214:217], v[182:185], v[32:35]
	v_mfma_f32_16x16x32_bf16 v[60:63], v[194:197], v[178:181], v[60:63]
	v_mfma_f32_16x16x32_bf16 v[56:59], v[194:197], v[186:189], v[56:59]
	v_mfma_f32_16x16x32_bf16 v[52:55], v[202:205], v[178:181], v[52:55]
	v_mfma_f32_16x16x32_bf16 v[48:51], v[202:205], v[186:189], v[48:51]
	v_mfma_f32_16x16x32_bf16 v[44:47], v[210:213], v[178:181], v[44:47]
	v_mfma_f32_16x16x32_bf16 v[40:43], v[210:213], v[186:189], v[40:43]
	v_mfma_f32_16x16x32_bf16 v[36:39], v[218:221], v[178:181], v[36:39]
	v_mfma_f32_16x16x32_bf16 v[32:35], v[218:221], v[186:189], v[32:35]
	s_setprio 0
	s_barrier
	v_readfirstlane_b32 s51, v169
	v_lshl_add_u64 v[174:175], v[242:243], 0, s[18:19]
	s_mov_b32 m0, s51
	v_readfirstlane_b32 s51, v170
	global_load_lds_dwordx4 v[174:175], off
	v_lshl_add_u64 v[174:175], v[244:245], 0, s[18:19]
	s_mov_b32 m0, s51
	s_nop 0
	global_load_lds_dwordx4 v[174:175], off
	s_waitcnt vmcnt(6)
	s_barrier
	s_setprio 1
	v_mfma_f32_16x16x32_bf16 v[28:31], v[190:193], v[222:225], v[28:31]
	v_mfma_f32_16x16x32_bf16 v[24:27], v[190:193], v[230:233], v[24:27]
	v_mfma_f32_16x16x32_bf16 v[20:23], v[198:201], v[222:225], v[20:23]
	v_mfma_f32_16x16x32_bf16 v[16:19], v[198:201], v[230:233], v[16:19]
	v_mfma_f32_16x16x32_bf16 v[12:15], v[206:209], v[222:225], v[12:15]
	v_mfma_f32_16x16x32_bf16 v[8:11], v[206:209], v[230:233], v[8:11]
	v_mfma_f32_16x16x32_bf16 v[4:7], v[214:217], v[222:225], v[4:7]
	v_mfma_f32_16x16x32_bf16 v[0:3], v[214:217], v[230:233], v[0:3]
	v_mfma_f32_16x16x32_bf16 v[28:31], v[194:197], v[226:229], v[28:31]
	v_mfma_f32_16x16x32_bf16 v[24:27], v[194:197], v[234:237], v[24:27]
	v_mfma_f32_16x16x32_bf16 v[20:23], v[202:205], v[226:229], v[20:23]
	v_mfma_f32_16x16x32_bf16 v[16:19], v[202:205], v[234:237], v[16:19]
	v_mfma_f32_16x16x32_bf16 v[12:15], v[210:213], v[226:229], v[12:15]
	v_mfma_f32_16x16x32_bf16 v[8:11], v[210:213], v[234:237], v[8:11]
	v_mfma_f32_16x16x32_bf16 v[4:7], v[218:221], v[226:229], v[4:7]
	v_mfma_f32_16x16x32_bf16 v[0:3], v[218:221], v[234:237], v[0:3]
	s_setprio 0
	s_add_i32 s50, s50, 2
	s_add_u32 s26, s26, 0x10000
	s_addc_u32 s27, s27, 0
	s_add_u32 s24, s24, 0x100
	s_addc_u32 s25, s25, 0
	s_cmpk_lt_u32 s50, 0x54
	s_barrier
	s_cbranch_scc1 .LBB0_1738
	s_add_u32 s22, s22, 0x2bc000
	s_addc_u32 s23, s23, 0
	v_readfirstlane_b32 s24, v172
	v_lshl_add_u64 v[210:211], s[22:23], 0, v[130:131]
	s_mov_b32 m0, s24
	ds_read_b128 v[158:161], v171
	ds_read_b128 v[162:165], v171 offset:1024
	ds_read_b128 v[174:177], v171 offset:2048
	ds_read_b128 v[168:171], v171 offset:3072
	ds_read_b128 v[178:181], v153
	ds_read_b128 v[182:185], v153 offset:1024
	ds_read_b128 v[186:189], v152
	ds_read_b128 v[190:193], v152 offset:1024
	ds_read_b128 v[194:197], v151
	ds_read_b128 v[198:201], v151 offset:1024
	ds_read_b128 v[202:205], v150
	ds_read_b128 v[206:209], v150 offset:1024
	global_load_lds_dwordx4 v[210:211], off
	v_lshl_add_u64 v[210:211], s[22:23], 0, v[128:129]
	v_readfirstlane_b32 s22, v173
	s_mov_b32 m0, s22
	s_nop 0
	global_load_lds_dwordx4 v[210:211], off
	s_barrier
	s_waitcnt lgkmcnt(0)
	s_setprio 1
	v_mfma_f32_16x16x32_bf16 v[124:127], v[178:181], v[158:161], v[124:127]
	v_mfma_f32_16x16x32_bf16 v[120:123], v[178:181], v[174:177], v[120:123]
	v_mfma_f32_16x16x32_bf16 v[108:111], v[194:197], v[158:161], v[108:111]
	v_mfma_f32_16x16x32_bf16 v[104:107], v[194:197], v[174:177], v[104:107]
	v_mfma_f32_16x16x32_bf16 v[124:127], v[182:185], v[162:165], v[124:127]
	v_mfma_f32_16x16x32_bf16 v[120:123], v[182:185], v[168:171], v[120:123]
	v_mfma_f32_16x16x32_bf16 v[116:119], v[186:189], v[158:161], v[116:119]
	v_mfma_f32_16x16x32_bf16 v[112:115], v[186:189], v[174:177], v[112:115]
	v_mfma_f32_16x16x32_bf16 v[108:111], v[198:201], v[162:165], v[108:111]
	v_mfma_f32_16x16x32_bf16 v[104:107], v[198:201], v[168:171], v[104:107]
	v_mfma_f32_16x16x32_bf16 v[100:103], v[202:205], v[158:161], v[100:103]
	v_mfma_f32_16x16x32_bf16 v[96:99], v[202:205], v[174:177], v[96:99]
	v_mfma_f32_16x16x32_bf16 v[210:213], v[190:193], v[162:165], v[116:119]
	v_mfma_f32_16x16x32_bf16 v[214:217], v[190:193], v[168:171], v[112:115]
	v_mfma_f32_16x16x32_bf16 v[218:221], v[206:209], v[162:165], v[100:103]
	v_mfma_f32_16x16x32_bf16 v[222:225], v[206:209], v[168:171], v[96:99]
	s_setprio 0
	s_barrier
	s_nop 1
	ds_read_b128 v[96:99], v167
	ds_read_b128 v[100:103], v167 offset:1024
	ds_read_b128 v[112:115], v167 offset:2048
	ds_read_b128 v[116:119], v167 offset:3072
	s_barrier
	s_waitcnt lgkmcnt(0)
	s_setprio 1
	v_mfma_f32_16x16x32_bf16 v[92:95], v[178:181], v[96:99], v[92:95]
	v_mfma_f32_16x16x32_bf16 v[88:91], v[178:181], v[112:115], v[88:91]
	v_mfma_f32_16x16x32_bf16 v[76:79], v[194:197], v[96:99], v[76:79]
	v_mfma_f32_16x16x32_bf16 v[72:75], v[194:197], v[112:115], v[72:75]
	v_mfma_f32_16x16x32_bf16 v[92:95], v[182:185], v[100:103], v[92:95]
	v_mfma_f32_16x16x32_bf16 v[88:91], v[182:185], v[116:119], v[88:91]
	v_mfma_f32_16x16x32_bf16 v[84:87], v[186:189], v[96:99], v[84:87]
	v_mfma_f32_16x16x32_bf16 v[80:83], v[186:189], v[112:115], v[80:83]
	v_mfma_f32_16x16x32_bf16 v[76:79], v[198:201], v[100:103], v[76:79]
	v_mfma_f32_16x16x32_bf16 v[72:75], v[198:201], v[116:119], v[72:75]
	v_mfma_f32_16x16x32_bf16 v[68:71], v[202:205], v[96:99], v[68:71]
	v_mfma_f32_16x16x32_bf16 v[64:67], v[202:205], v[112:115], v[64:67]
	v_mfma_f32_16x16x32_bf16 v[178:181], v[190:193], v[100:103], v[84:87]
	v_mfma_f32_16x16x32_bf16 v[182:185], v[190:193], v[116:119], v[80:83]
	v_mfma_f32_16x16x32_bf16 v[186:189], v[206:209], v[100:103], v[68:71]
	v_mfma_f32_16x16x32_bf16 v[190:193], v[206:209], v[116:119], v[64:67]
	s_setprio 0
	s_barrier
; #define LDA(dst, b, h) for (int m = 0; m < 4; ++m) for (int k = 0; k < 2; ++k) \
;     dst[m][k] = *reinterpret_cast<const bf16x8*>((char*)SA(b, h) + lds_byte(wr * 64 + m * 16 + fr, k * 32 + fq * 8))
; #define LDB(dst, b, h) for (int n = 0; n < 2; ++n) for (int k = 0; k < 2; ++k) \
;     dst[n][k] = *reinterpret_cast<const bf16x8*>((char*)SB(b, h) + lds_byte(wc * 32 + n * 16 + fr, k * 32 + fq * 8))
; #define MMA(ai, bj, At, Bt) do { __builtin_amdgcn_s_setprio(1); \
;     for (int m = 0; m < 4; ++m) for (int n = 0; n < 2; ++n) for (int k = 0; k < 2; ++k) \
;       acc[ai][bj][m][n] = __builtin_amdgcn_mfma_f32_16x16x32_bf16(At[m][k], Bt[n][k], acc[ai][bj][m][n], 0, 0, 0); \
;     __builtin_amdgcn_s_setprio(0); } while (0)
; #define WAIT_V(n) asm volatile("s_waitcnt vmcnt(" #n ")" ::: "memory")
; #define WAIT_L(n) asm volatile("s_waitcnt lgkmcnt(" #n ")" ::: "memory")
; #define BAR __builtin_amdgcn_s_barrier()
; template <int EPI> ...
;     ...
;     LDA(At, 0, 1); WAIT_V(4); BAR; WAIT_L(0); MMA(1, 0, At, B0); MMA(1, 1, At, B1); BAR; }
;   { LDB(B0, 1, 0); LDA(At, 1, 0); WAIT_V(2); BAR; WAIT_L(0); MMA(0, 0, At, B0); BAR;
	s_nop 1
	ds_read_b128 v[64:67], v153 offset:16384
	ds_read_b128 v[68:71], v153 offset:17408
	ds_read_b128 v[80:83], v152 offset:16384
	ds_read_b128 v[84:87], v152 offset:17408
	ds_read_b128 v[194:197], v151 offset:16384
	ds_read_b128 v[198:201], v151 offset:17408
	ds_read_b128 v[202:205], v150 offset:16384
	ds_read_b128 v[206:209], v150 offset:17408
	s_waitcnt vmcnt(4)
	s_barrier
	s_waitcnt lgkmcnt(0)
	s_setprio 1
	v_mfma_f32_16x16x32_bf16 v[60:63], v[64:67], v[158:161], v[60:63]
	v_mfma_f32_16x16x32_bf16 v[56:59], v[64:67], v[174:177], v[56:59]
	v_mfma_f32_16x16x32_bf16 v[44:47], v[194:197], v[158:161], v[44:47]
	v_mfma_f32_16x16x32_bf16 v[40:43], v[194:197], v[174:177], v[40:43]
	v_mfma_f32_16x16x32_bf16 v[60:63], v[68:71], v[162:165], v[60:63]
	v_mfma_f32_16x16x32_bf16 v[56:59], v[68:71], v[168:171], v[56:59]
	v_mfma_f32_16x16x32_bf16 v[52:55], v[80:83], v[158:161], v[52:55]
	v_mfma_f32_16x16x32_bf16 v[48:51], v[80:83], v[174:177], v[48:51]
	v_mfma_f32_16x16x32_bf16 v[44:47], v[198:201], v[162:165], v[44:47]
	v_mfma_f32_16x16x32_bf16 v[40:43], v[198:201], v[168:171], v[40:43]
	v_mfma_f32_16x16x32_bf16 v[36:39], v[202:205], v[158:161], v[36:39]
	v_mfma_f32_16x16x32_bf16 v[32:35], v[202:205], v[174:177], v[32:35]
	v_mfma_f32_16x16x32_bf16 v[226:229], v[84:87], v[162:165], v[52:55]
	v_mfma_f32_16x16x32_bf16 v[230:233], v[84:87], v[168:171], v[48:51]
	v_mfma_f32_16x16x32_bf16 v[158:161], v[206:209], v[162:165], v[36:39]
	v_mfma_f32_16x16x32_bf16 v[162:165], v[206:209], v[168:171], v[32:35]
	s_setprio 0
	s_setprio 1
	v_mfma_f32_16x16x32_bf16 v[28:31], v[64:67], v[96:99], v[28:31]
	v_mfma_f32_16x16x32_bf16 v[24:27], v[64:67], v[112:115], v[24:27]
	v_mfma_f32_16x16x32_bf16 v[12:15], v[194:197], v[96:99], v[12:15]
	v_mfma_f32_16x16x32_bf16 v[8:11], v[194:197], v[112:115], v[8:11]
	v_mfma_f32_16x16x32_bf16 v[28:31], v[68:71], v[100:103], v[28:31]
	v_mfma_f32_16x16x32_bf16 v[24:27], v[68:71], v[116:119], v[24:27]
	v_mfma_f32_16x16x32_bf16 v[20:23], v[80:83], v[96:99], v[20:23]
	v_mfma_f32_16x16x32_bf16 v[16:19], v[80:83], v[112:115], v[16:19]
	v_mfma_f32_16x16x32_bf16 v[12:15], v[198:201], v[100:103], v[12:15]
	v_mfma_f32_16x16x32_bf16 v[8:11], v[198:201], v[116:119], v[8:11]
	v_mfma_f32_16x16x32_bf16 v[4:7], v[202:205], v[96:99], v[4:7]
	v_mfma_f32_16x16x32_bf16 v[0:3], v[202:205], v[112:115], v[0:3]
	v_mfma_f32_16x16x32_bf16 v[166:169], v[84:87], v[100:103], v[20:23]
	v_mfma_f32_16x16x32_bf16 v[170:173], v[84:87], v[116:119], v[16:19]
	v_mfma_f32_16x16x32_bf16 v[174:177], v[206:209], v[100:103], v[4:7]
	v_mfma_f32_16x16x32_bf16 v[194:197], v[206:209], v[116:119], v[0:3]
	s_setprio 0
	s_barrier
	s_nop 1
	ds_read_b128 v[0:3], v156
	ds_read_b128 v[4:7], v156 offset:1024
	ds_read_b128 v[198:201], v156 offset:2048
	ds_read_b128 v[202:205], v156 offset:3072
	ds_read_b128 v[16:19], v153 offset:32768
	ds_read_b128 v[20:23], v153 offset:33792
	ds_read_b128 v[32:35], v152 offset:32768
	ds_read_b128 v[36:39], v152 offset:33792
	ds_read_b128 v[48:51], v151 offset:32768
	ds_read_b128 v[52:55], v151 offset:33792
	ds_read_b128 v[206:209], v150 offset:32768
	ds_read_b128 v[234:237], v150 offset:33792
	s_waitcnt vmcnt(2)
	s_barrier
	s_waitcnt lgkmcnt(0)
	s_setprio 1
	v_mfma_f32_16x16x32_bf16 v[64:67], v[16:19], v[0:3], v[124:127]
	v_mfma_f32_16x16x32_bf16 v[116:119], v[20:23], v[4:7], v[64:67]
	v_mfma_f32_16x16x32_bf16 v[64:67], v[16:19], v[198:201], v[120:123]
	v_mfma_f32_16x16x32_bf16 v[112:115], v[20:23], v[202:205], v[64:67]
	v_mfma_f32_16x16x32_bf16 v[64:67], v[32:35], v[0:3], v[210:213]
	v_mfma_f32_16x16x32_bf16 v[100:103], v[36:39], v[4:7], v[64:67]
	v_mfma_f32_16x16x32_bf16 v[64:67], v[32:35], v[198:201], v[214:217]
	v_mfma_f32_16x16x32_bf16 v[96:99], v[36:39], v[202:205], v[64:67]
	v_mfma_f32_16x16x32_bf16 v[64:67], v[48:51], v[0:3], v[108:111]
	v_mfma_f32_16x16x32_bf16 v[84:87], v[52:55], v[4:7], v[64:67]
	v_mfma_f32_16x16x32_bf16 v[64:67], v[48:51], v[198:201], v[104:107]
	v_mfma_f32_16x16x32_bf16 v[80:83], v[52:55], v[202:205], v[64:67]
	v_mfma_f32_16x16x32_bf16 v[64:67], v[206:209], v[0:3], v[218:221]
	v_mfma_f32_16x16x32_bf16 v[68:71], v[234:237], v[4:7], v[64:67]
	v_mfma_f32_16x16x32_bf16 v[64:67], v[206:209], v[198:201], v[222:225]
	v_mfma_f32_16x16x32_bf16 v[64:67], v[234:237], v[202:205], v[64:67]
	s_setprio 0
	s_barrier
; #define LDA(dst, b, h) for (int m = 0; m < 4; ++m) for (int k = 0; k < 2; ++k) \
;     dst[m][k] = *reinterpret_cast<const bf16x8*>((char*)SA(b, h) + lds_byte(wr * 64 + m * 16 + fr, k * 32 + fq * 8))
; #define LDB(dst, b, h) for (int n = 0; n < 2; ++n) for (int k = 0; k < 2; ++k) \
;     dst[n][k] = *reinterpret_cast<const bf16x8*>((char*)SB(b, h) + lds_byte(wc * 32 + n * 16 + fr, k * 32 + fq * 8))
; #define MMA(ai, bj, At, Bt) do { __builtin_amdgcn_s_setprio(1); \
;     for (int m = 0; m < 4; ++m) for (int n = 0; n < 2; ++n) for (int k = 0; k < 2; ++k) \
;       acc[ai][bj][m][n] = __builtin_amdgcn_mfma_f32_16x16x32_bf16(At[m][k], Bt[n][k], acc[ai][bj][m][n], 0, 0, 0); \
;     __builtin_amdgcn_s_setprio(0); } while (0)
; #define WAIT_V(n) asm volatile("s_waitcnt vmcnt(" #n ")" ::: "memory")
; #define WAIT_L(n) asm volatile("s_waitcnt lgkmcnt(" #n ")" ::: "memory")
; #define BAR __builtin_amdgcn_s_barrier()
; template <int EPI> ...
;     ...
;   { LDB(B0, 1, 0); LDA(At, 1, 0); WAIT_V(2); BAR; WAIT_L(0); MMA(0, 0, At, B0); BAR;
;     LDB(B1, 1, 1); WAIT_V(0); BAR; WAIT_L(0); MMA(0, 1, At, B1); BAR;
;     LDA(At, 1, 1); BAR; WAIT_L(0); MMA(1, 0, At, B0); MMA(1, 1, At, B1); BAR; }
;   if (wr == 0) BAR;
	ds_read_b128 v[210:213], v154
	ds_read_b128 v[214:217], v154 offset:1024
	ds_read_b128 v[218:221], v154 offset:2048
	ds_read_b128 v[154:157], v154 offset:3072
	s_waitcnt vmcnt(0)
	s_barrier
	s_waitcnt lgkmcnt(0)
	s_setprio 1
	v_mfma_f32_16x16x32_bf16 v[92:95], v[16:19], v[210:213], v[92:95]
	v_mfma_f32_16x16x32_bf16 v[16:19], v[16:19], v[218:221], v[88:91]
	v_mfma_f32_16x16x32_bf16 v[120:123], v[20:23], v[154:157], v[16:19]
	v_mfma_f32_16x16x32_bf16 v[16:19], v[32:35], v[210:213], v[178:181]
	v_mfma_f32_16x16x32_bf16 v[108:111], v[36:39], v[214:217], v[16:19]
	v_mfma_f32_16x16x32_bf16 v[16:19], v[32:35], v[218:221], v[182:185]
	v_mfma_f32_16x16x32_bf16 v[104:107], v[36:39], v[154:157], v[16:19]
	v_mfma_f32_16x16x32_bf16 v[16:19], v[48:51], v[210:213], v[76:79]
	v_mfma_f32_16x16x32_bf16 v[124:127], v[20:23], v[214:217], v[92:95]
	v_mfma_f32_16x16x32_bf16 v[92:95], v[52:55], v[214:217], v[16:19]
	v_mfma_f32_16x16x32_bf16 v[16:19], v[48:51], v[218:221], v[72:75]
	v_mfma_f32_16x16x32_bf16 v[88:91], v[52:55], v[154:157], v[16:19]
	v_mfma_f32_16x16x32_bf16 v[16:19], v[206:209], v[210:213], v[186:189]
	v_mfma_f32_16x16x32_bf16 v[76:79], v[234:237], v[214:217], v[16:19]
	v_mfma_f32_16x16x32_bf16 v[16:19], v[206:209], v[218:221], v[190:193]
	v_mfma_f32_16x16x32_bf16 v[72:75], v[234:237], v[154:157], v[16:19]
	s_setprio 0
	s_barrier
	ds_read_b128 v[178:181], v153 offset:49152
	ds_read_b128 v[182:185], v153 offset:50176
	ds_read_b128 v[186:189], v152 offset:49152
	ds_read_b128 v[190:193], v152 offset:50176
	ds_read_b128 v[206:209], v151 offset:49152
	ds_read_b128 v[222:225], v151 offset:50176
	ds_read_b128 v[234:237], v150 offset:49152
	ds_read_b128 v[150:153], v150 offset:50176
	s_barrier
	s_waitcnt lgkmcnt(0)
	s_setprio 1
	v_mfma_f32_16x16x32_bf16 v[16:19], v[178:181], v[0:3], v[60:63]
	v_mfma_f32_16x16x32_bf16 v[52:55], v[182:185], v[4:7], v[16:19]
	v_mfma_f32_16x16x32_bf16 v[16:19], v[178:181], v[198:201], v[56:59]
	v_mfma_f32_16x16x32_bf16 v[48:51], v[182:185], v[202:205], v[16:19]
	v_mfma_f32_16x16x32_bf16 v[16:19], v[186:189], v[0:3], v[226:229]
	v_mfma_f32_16x16x32_bf16 v[36:39], v[190:193], v[4:7], v[16:19]
	v_mfma_f32_16x16x32_bf16 v[16:19], v[186:189], v[198:201], v[230:233]
	v_mfma_f32_16x16x32_bf16 v[32:35], v[190:193], v[202:205], v[16:19]
	v_mfma_f32_16x16x32_bf16 v[16:19], v[206:209], v[0:3], v[44:47]
	v_mfma_f32_16x16x32_bf16 v[0:3], v[234:237], v[0:3], v[158:161]
	v_mfma_f32_16x16x32_bf16 v[20:23], v[222:225], v[4:7], v[16:19]
	v_mfma_f32_16x16x32_bf16 v[16:19], v[206:209], v[198:201], v[40:43]
	v_mfma_f32_16x16x32_bf16 v[4:7], v[150:153], v[4:7], v[0:3]
	v_mfma_f32_16x16x32_bf16 v[0:3], v[234:237], v[198:201], v[162:165]
	v_mfma_f32_16x16x32_bf16 v[16:19], v[222:225], v[202:205], v[16:19]
	v_mfma_f32_16x16x32_bf16 v[0:3], v[150:153], v[202:205], v[0:3]
	s_setprio 0
	s_setprio 1
	v_mfma_f32_16x16x32_bf16 v[24:27], v[178:181], v[218:221], v[24:27]
	v_mfma_f32_16x16x32_bf16 v[56:59], v[182:185], v[154:157], v[24:27]
	v_mfma_f32_16x16x32_bf16 v[24:27], v[186:189], v[210:213], v[166:169]
	v_mfma_f32_16x16x32_bf16 v[44:47], v[190:193], v[214:217], v[24:27]
	v_mfma_f32_16x16x32_bf16 v[24:27], v[186:189], v[218:221], v[170:173]
	v_mfma_f32_16x16x32_bf16 v[8:11], v[206:209], v[218:221], v[8:11]
	v_mfma_f32_16x16x32_bf16 v[28:31], v[178:181], v[210:213], v[28:31]
	v_mfma_f32_16x16x32_bf16 v[40:43], v[190:193], v[154:157], v[24:27]
	v_mfma_f32_16x16x32_bf16 v[12:15], v[206:209], v[210:213], v[12:15]
	v_mfma_f32_16x16x32_bf16 v[24:27], v[222:225], v[154:157], v[8:11]
	v_mfma_f32_16x16x32_bf16 v[8:11], v[234:237], v[210:213], v[174:177]
	v_mfma_f32_16x16x32_bf16 v[60:63], v[182:185], v[214:217], v[28:31]
	v_mfma_f32_16x16x32_bf16 v[28:31], v[222:225], v[214:217], v[12:15]
	v_mfma_f32_16x16x32_bf16 v[12:15], v[150:153], v[214:217], v[8:11]
	v_mfma_f32_16x16x32_bf16 v[8:11], v[234:237], v[218:221], v[194:197]
	v_mfma_f32_16x16x32_bf16 v[8:11], v[150:153], v[154:157], v[8:11]
	s_setprio 0
	v_cmp_gt_u32_e32 vcc, s43, v144
	s_barrier
	s_and_saveexec_b64 s[22:23], vcc
	s_cbranch_execz .LBB0_1741
	s_barrier
